# single-pass int8 conversion for all four int8 weight matrices (FFN2 w_in in P3), next-block loads prefetched during quantisation; the separate column-absmax pass is gone
# speedup vs baseline: 1.0196x; 1.0059x over previous
.LBB0_88:
	s_or_b64 exec, exec, s[0:1]
	v_readlane_b32 s0, v254, 15
	s_lshl_b32 s21, s0, 9
	s_mov_b32 s14, s90
	s_cmpk_gt_i32 s90, 0x69ff
	s_waitcnt lgkmcnt(0)
	s_barrier
	s_cbranch_scc1 .LBB0_115
	v_mbcnt_lo_u32_b32 v135, -1, 0
	v_mbcnt_hi_u32_b32 v135, -1, v135
	v_lshrrev_b32_e32 v136, 2, v135
	v_and_b32_e32 v137, 3, v135
	v_lshlrev_b32_e32 v230, 4, v137
	v_readlane_b32 s62, v254, 17
	v_readlane_b32 s1, v254, 16
	v_readlane_b32 s72, v254, 15
	s_mov_b32 s74, 0x42fe0000
	s_mov_b32 s11, 0
	v_lshlrev_b32_e32 v139, 11, v137
	v_lshl_add_u32 v139, v136, 2, v139
	s_nop 1
	v_add_u32_e32 v139, s62, v139
	v_lshlrev_b32_e32 v174, 2, v135
	v_xor_b32_e32 v192, 0x10, v174
	v_xor_b32_e32 v193, 0x20, v174
	v_xor_b32_e32 v194, 0x40, v174
	v_xor_b32_e32 v195, 0x80, v174
	v_lshrrev_b32_e32 v175, 5, v135
	v_and_b32_e32 v176, 31, v135
	v_lshlrev_b32_e32 v212, 9, v175
	v_lshl_add_u32 v212, v176, 4, v212
	v_add_u32_e32 v212, s62, v212
	v_lshlrev_b32_e32 v213, 12, v175
	v_lshl_add_u32 v213, v176, 4, v213
	v_readlane_b32 s48, v255, 47
	v_readlane_b32 s49, v255, 48
	v_mul_u32_u24_e32 v138, 0x20000, v136
	v_lshl_add_u32 v138, v137, 4, v138
	s_mul_i32 s3, s1, 0x1000000
	s_nop 1
	s_add_u32 s48, s48, s3
	s_addc_u32 s49, s49, 0
	s_mov_b32 s0, s72
	s_cmp_ge_u32 s0, 0x200
	s_cbranch_scc1 .Lc16_gates_done
	s_lshl_b32 s3, s0, 6
	s_add_u32 s56, s48, s3
	s_addc_u32 s57, s49, 0
	global_load_dwordx4 v[6:9], v138, s[56:57] nt
	s_add_u32 s56, s56, 0x8000
	s_addc_u32 s57, s57, 0
	global_load_dwordx4 v[10:13], v138, s[56:57] nt
	s_add_u32 s56, s56, 0x8000
	s_addc_u32 s57, s57, 0
	global_load_dwordx4 v[14:17], v138, s[56:57] nt
	s_add_u32 s56, s56, 0x8000
	s_addc_u32 s57, s57, 0
	global_load_dwordx4 v[18:21], v138, s[56:57] nt
	s_add_u32 s56, s56, 0x1e8000
	s_addc_u32 s57, s57, 0
	global_load_dwordx4 v[22:25], v138, s[56:57] nt
	s_add_u32 s56, s56, 0x8000
	s_addc_u32 s57, s57, 0
	global_load_dwordx4 v[26:29], v138, s[56:57] nt
	s_add_u32 s56, s56, 0x8000
	s_addc_u32 s57, s57, 0
	global_load_dwordx4 v[30:33], v138, s[56:57] nt
	s_add_u32 s56, s56, 0x8000
	s_addc_u32 s57, s57, 0
	global_load_dwordx4 v[34:37], v138, s[56:57] nt
	s_add_u32 s56, s56, 0x1e8000
	s_addc_u32 s57, s57, 0
	global_load_dwordx4 v[38:41], v138, s[56:57] nt
	s_add_u32 s56, s56, 0x8000
	s_addc_u32 s57, s57, 0
	global_load_dwordx4 v[42:45], v138, s[56:57] nt
	s_add_u32 s56, s56, 0x8000
	s_addc_u32 s57, s57, 0
	global_load_dwordx4 v[46:49], v138, s[56:57] nt
	s_add_u32 s56, s56, 0x8000
	s_addc_u32 s57, s57, 0
	global_load_dwordx4 v[50:53], v138, s[56:57] nt
	s_add_u32 s56, s56, 0x1e8000
	s_addc_u32 s57, s57, 0
	global_load_dwordx4 v[54:57], v138, s[56:57] nt
	s_add_u32 s56, s56, 0x8000
	s_addc_u32 s57, s57, 0
	global_load_dwordx4 v[58:61], v138, s[56:57] nt
	s_add_u32 s56, s56, 0x8000
	s_addc_u32 s57, s57, 0
	global_load_dwordx4 v[62:65], v138, s[56:57] nt
	s_add_u32 s56, s56, 0x8000
	s_addc_u32 s57, s57, 0
	global_load_dwordx4 v[66:69], v138, s[56:57] nt
	s_add_u32 s56, s56, 0x1e8000
	s_addc_u32 s57, s57, 0
	global_load_dwordx4 v[70:73], v138, s[56:57] nt
	s_add_u32 s56, s56, 0x8000
	s_addc_u32 s57, s57, 0
	global_load_dwordx4 v[74:77], v138, s[56:57] nt
	s_add_u32 s56, s56, 0x8000
	s_addc_u32 s57, s57, 0
	global_load_dwordx4 v[78:81], v138, s[56:57] nt
	s_add_u32 s56, s56, 0x8000
	s_addc_u32 s57, s57, 0
	global_load_dwordx4 v[82:85], v138, s[56:57] nt
	s_add_u32 s56, s56, 0x1e8000
	s_addc_u32 s57, s57, 0
	global_load_dwordx4 v[86:89], v138, s[56:57] nt
	s_add_u32 s56, s56, 0x8000
	s_addc_u32 s57, s57, 0
	global_load_dwordx4 v[90:93], v138, s[56:57] nt
	s_add_u32 s56, s56, 0x8000
	s_addc_u32 s57, s57, 0
	global_load_dwordx4 v[94:97], v138, s[56:57] nt
	s_add_u32 s56, s56, 0x8000
	s_addc_u32 s57, s57, 0
	global_load_dwordx4 v[98:101], v138, s[56:57] nt
	s_add_u32 s56, s56, 0x1e8000
	s_addc_u32 s57, s57, 0
	global_load_dwordx4 v[102:105], v138, s[56:57] nt
	s_add_u32 s56, s56, 0x8000
	s_addc_u32 s57, s57, 0
	global_load_dwordx4 v[106:109], v138, s[56:57] nt
	s_add_u32 s56, s56, 0x8000
	s_addc_u32 s57, s57, 0
	global_load_dwordx4 v[110:113], v138, s[56:57] nt
	s_add_u32 s56, s56, 0x8000
	s_addc_u32 s57, s57, 0
	global_load_dwordx4 v[114:117], v138, s[56:57] nt
	s_add_u32 s56, s56, 0x1e8000
	s_addc_u32 s57, s57, 0
	global_load_dwordx4 v[118:121], v138, s[56:57] nt
	s_add_u32 s56, s56, 0x8000
	s_addc_u32 s57, s57, 0
	global_load_dwordx4 v[122:125], v138, s[56:57] nt
	s_add_u32 s56, s56, 0x8000
	s_addc_u32 s57, s57, 0
	global_load_dwordx4 v[126:129], v138, s[56:57] nt
	s_add_u32 s56, s56, 0x8000
	s_addc_u32 s57, s57, 0
	global_load_dwordx4 v[130:133], v138, s[56:57] nt
.Lc16_gates_loop:
	s_lshl_b32 s2, s0, 4
	s_mov_b32 s60, s2
	s_lshl_b32 s63, s11, 9
	s_add_u32 s63, s63, 0x21000
	s_lshl_b32 s3, s1, 6
	s_add_u32 s3, s3, s63
	v_add_u32_e32 v172, s3, v230
	v_add_u32_e32 v173, s63, v230
	s_waitcnt vmcnt(0)
	v_max3_f32 v216, |v6|, |v10|, |v14|
	v_max3_f32 v216, v216, |v18|, |v22|
	v_max3_f32 v216, v216, |v26|, |v30|
	v_max3_f32 v216, v216, |v34|, |v38|
	v_max3_f32 v216, v216, |v42|, |v46|
	v_max3_f32 v216, v216, |v50|, |v54|
	v_max3_f32 v216, v216, |v58|, |v62|
	v_max3_f32 v216, v216, |v66|, |v70|
	v_max3_f32 v216, v216, |v74|, |v78|
	v_max3_f32 v216, v216, |v82|, |v86|
	v_max3_f32 v216, v216, |v90|, |v94|
	v_max3_f32 v216, v216, |v98|, |v102|
	v_max3_f32 v216, v216, |v106|, |v110|
	v_max3_f32 v216, v216, |v114|, |v118|
	v_max3_f32 v216, v216, |v122|, |v126|
	v_max_f32_e64 v216, v216, |v130|
	v_max3_f32 v217, |v7|, |v11|, |v15|
	v_max3_f32 v217, v217, |v19|, |v23|
	v_max3_f32 v217, v217, |v27|, |v31|
	v_max3_f32 v217, v217, |v35|, |v39|
	v_max3_f32 v217, v217, |v43|, |v47|
	v_max3_f32 v217, v217, |v51|, |v55|
	v_max3_f32 v217, v217, |v59|, |v63|
	v_max3_f32 v217, v217, |v67|, |v71|
	v_max3_f32 v217, v217, |v75|, |v79|
	v_max3_f32 v217, v217, |v83|, |v87|
	v_max3_f32 v217, v217, |v91|, |v95|
	v_max3_f32 v217, v217, |v99|, |v103|
	v_max3_f32 v217, v217, |v107|, |v111|
	v_max3_f32 v217, v217, |v115|, |v119|
	v_max3_f32 v217, v217, |v123|, |v127|
	v_max_f32_e64 v217, v217, |v131|
	v_max3_f32 v218, |v8|, |v12|, |v16|
	v_max3_f32 v218, v218, |v20|, |v24|
	v_max3_f32 v218, v218, |v28|, |v32|
	v_max3_f32 v218, v218, |v36|, |v40|
	v_max3_f32 v218, v218, |v44|, |v48|
	v_max3_f32 v218, v218, |v52|, |v56|
	v_max3_f32 v218, v218, |v60|, |v64|
	v_max3_f32 v218, v218, |v68|, |v72|
	v_max3_f32 v218, v218, |v76|, |v80|
	v_max3_f32 v218, v218, |v84|, |v88|
	v_max3_f32 v218, v218, |v92|, |v96|
	v_max3_f32 v218, v218, |v100|, |v104|
	v_max3_f32 v218, v218, |v108|, |v112|
	v_max3_f32 v218, v218, |v116|, |v120|
	v_max3_f32 v218, v218, |v124|, |v128|
	v_max_f32_e64 v218, v218, |v132|
	v_max3_f32 v219, |v9|, |v13|, |v17|
	v_max3_f32 v219, v219, |v21|, |v25|
	v_max3_f32 v219, v219, |v29|, |v33|
	v_max3_f32 v219, v219, |v37|, |v41|
	v_max3_f32 v219, v219, |v45|, |v49|
	v_max3_f32 v219, v219, |v53|, |v57|
	v_max3_f32 v219, v219, |v61|, |v65|
	v_max3_f32 v219, v219, |v69|, |v73|
	v_max3_f32 v219, v219, |v77|, |v81|
	v_max3_f32 v219, v219, |v85|, |v89|
	v_max3_f32 v219, v219, |v93|, |v97|
	v_max3_f32 v219, v219, |v101|, |v105|
	v_max3_f32 v219, v219, |v109|, |v113|
	v_max3_f32 v219, v219, |v117|, |v121|
	v_max3_f32 v219, v219, |v125|, |v129|
	v_max_f32_e64 v219, v219, |v133|
	ds_bpermute_b32 v174, v192, v216
	ds_bpermute_b32 v175, v192, v217
	ds_bpermute_b32 v176, v192, v218
	ds_bpermute_b32 v177, v192, v219
	s_waitcnt lgkmcnt(0)
	v_max_f32_e32 v216, v216, v174
	v_max_f32_e32 v217, v217, v175
	v_max_f32_e32 v218, v218, v176
	v_max_f32_e32 v219, v219, v177
	ds_bpermute_b32 v174, v193, v216
	ds_bpermute_b32 v175, v193, v217
	ds_bpermute_b32 v176, v193, v218
	ds_bpermute_b32 v177, v193, v219
	s_waitcnt lgkmcnt(0)
	v_max_f32_e32 v216, v216, v174
	v_max_f32_e32 v217, v217, v175
	v_max_f32_e32 v218, v218, v176
	v_max_f32_e32 v219, v219, v177
	ds_bpermute_b32 v174, v194, v216
	ds_bpermute_b32 v175, v194, v217
	ds_bpermute_b32 v176, v194, v218
	ds_bpermute_b32 v177, v194, v219
	s_waitcnt lgkmcnt(0)
	v_max_f32_e32 v216, v216, v174
	v_max_f32_e32 v217, v217, v175
	v_max_f32_e32 v218, v218, v176
	v_max_f32_e32 v219, v219, v177
	ds_bpermute_b32 v174, v195, v216
	ds_bpermute_b32 v175, v195, v217
	ds_bpermute_b32 v176, v195, v218
	ds_bpermute_b32 v177, v195, v219
	s_waitcnt lgkmcnt(0)
	v_max_f32_e32 v216, v216, v174
	v_max_f32_e32 v217, v217, v175
	v_max_f32_e32 v218, v218, v176
	v_max_f32_e32 v219, v219, v177
	s_mov_b64 s[70:71], exec
	s_mov_b64 exec, 15
	ds_write_b128 v172, v[216:219]
	s_mov_b64 exec, s[70:71]
	s_waitcnt lgkmcnt(0)
	s_barrier
	ds_read_b128 v[140:143], v173 offset:0
	ds_read_b128 v[144:147], v173 offset:64
	ds_read_b128 v[148:151], v173 offset:128
	ds_read_b128 v[152:155], v173 offset:192
	ds_read_b128 v[156:159], v173 offset:256
	ds_read_b128 v[160:163], v173 offset:320
	ds_read_b128 v[164:167], v173 offset:384
	ds_read_b128 v[232:235], v173 offset:448
	s_waitcnt lgkmcnt(0)
	v_max3_f32 v220, v140, v144, v148
	v_max3_f32 v220, v220, v152, v156
	v_max3_f32 v220, v220, v160, v164
	v_max_f32_e32 v220, v220, v232
	v_max3_f32 v221, v141, v145, v149
	v_max3_f32 v221, v221, v153, v157
	v_max3_f32 v221, v221, v161, v165
	v_max_f32_e32 v221, v221, v233
	v_max3_f32 v222, v142, v146, v150
	v_max3_f32 v222, v222, v154, v158
	v_max3_f32 v222, v222, v162, v166
	v_max_f32_e32 v222, v222, v234
	v_max3_f32 v223, v143, v147, v151
	v_max3_f32 v223, v223, v155, v159
	v_max3_f32 v223, v223, v163, v167
	v_max_f32_e32 v223, v223, v235
	s_cmp_lg_u32 s1, 0
	s_cbranch_scc1 .Lc16_gates_nocm
	s_lshl_b32 s3, s2, 2
	s_add_u32 s56, s34, s3
	s_addc_u32 s57, s35, 0
	s_add_u32 s56, s56, 0x80000
	s_addc_u32 s57, s57, 0
	s_mov_b64 s[70:71], exec
	s_mov_b64 exec, 15
	global_store_dwordx4 v230, v[220:223], s[56:57]
	s_mov_b64 exec, s[70:71]
.Lc16_gates_nocm:
	v_div_scale_f32 v175, s[70:71], v220, v220, s74
	v_rcp_f32_e32 v176, v175
	s_nop 0
	v_fma_f32 v177, -v175, v176, 1.0
	v_fmac_f32_e32 v176, v177, v176
	v_div_scale_f32 v177, vcc, s74, v220, s74
	v_mul_f32_e32 v178, v177, v176
	v_fma_f32 v180, -v175, v178, v177
	v_fmac_f32_e32 v178, v180, v176
	v_fma_f32 v175, -v175, v178, v177
	s_nop 0
	v_div_fmas_f32 v175, v175, v176, v178
	v_div_fixup_f32 v175, v175, v220, s74
	v_cmp_lt_f32_e32 vcc, 0, v220
	s_nop 1
	v_cndmask_b32_e32 v226, 0, v175, vcc
	v_div_scale_f32 v175, s[70:71], v221, v221, s74
	v_rcp_f32_e32 v176, v175
	s_nop 0
	v_fma_f32 v177, -v175, v176, 1.0
	v_fmac_f32_e32 v176, v177, v176
	v_div_scale_f32 v177, vcc, s74, v221, s74
	v_mul_f32_e32 v178, v177, v176
	v_fma_f32 v180, -v175, v178, v177
	v_fmac_f32_e32 v178, v180, v176
	v_fma_f32 v175, -v175, v178, v177
	s_nop 0
	v_div_fmas_f32 v175, v175, v176, v178
	v_div_fixup_f32 v175, v175, v221, s74
	v_cmp_lt_f32_e32 vcc, 0, v221
	s_nop 1
	v_cndmask_b32_e32 v227, 0, v175, vcc
	v_div_scale_f32 v175, s[70:71], v222, v222, s74
	v_rcp_f32_e32 v176, v175
	s_nop 0
	v_fma_f32 v177, -v175, v176, 1.0
	v_fmac_f32_e32 v176, v177, v176
	v_div_scale_f32 v177, vcc, s74, v222, s74
	v_mul_f32_e32 v178, v177, v176
	v_fma_f32 v180, -v175, v178, v177
	v_fmac_f32_e32 v178, v180, v176
	v_fma_f32 v175, -v175, v178, v177
	s_nop 0
	v_div_fmas_f32 v175, v175, v176, v178
	v_div_fixup_f32 v175, v175, v222, s74
	v_cmp_lt_f32_e32 vcc, 0, v222
	s_nop 1
	v_cndmask_b32_e32 v228, 0, v175, vcc
	v_div_scale_f32 v175, s[70:71], v223, v223, s74
	v_rcp_f32_e32 v176, v175
	s_nop 0
	v_fma_f32 v177, -v175, v176, 1.0
	v_fmac_f32_e32 v176, v177, v176
	v_div_scale_f32 v177, vcc, s74, v223, s74
	v_mul_f32_e32 v178, v177, v176
	v_fma_f32 v180, -v175, v178, v177
	v_fmac_f32_e32 v178, v180, v176
	v_fma_f32 v175, -v175, v178, v177
	s_nop 0
	v_div_fmas_f32 v175, v175, v176, v178
	v_div_fixup_f32 v175, v175, v223, s74
	v_cmp_lt_f32_e32 vcc, 0, v223
	s_nop 1
	v_cndmask_b32_e32 v229, 0, v175, vcc
	s_add_u32 s10, s0, s33
	s_lshl_b32 s3, s10, 6
	s_add_u32 s56, s48, s3
	s_addc_u32 s57, s49, 0
	v_mul_f32_e32 v186, v6, v226
	v_rndne_f32_e32 v186, v186
	v_cvt_i32_f32_e32 v186, v186
	v_mul_f32_e32 v187, v10, v226
	v_rndne_f32_e32 v187, v187
	v_cvt_i32_f32_e32 v187, v187
	v_mul_f32_e32 v188, v14, v226
	v_rndne_f32_e32 v188, v188
	v_cvt_i32_f32_e32 v188, v188
	v_mul_f32_e32 v189, v18, v226
	v_rndne_f32_e32 v189, v189
	v_cvt_i32_f32_e32 v189, v189
	v_and_b32_e32 v186, 0xff, v186
	v_and_b32_e32 v187, 0xff, v187
	v_and_b32_e32 v188, 0xff, v188
	v_lshl_or_b32 v190, v187, 8, v186
	v_lshl_or_b32 v190, v188, 16, v190
	v_lshl_or_b32 v190, v189, 24, v190
	ds_write_b32 v139, v190 offset:0
	v_mul_f32_e32 v186, v7, v227
	v_rndne_f32_e32 v186, v186
	v_cvt_i32_f32_e32 v186, v186
	v_mul_f32_e32 v187, v11, v227
	v_rndne_f32_e32 v187, v187
	v_cvt_i32_f32_e32 v187, v187
	v_mul_f32_e32 v188, v15, v227
	v_rndne_f32_e32 v188, v188
	v_cvt_i32_f32_e32 v188, v188
	v_mul_f32_e32 v189, v19, v227
	v_rndne_f32_e32 v189, v189
	v_cvt_i32_f32_e32 v189, v189
	v_and_b32_e32 v186, 0xff, v186
	v_and_b32_e32 v187, 0xff, v187
	v_and_b32_e32 v188, 0xff, v188
	v_lshl_or_b32 v190, v187, 8, v186
	v_lshl_or_b32 v190, v188, 16, v190
	v_lshl_or_b32 v190, v189, 24, v190
	ds_write_b32 v139, v190 offset:512
	v_mul_f32_e32 v186, v8, v228
	v_rndne_f32_e32 v186, v186
	v_cvt_i32_f32_e32 v186, v186
	v_mul_f32_e32 v187, v12, v228
	v_rndne_f32_e32 v187, v187
	v_cvt_i32_f32_e32 v187, v187
	v_mul_f32_e32 v188, v16, v228
	v_rndne_f32_e32 v188, v188
	v_cvt_i32_f32_e32 v188, v188
	v_mul_f32_e32 v189, v20, v228
	v_rndne_f32_e32 v189, v189
	v_cvt_i32_f32_e32 v189, v189
	v_and_b32_e32 v186, 0xff, v186
	v_and_b32_e32 v187, 0xff, v187
	v_and_b32_e32 v188, 0xff, v188
	v_lshl_or_b32 v190, v187, 8, v186
	v_lshl_or_b32 v190, v188, 16, v190
	v_lshl_or_b32 v190, v189, 24, v190
	ds_write_b32 v139, v190 offset:1024
	v_mul_f32_e32 v186, v9, v229
	v_rndne_f32_e32 v186, v186
	v_cvt_i32_f32_e32 v186, v186
	v_mul_f32_e32 v187, v13, v229
	v_rndne_f32_e32 v187, v187
	v_cvt_i32_f32_e32 v187, v187
	v_mul_f32_e32 v188, v17, v229
	v_rndne_f32_e32 v188, v188
	v_cvt_i32_f32_e32 v188, v188
	v_mul_f32_e32 v189, v21, v229
	v_rndne_f32_e32 v189, v189
	v_cvt_i32_f32_e32 v189, v189
	v_and_b32_e32 v186, 0xff, v186
	v_and_b32_e32 v187, 0xff, v187
	v_and_b32_e32 v188, 0xff, v188
	v_lshl_or_b32 v190, v187, 8, v186
	v_lshl_or_b32 v190, v188, 16, v190
	v_lshl_or_b32 v190, v189, 24, v190
	ds_write_b32 v139, v190 offset:1536
	s_cmp_ge_u32 s10, 0x200
	s_cbranch_scc1 .Lc16_gates_nopf_0
	global_load_dwordx4 v[6:9], v138, s[56:57] nt
	s_add_u32 s56, s56, 0x8000
	s_addc_u32 s57, s57, 0
	global_load_dwordx4 v[10:13], v138, s[56:57] nt
	s_add_u32 s56, s56, 0x8000
	s_addc_u32 s57, s57, 0
	global_load_dwordx4 v[14:17], v138, s[56:57] nt
	s_add_u32 s56, s56, 0x8000
	s_addc_u32 s57, s57, 0
	global_load_dwordx4 v[18:21], v138, s[56:57] nt
	s_add_u32 s56, s56, 0x1e8000
	s_addc_u32 s57, s57, 0
.Lc16_gates_nopf_0:
	v_mul_f32_e32 v186, v22, v226
	v_rndne_f32_e32 v186, v186
	v_cvt_i32_f32_e32 v186, v186
	v_mul_f32_e32 v187, v26, v226
	v_rndne_f32_e32 v187, v187
	v_cvt_i32_f32_e32 v187, v187
	v_mul_f32_e32 v188, v30, v226
	v_rndne_f32_e32 v188, v188
	v_cvt_i32_f32_e32 v188, v188
	v_mul_f32_e32 v189, v34, v226
	v_rndne_f32_e32 v189, v189
	v_cvt_i32_f32_e32 v189, v189
	v_and_b32_e32 v186, 0xff, v186
	v_and_b32_e32 v187, 0xff, v187
	v_and_b32_e32 v188, 0xff, v188
	v_lshl_or_b32 v190, v187, 8, v186
	v_lshl_or_b32 v190, v188, 16, v190
	v_lshl_or_b32 v190, v189, 24, v190
	ds_write_b32 v139, v190 offset:64
	v_mul_f32_e32 v186, v23, v227
	v_rndne_f32_e32 v186, v186
	v_cvt_i32_f32_e32 v186, v186
	v_mul_f32_e32 v187, v27, v227
	v_rndne_f32_e32 v187, v187
	v_cvt_i32_f32_e32 v187, v187
	v_mul_f32_e32 v188, v31, v227
	v_rndne_f32_e32 v188, v188
	v_cvt_i32_f32_e32 v188, v188
	v_mul_f32_e32 v189, v35, v227
	v_rndne_f32_e32 v189, v189
	v_cvt_i32_f32_e32 v189, v189
	v_and_b32_e32 v186, 0xff, v186
	v_and_b32_e32 v187, 0xff, v187
	v_and_b32_e32 v188, 0xff, v188
	v_lshl_or_b32 v190, v187, 8, v186
	v_lshl_or_b32 v190, v188, 16, v190
	v_lshl_or_b32 v190, v189, 24, v190
	ds_write_b32 v139, v190 offset:576
	v_mul_f32_e32 v186, v24, v228
	v_rndne_f32_e32 v186, v186
	v_cvt_i32_f32_e32 v186, v186
	v_mul_f32_e32 v187, v28, v228
	v_rndne_f32_e32 v187, v187
	v_cvt_i32_f32_e32 v187, v187
	v_mul_f32_e32 v188, v32, v228
	v_rndne_f32_e32 v188, v188
	v_cvt_i32_f32_e32 v188, v188
	v_mul_f32_e32 v189, v36, v228
	v_rndne_f32_e32 v189, v189
	v_cvt_i32_f32_e32 v189, v189
	v_and_b32_e32 v186, 0xff, v186
	v_and_b32_e32 v187, 0xff, v187
	v_and_b32_e32 v188, 0xff, v188
	v_lshl_or_b32 v190, v187, 8, v186
	v_lshl_or_b32 v190, v188, 16, v190
	v_lshl_or_b32 v190, v189, 24, v190
	ds_write_b32 v139, v190 offset:1088
	v_mul_f32_e32 v186, v25, v229
	v_rndne_f32_e32 v186, v186
	v_cvt_i32_f32_e32 v186, v186
	v_mul_f32_e32 v187, v29, v229
	v_rndne_f32_e32 v187, v187
	v_cvt_i32_f32_e32 v187, v187
	v_mul_f32_e32 v188, v33, v229
	v_rndne_f32_e32 v188, v188
	v_cvt_i32_f32_e32 v188, v188
	v_mul_f32_e32 v189, v37, v229
	v_rndne_f32_e32 v189, v189
	v_cvt_i32_f32_e32 v189, v189
	v_and_b32_e32 v186, 0xff, v186
	v_and_b32_e32 v187, 0xff, v187
	v_and_b32_e32 v188, 0xff, v188
	v_lshl_or_b32 v190, v187, 8, v186
	v_lshl_or_b32 v190, v188, 16, v190
	v_lshl_or_b32 v190, v189, 24, v190
	ds_write_b32 v139, v190 offset:1600
	s_cmp_ge_u32 s10, 0x200
	s_cbranch_scc1 .Lc16_gates_nopf_1
	global_load_dwordx4 v[22:25], v138, s[56:57] nt
	s_add_u32 s56, s56, 0x8000
	s_addc_u32 s57, s57, 0
	global_load_dwordx4 v[26:29], v138, s[56:57] nt
	s_add_u32 s56, s56, 0x8000
	s_addc_u32 s57, s57, 0
	global_load_dwordx4 v[30:33], v138, s[56:57] nt
	s_add_u32 s56, s56, 0x8000
	s_addc_u32 s57, s57, 0
	global_load_dwordx4 v[34:37], v138, s[56:57] nt
	s_add_u32 s56, s56, 0x1e8000
	s_addc_u32 s57, s57, 0
.Lc16_gates_nopf_1:
	v_mul_f32_e32 v186, v38, v226
	v_rndne_f32_e32 v186, v186
	v_cvt_i32_f32_e32 v186, v186
	v_mul_f32_e32 v187, v42, v226
	v_rndne_f32_e32 v187, v187
	v_cvt_i32_f32_e32 v187, v187
	v_mul_f32_e32 v188, v46, v226
	v_rndne_f32_e32 v188, v188
	v_cvt_i32_f32_e32 v188, v188
	v_mul_f32_e32 v189, v50, v226
	v_rndne_f32_e32 v189, v189
	v_cvt_i32_f32_e32 v189, v189
	v_and_b32_e32 v186, 0xff, v186
	v_and_b32_e32 v187, 0xff, v187
	v_and_b32_e32 v188, 0xff, v188
	v_lshl_or_b32 v190, v187, 8, v186
	v_lshl_or_b32 v190, v188, 16, v190
	v_lshl_or_b32 v190, v189, 24, v190
	ds_write_b32 v139, v190 offset:128
	v_mul_f32_e32 v186, v39, v227
	v_rndne_f32_e32 v186, v186
	v_cvt_i32_f32_e32 v186, v186
	v_mul_f32_e32 v187, v43, v227
	v_rndne_f32_e32 v187, v187
	v_cvt_i32_f32_e32 v187, v187
	v_mul_f32_e32 v188, v47, v227
	v_rndne_f32_e32 v188, v188
	v_cvt_i32_f32_e32 v188, v188
	v_mul_f32_e32 v189, v51, v227
	v_rndne_f32_e32 v189, v189
	v_cvt_i32_f32_e32 v189, v189
	v_and_b32_e32 v186, 0xff, v186
	v_and_b32_e32 v187, 0xff, v187
	v_and_b32_e32 v188, 0xff, v188
	v_lshl_or_b32 v190, v187, 8, v186
	v_lshl_or_b32 v190, v188, 16, v190
	v_lshl_or_b32 v190, v189, 24, v190
	ds_write_b32 v139, v190 offset:640
	v_mul_f32_e32 v186, v40, v228
	v_rndne_f32_e32 v186, v186
	v_cvt_i32_f32_e32 v186, v186
	v_mul_f32_e32 v187, v44, v228
	v_rndne_f32_e32 v187, v187
	v_cvt_i32_f32_e32 v187, v187
	v_mul_f32_e32 v188, v48, v228
	v_rndne_f32_e32 v188, v188
	v_cvt_i32_f32_e32 v188, v188
	v_mul_f32_e32 v189, v52, v228
	v_rndne_f32_e32 v189, v189
	v_cvt_i32_f32_e32 v189, v189
	v_and_b32_e32 v186, 0xff, v186
	v_and_b32_e32 v187, 0xff, v187
	v_and_b32_e32 v188, 0xff, v188
	v_lshl_or_b32 v190, v187, 8, v186
	v_lshl_or_b32 v190, v188, 16, v190
	v_lshl_or_b32 v190, v189, 24, v190
	ds_write_b32 v139, v190 offset:1152
	v_mul_f32_e32 v186, v41, v229
	v_rndne_f32_e32 v186, v186
	v_cvt_i32_f32_e32 v186, v186
	v_mul_f32_e32 v187, v45, v229
	v_rndne_f32_e32 v187, v187
	v_cvt_i32_f32_e32 v187, v187
	v_mul_f32_e32 v188, v49, v229
	v_rndne_f32_e32 v188, v188
	v_cvt_i32_f32_e32 v188, v188
	v_mul_f32_e32 v189, v53, v229
	v_rndne_f32_e32 v189, v189
	v_cvt_i32_f32_e32 v189, v189
	v_and_b32_e32 v186, 0xff, v186
	v_and_b32_e32 v187, 0xff, v187
	v_and_b32_e32 v188, 0xff, v188
	v_lshl_or_b32 v190, v187, 8, v186
	v_lshl_or_b32 v190, v188, 16, v190
	v_lshl_or_b32 v190, v189, 24, v190
	ds_write_b32 v139, v190 offset:1664
	s_cmp_ge_u32 s10, 0x200
	s_cbranch_scc1 .Lc16_gates_nopf_2
	global_load_dwordx4 v[38:41], v138, s[56:57] nt
	s_add_u32 s56, s56, 0x8000
	s_addc_u32 s57, s57, 0
	global_load_dwordx4 v[42:45], v138, s[56:57] nt
	s_add_u32 s56, s56, 0x8000
	s_addc_u32 s57, s57, 0
	global_load_dwordx4 v[46:49], v138, s[56:57] nt
	s_add_u32 s56, s56, 0x8000
	s_addc_u32 s57, s57, 0
	global_load_dwordx4 v[50:53], v138, s[56:57] nt
	s_add_u32 s56, s56, 0x1e8000
	s_addc_u32 s57, s57, 0
.Lc16_gates_nopf_2:
	v_mul_f32_e32 v186, v54, v226
	v_rndne_f32_e32 v186, v186
	v_cvt_i32_f32_e32 v186, v186
	v_mul_f32_e32 v187, v58, v226
	v_rndne_f32_e32 v187, v187
	v_cvt_i32_f32_e32 v187, v187
	v_mul_f32_e32 v188, v62, v226
	v_rndne_f32_e32 v188, v188
	v_cvt_i32_f32_e32 v188, v188
	v_mul_f32_e32 v189, v66, v226
	v_rndne_f32_e32 v189, v189
	v_cvt_i32_f32_e32 v189, v189
	v_and_b32_e32 v186, 0xff, v186
	v_and_b32_e32 v187, 0xff, v187
	v_and_b32_e32 v188, 0xff, v188
	v_lshl_or_b32 v190, v187, 8, v186
	v_lshl_or_b32 v190, v188, 16, v190
	v_lshl_or_b32 v190, v189, 24, v190
	ds_write_b32 v139, v190 offset:192
	v_mul_f32_e32 v186, v55, v227
	v_rndne_f32_e32 v186, v186
	v_cvt_i32_f32_e32 v186, v186
	v_mul_f32_e32 v187, v59, v227
	v_rndne_f32_e32 v187, v187
	v_cvt_i32_f32_e32 v187, v187
	v_mul_f32_e32 v188, v63, v227
	v_rndne_f32_e32 v188, v188
	v_cvt_i32_f32_e32 v188, v188
	v_mul_f32_e32 v189, v67, v227
	v_rndne_f32_e32 v189, v189
	v_cvt_i32_f32_e32 v189, v189
	v_and_b32_e32 v186, 0xff, v186
	v_and_b32_e32 v187, 0xff, v187
	v_and_b32_e32 v188, 0xff, v188
	v_lshl_or_b32 v190, v187, 8, v186
	v_lshl_or_b32 v190, v188, 16, v190
	v_lshl_or_b32 v190, v189, 24, v190
	ds_write_b32 v139, v190 offset:704
	v_mul_f32_e32 v186, v56, v228
	v_rndne_f32_e32 v186, v186
	v_cvt_i32_f32_e32 v186, v186
	v_mul_f32_e32 v187, v60, v228
	v_rndne_f32_e32 v187, v187
	v_cvt_i32_f32_e32 v187, v187
	v_mul_f32_e32 v188, v64, v228
	v_rndne_f32_e32 v188, v188
	v_cvt_i32_f32_e32 v188, v188
	v_mul_f32_e32 v189, v68, v228
	v_rndne_f32_e32 v189, v189
	v_cvt_i32_f32_e32 v189, v189
	v_and_b32_e32 v186, 0xff, v186
	v_and_b32_e32 v187, 0xff, v187
	v_and_b32_e32 v188, 0xff, v188
	v_lshl_or_b32 v190, v187, 8, v186
	v_lshl_or_b32 v190, v188, 16, v190
	v_lshl_or_b32 v190, v189, 24, v190
	ds_write_b32 v139, v190 offset:1216
	v_mul_f32_e32 v186, v57, v229
	v_rndne_f32_e32 v186, v186
	v_cvt_i32_f32_e32 v186, v186
	v_mul_f32_e32 v187, v61, v229
	v_rndne_f32_e32 v187, v187
	v_cvt_i32_f32_e32 v187, v187
	v_mul_f32_e32 v188, v65, v229
	v_rndne_f32_e32 v188, v188
	v_cvt_i32_f32_e32 v188, v188
	v_mul_f32_e32 v189, v69, v229
	v_rndne_f32_e32 v189, v189
	v_cvt_i32_f32_e32 v189, v189
	v_and_b32_e32 v186, 0xff, v186
	v_and_b32_e32 v187, 0xff, v187
	v_and_b32_e32 v188, 0xff, v188
	v_lshl_or_b32 v190, v187, 8, v186
	v_lshl_or_b32 v190, v188, 16, v190
	v_lshl_or_b32 v190, v189, 24, v190
	ds_write_b32 v139, v190 offset:1728
	s_cmp_ge_u32 s10, 0x200
	s_cbranch_scc1 .Lc16_gates_nopf_3
	global_load_dwordx4 v[54:57], v138, s[56:57] nt
	s_add_u32 s56, s56, 0x8000
	s_addc_u32 s57, s57, 0
	global_load_dwordx4 v[58:61], v138, s[56:57] nt
	s_add_u32 s56, s56, 0x8000
	s_addc_u32 s57, s57, 0
	global_load_dwordx4 v[62:65], v138, s[56:57] nt
	s_add_u32 s56, s56, 0x8000
	s_addc_u32 s57, s57, 0
	global_load_dwordx4 v[66:69], v138, s[56:57] nt
	s_add_u32 s56, s56, 0x1e8000
	s_addc_u32 s57, s57, 0
.Lc16_gates_nopf_3:
	v_mul_f32_e32 v186, v70, v226
	v_rndne_f32_e32 v186, v186
	v_cvt_i32_f32_e32 v186, v186
	v_mul_f32_e32 v187, v74, v226
	v_rndne_f32_e32 v187, v187
	v_cvt_i32_f32_e32 v187, v187
	v_mul_f32_e32 v188, v78, v226
	v_rndne_f32_e32 v188, v188
	v_cvt_i32_f32_e32 v188, v188
	v_mul_f32_e32 v189, v82, v226
	v_rndne_f32_e32 v189, v189
	v_cvt_i32_f32_e32 v189, v189
	v_and_b32_e32 v186, 0xff, v186
	v_and_b32_e32 v187, 0xff, v187
	v_and_b32_e32 v188, 0xff, v188
	v_lshl_or_b32 v190, v187, 8, v186
	v_lshl_or_b32 v190, v188, 16, v190
	v_lshl_or_b32 v190, v189, 24, v190
	ds_write_b32 v139, v190 offset:256
	v_mul_f32_e32 v186, v71, v227
	v_rndne_f32_e32 v186, v186
	v_cvt_i32_f32_e32 v186, v186
	v_mul_f32_e32 v187, v75, v227
	v_rndne_f32_e32 v187, v187
	v_cvt_i32_f32_e32 v187, v187
	v_mul_f32_e32 v188, v79, v227
	v_rndne_f32_e32 v188, v188
	v_cvt_i32_f32_e32 v188, v188
	v_mul_f32_e32 v189, v83, v227
	v_rndne_f32_e32 v189, v189
	v_cvt_i32_f32_e32 v189, v189
	v_and_b32_e32 v186, 0xff, v186
	v_and_b32_e32 v187, 0xff, v187
	v_and_b32_e32 v188, 0xff, v188
	v_lshl_or_b32 v190, v187, 8, v186
	v_lshl_or_b32 v190, v188, 16, v190
	v_lshl_or_b32 v190, v189, 24, v190
	ds_write_b32 v139, v190 offset:768
	v_mul_f32_e32 v186, v72, v228
	v_rndne_f32_e32 v186, v186
	v_cvt_i32_f32_e32 v186, v186
	v_mul_f32_e32 v187, v76, v228
	v_rndne_f32_e32 v187, v187
	v_cvt_i32_f32_e32 v187, v187
	v_mul_f32_e32 v188, v80, v228
	v_rndne_f32_e32 v188, v188
	v_cvt_i32_f32_e32 v188, v188
	v_mul_f32_e32 v189, v84, v228
	v_rndne_f32_e32 v189, v189
	v_cvt_i32_f32_e32 v189, v189
	v_and_b32_e32 v186, 0xff, v186
	v_and_b32_e32 v187, 0xff, v187
	v_and_b32_e32 v188, 0xff, v188
	v_lshl_or_b32 v190, v187, 8, v186
	v_lshl_or_b32 v190, v188, 16, v190
	v_lshl_or_b32 v190, v189, 24, v190
	ds_write_b32 v139, v190 offset:1280
	v_mul_f32_e32 v186, v73, v229
	v_rndne_f32_e32 v186, v186
	v_cvt_i32_f32_e32 v186, v186
	v_mul_f32_e32 v187, v77, v229
	v_rndne_f32_e32 v187, v187
	v_cvt_i32_f32_e32 v187, v187
	v_mul_f32_e32 v188, v81, v229
	v_rndne_f32_e32 v188, v188
	v_cvt_i32_f32_e32 v188, v188
	v_mul_f32_e32 v189, v85, v229
	v_rndne_f32_e32 v189, v189
	v_cvt_i32_f32_e32 v189, v189
	v_and_b32_e32 v186, 0xff, v186
	v_and_b32_e32 v187, 0xff, v187
	v_and_b32_e32 v188, 0xff, v188
	v_lshl_or_b32 v190, v187, 8, v186
	v_lshl_or_b32 v190, v188, 16, v190
	v_lshl_or_b32 v190, v189, 24, v190
	ds_write_b32 v139, v190 offset:1792
	s_cmp_ge_u32 s10, 0x200
	s_cbranch_scc1 .Lc16_gates_nopf_4
	global_load_dwordx4 v[70:73], v138, s[56:57] nt
	s_add_u32 s56, s56, 0x8000
	s_addc_u32 s57, s57, 0
	global_load_dwordx4 v[74:77], v138, s[56:57] nt
	s_add_u32 s56, s56, 0x8000
	s_addc_u32 s57, s57, 0
	global_load_dwordx4 v[78:81], v138, s[56:57] nt
	s_add_u32 s56, s56, 0x8000
	s_addc_u32 s57, s57, 0
	global_load_dwordx4 v[82:85], v138, s[56:57] nt
	s_add_u32 s56, s56, 0x1e8000
	s_addc_u32 s57, s57, 0
.Lc16_gates_nopf_4:
	v_mul_f32_e32 v186, v86, v226
	v_rndne_f32_e32 v186, v186
	v_cvt_i32_f32_e32 v186, v186
	v_mul_f32_e32 v187, v90, v226
	v_rndne_f32_e32 v187, v187
	v_cvt_i32_f32_e32 v187, v187
	v_mul_f32_e32 v188, v94, v226
	v_rndne_f32_e32 v188, v188
	v_cvt_i32_f32_e32 v188, v188
	v_mul_f32_e32 v189, v98, v226
	v_rndne_f32_e32 v189, v189
	v_cvt_i32_f32_e32 v189, v189
	v_and_b32_e32 v186, 0xff, v186
	v_and_b32_e32 v187, 0xff, v187
	v_and_b32_e32 v188, 0xff, v188
	v_lshl_or_b32 v190, v187, 8, v186
	v_lshl_or_b32 v190, v188, 16, v190
	v_lshl_or_b32 v190, v189, 24, v190
	ds_write_b32 v139, v190 offset:320
	v_mul_f32_e32 v186, v87, v227
	v_rndne_f32_e32 v186, v186
	v_cvt_i32_f32_e32 v186, v186
	v_mul_f32_e32 v187, v91, v227
	v_rndne_f32_e32 v187, v187
	v_cvt_i32_f32_e32 v187, v187
	v_mul_f32_e32 v188, v95, v227
	v_rndne_f32_e32 v188, v188
	v_cvt_i32_f32_e32 v188, v188
	v_mul_f32_e32 v189, v99, v227
	v_rndne_f32_e32 v189, v189
	v_cvt_i32_f32_e32 v189, v189
	v_and_b32_e32 v186, 0xff, v186
	v_and_b32_e32 v187, 0xff, v187
	v_and_b32_e32 v188, 0xff, v188
	v_lshl_or_b32 v190, v187, 8, v186
	v_lshl_or_b32 v190, v188, 16, v190
	v_lshl_or_b32 v190, v189, 24, v190
	ds_write_b32 v139, v190 offset:832
	v_mul_f32_e32 v186, v88, v228
	v_rndne_f32_e32 v186, v186
	v_cvt_i32_f32_e32 v186, v186
	v_mul_f32_e32 v187, v92, v228
	v_rndne_f32_e32 v187, v187
	v_cvt_i32_f32_e32 v187, v187
	v_mul_f32_e32 v188, v96, v228
	v_rndne_f32_e32 v188, v188
	v_cvt_i32_f32_e32 v188, v188
	v_mul_f32_e32 v189, v100, v228
	v_rndne_f32_e32 v189, v189
	v_cvt_i32_f32_e32 v189, v189
	v_and_b32_e32 v186, 0xff, v186
	v_and_b32_e32 v187, 0xff, v187
	v_and_b32_e32 v188, 0xff, v188
	v_lshl_or_b32 v190, v187, 8, v186
	v_lshl_or_b32 v190, v188, 16, v190
	v_lshl_or_b32 v190, v189, 24, v190
	ds_write_b32 v139, v190 offset:1344
	v_mul_f32_e32 v186, v89, v229
	v_rndne_f32_e32 v186, v186
	v_cvt_i32_f32_e32 v186, v186
	v_mul_f32_e32 v187, v93, v229
	v_rndne_f32_e32 v187, v187
	v_cvt_i32_f32_e32 v187, v187
	v_mul_f32_e32 v188, v97, v229
	v_rndne_f32_e32 v188, v188
	v_cvt_i32_f32_e32 v188, v188
	v_mul_f32_e32 v189, v101, v229
	v_rndne_f32_e32 v189, v189
	v_cvt_i32_f32_e32 v189, v189
	v_and_b32_e32 v186, 0xff, v186
	v_and_b32_e32 v187, 0xff, v187
	v_and_b32_e32 v188, 0xff, v188
	v_lshl_or_b32 v190, v187, 8, v186
	v_lshl_or_b32 v190, v188, 16, v190
	v_lshl_or_b32 v190, v189, 24, v190
	ds_write_b32 v139, v190 offset:1856
	s_cmp_ge_u32 s10, 0x200
	s_cbranch_scc1 .Lc16_gates_nopf_5
	global_load_dwordx4 v[86:89], v138, s[56:57] nt
	s_add_u32 s56, s56, 0x8000
	s_addc_u32 s57, s57, 0
	global_load_dwordx4 v[90:93], v138, s[56:57] nt
	s_add_u32 s56, s56, 0x8000
	s_addc_u32 s57, s57, 0
	global_load_dwordx4 v[94:97], v138, s[56:57] nt
	s_add_u32 s56, s56, 0x8000
	s_addc_u32 s57, s57, 0
	global_load_dwordx4 v[98:101], v138, s[56:57] nt
	s_add_u32 s56, s56, 0x1e8000
	s_addc_u32 s57, s57, 0
.Lc16_gates_nopf_5:
	v_mul_f32_e32 v186, v102, v226
	v_rndne_f32_e32 v186, v186
	v_cvt_i32_f32_e32 v186, v186
	v_mul_f32_e32 v187, v106, v226
	v_rndne_f32_e32 v187, v187
	v_cvt_i32_f32_e32 v187, v187
	v_mul_f32_e32 v188, v110, v226
	v_rndne_f32_e32 v188, v188
	v_cvt_i32_f32_e32 v188, v188
	v_mul_f32_e32 v189, v114, v226
	v_rndne_f32_e32 v189, v189
	v_cvt_i32_f32_e32 v189, v189
	v_and_b32_e32 v186, 0xff, v186
	v_and_b32_e32 v187, 0xff, v187
	v_and_b32_e32 v188, 0xff, v188
	v_lshl_or_b32 v190, v187, 8, v186
	v_lshl_or_b32 v190, v188, 16, v190
	v_lshl_or_b32 v190, v189, 24, v190
	ds_write_b32 v139, v190 offset:384
	v_mul_f32_e32 v186, v103, v227
	v_rndne_f32_e32 v186, v186
	v_cvt_i32_f32_e32 v186, v186
	v_mul_f32_e32 v187, v107, v227
	v_rndne_f32_e32 v187, v187
	v_cvt_i32_f32_e32 v187, v187
	v_mul_f32_e32 v188, v111, v227
	v_rndne_f32_e32 v188, v188
	v_cvt_i32_f32_e32 v188, v188
	v_mul_f32_e32 v189, v115, v227
	v_rndne_f32_e32 v189, v189
	v_cvt_i32_f32_e32 v189, v189
	v_and_b32_e32 v186, 0xff, v186
	v_and_b32_e32 v187, 0xff, v187
	v_and_b32_e32 v188, 0xff, v188
	v_lshl_or_b32 v190, v187, 8, v186
	v_lshl_or_b32 v190, v188, 16, v190
	v_lshl_or_b32 v190, v189, 24, v190
	ds_write_b32 v139, v190 offset:896
	v_mul_f32_e32 v186, v104, v228
	v_rndne_f32_e32 v186, v186
	v_cvt_i32_f32_e32 v186, v186
	v_mul_f32_e32 v187, v108, v228
	v_rndne_f32_e32 v187, v187
	v_cvt_i32_f32_e32 v187, v187
	v_mul_f32_e32 v188, v112, v228
	v_rndne_f32_e32 v188, v188
	v_cvt_i32_f32_e32 v188, v188
	v_mul_f32_e32 v189, v116, v228
	v_rndne_f32_e32 v189, v189
	v_cvt_i32_f32_e32 v189, v189
	v_and_b32_e32 v186, 0xff, v186
	v_and_b32_e32 v187, 0xff, v187
	v_and_b32_e32 v188, 0xff, v188
	v_lshl_or_b32 v190, v187, 8, v186
	v_lshl_or_b32 v190, v188, 16, v190
	v_lshl_or_b32 v190, v189, 24, v190
	ds_write_b32 v139, v190 offset:1408
	v_mul_f32_e32 v186, v105, v229
	v_rndne_f32_e32 v186, v186
	v_cvt_i32_f32_e32 v186, v186
	v_mul_f32_e32 v187, v109, v229
	v_rndne_f32_e32 v187, v187
	v_cvt_i32_f32_e32 v187, v187
	v_mul_f32_e32 v188, v113, v229
	v_rndne_f32_e32 v188, v188
	v_cvt_i32_f32_e32 v188, v188
	v_mul_f32_e32 v189, v117, v229
	v_rndne_f32_e32 v189, v189
	v_cvt_i32_f32_e32 v189, v189
	v_and_b32_e32 v186, 0xff, v186
	v_and_b32_e32 v187, 0xff, v187
	v_and_b32_e32 v188, 0xff, v188
	v_lshl_or_b32 v190, v187, 8, v186
	v_lshl_or_b32 v190, v188, 16, v190
	v_lshl_or_b32 v190, v189, 24, v190
	ds_write_b32 v139, v190 offset:1920
	s_cmp_ge_u32 s10, 0x200
	s_cbranch_scc1 .Lc16_gates_nopf_6
	global_load_dwordx4 v[102:105], v138, s[56:57] nt
	s_add_u32 s56, s56, 0x8000
	s_addc_u32 s57, s57, 0
	global_load_dwordx4 v[106:109], v138, s[56:57] nt
	s_add_u32 s56, s56, 0x8000
	s_addc_u32 s57, s57, 0
	global_load_dwordx4 v[110:113], v138, s[56:57] nt
	s_add_u32 s56, s56, 0x8000
	s_addc_u32 s57, s57, 0
	global_load_dwordx4 v[114:117], v138, s[56:57] nt
	s_add_u32 s56, s56, 0x1e8000
	s_addc_u32 s57, s57, 0
.Lc16_gates_nopf_6:
	v_mul_f32_e32 v186, v118, v226
	v_rndne_f32_e32 v186, v186
	v_cvt_i32_f32_e32 v186, v186
	v_mul_f32_e32 v187, v122, v226
	v_rndne_f32_e32 v187, v187
	v_cvt_i32_f32_e32 v187, v187
	v_mul_f32_e32 v188, v126, v226
	v_rndne_f32_e32 v188, v188
	v_cvt_i32_f32_e32 v188, v188
	v_mul_f32_e32 v189, v130, v226
	v_rndne_f32_e32 v189, v189
	v_cvt_i32_f32_e32 v189, v189
	v_and_b32_e32 v186, 0xff, v186
	v_and_b32_e32 v187, 0xff, v187
	v_and_b32_e32 v188, 0xff, v188
	v_lshl_or_b32 v190, v187, 8, v186
	v_lshl_or_b32 v190, v188, 16, v190
	v_lshl_or_b32 v190, v189, 24, v190
	ds_write_b32 v139, v190 offset:448
	v_mul_f32_e32 v186, v119, v227
	v_rndne_f32_e32 v186, v186
	v_cvt_i32_f32_e32 v186, v186
	v_mul_f32_e32 v187, v123, v227
	v_rndne_f32_e32 v187, v187
	v_cvt_i32_f32_e32 v187, v187
	v_mul_f32_e32 v188, v127, v227
	v_rndne_f32_e32 v188, v188
	v_cvt_i32_f32_e32 v188, v188
	v_mul_f32_e32 v189, v131, v227
	v_rndne_f32_e32 v189, v189
	v_cvt_i32_f32_e32 v189, v189
	v_and_b32_e32 v186, 0xff, v186
	v_and_b32_e32 v187, 0xff, v187
	v_and_b32_e32 v188, 0xff, v188
	v_lshl_or_b32 v190, v187, 8, v186
	v_lshl_or_b32 v190, v188, 16, v190
	v_lshl_or_b32 v190, v189, 24, v190
	ds_write_b32 v139, v190 offset:960
	v_mul_f32_e32 v186, v120, v228
	v_rndne_f32_e32 v186, v186
	v_cvt_i32_f32_e32 v186, v186
	v_mul_f32_e32 v187, v124, v228
	v_rndne_f32_e32 v187, v187
	v_cvt_i32_f32_e32 v187, v187
	v_mul_f32_e32 v188, v128, v228
	v_rndne_f32_e32 v188, v188
	v_cvt_i32_f32_e32 v188, v188
	v_mul_f32_e32 v189, v132, v228
	v_rndne_f32_e32 v189, v189
	v_cvt_i32_f32_e32 v189, v189
	v_and_b32_e32 v186, 0xff, v186
	v_and_b32_e32 v187, 0xff, v187
	v_and_b32_e32 v188, 0xff, v188
	v_lshl_or_b32 v190, v187, 8, v186
	v_lshl_or_b32 v190, v188, 16, v190
	v_lshl_or_b32 v190, v189, 24, v190
	ds_write_b32 v139, v190 offset:1472
	v_mul_f32_e32 v186, v121, v229
	v_rndne_f32_e32 v186, v186
	v_cvt_i32_f32_e32 v186, v186
	v_mul_f32_e32 v187, v125, v229
	v_rndne_f32_e32 v187, v187
	v_cvt_i32_f32_e32 v187, v187
	v_mul_f32_e32 v188, v129, v229
	v_rndne_f32_e32 v188, v188
	v_cvt_i32_f32_e32 v188, v188
	v_mul_f32_e32 v189, v133, v229
	v_rndne_f32_e32 v189, v189
	v_cvt_i32_f32_e32 v189, v189
	v_and_b32_e32 v186, 0xff, v186
	v_and_b32_e32 v187, 0xff, v187
	v_and_b32_e32 v188, 0xff, v188
	v_lshl_or_b32 v190, v187, 8, v186
	v_lshl_or_b32 v190, v188, 16, v190
	v_lshl_or_b32 v190, v189, 24, v190
	ds_write_b32 v139, v190 offset:1984
	s_cmp_ge_u32 s10, 0x200
	s_cbranch_scc1 .Lc16_gates_nopf_7
	global_load_dwordx4 v[118:121], v138, s[56:57] nt
	s_add_u32 s56, s56, 0x8000
	s_addc_u32 s57, s57, 0
	global_load_dwordx4 v[122:125], v138, s[56:57] nt
	s_add_u32 s56, s56, 0x8000
	s_addc_u32 s57, s57, 0
	global_load_dwordx4 v[126:129], v138, s[56:57] nt
	s_add_u32 s56, s56, 0x8000
	s_addc_u32 s57, s57, 0
	global_load_dwordx4 v[130:133], v138, s[56:57] nt
.Lc16_gates_nopf_7:
	s_waitcnt lgkmcnt(0)
	s_lshl_b32 s3, s60, 12
	s_lshl_b32 s10, s1, 9
	s_add_u32 s3, s3, s10
	s_add_u32 s58, s34, s3
	s_addc_u32 s59, s35, 0
	s_add_u32 s58, s58, 0x5100000
	s_addc_u32 s59, s59, 0
	ds_read_b128 v[204:207], v212 offset:0
	s_waitcnt lgkmcnt(0)
	global_store_dwordx4 v213, v[204:207], s[58:59]
	s_add_u32 s58, s58, 0x2000
	s_addc_u32 s59, s59, 0
	ds_read_b128 v[208:211], v212 offset:1024
	s_waitcnt lgkmcnt(0)
	global_store_dwordx4 v213, v[208:211], s[58:59]
	s_add_u32 s58, s58, 0x2000
	s_addc_u32 s59, s59, 0
	ds_read_b128 v[204:207], v212 offset:2048
	s_waitcnt lgkmcnt(0)
	global_store_dwordx4 v213, v[204:207], s[58:59]
	s_add_u32 s58, s58, 0x2000
	s_addc_u32 s59, s59, 0
	ds_read_b128 v[208:211], v212 offset:3072
	s_waitcnt lgkmcnt(0)
	global_store_dwordx4 v213, v[208:211], s[58:59]
	s_add_u32 s58, s58, 0x2000
	s_addc_u32 s59, s59, 0
	ds_read_b128 v[204:207], v212 offset:4096
	s_waitcnt lgkmcnt(0)
	global_store_dwordx4 v213, v[204:207], s[58:59]
	s_add_u32 s58, s58, 0x2000
	s_addc_u32 s59, s59, 0
	ds_read_b128 v[208:211], v212 offset:5120
	s_waitcnt lgkmcnt(0)
	global_store_dwordx4 v213, v[208:211], s[58:59]
	s_add_u32 s58, s58, 0x2000
	s_addc_u32 s59, s59, 0
	ds_read_b128 v[204:207], v212 offset:6144
	s_waitcnt lgkmcnt(0)
	global_store_dwordx4 v213, v[204:207], s[58:59]
	s_add_u32 s58, s58, 0x2000
	s_addc_u32 s59, s59, 0
	ds_read_b128 v[208:211], v212 offset:7168
	s_waitcnt lgkmcnt(0)
	global_store_dwordx4 v213, v[208:211], s[58:59]
	s_xor_b32 s11, s11, 1
	s_add_u32 s0, s0, s33
	s_cmp_lt_u32 s0, 0x200
	s_cbranch_scc1 .Lc16_gates_loop
.Lc16_gates_done:
	v_readlane_b32 s48, v255, 19
	v_readlane_b32 s49, v255, 20
	v_mul_u32_u24_e32 v138, 0x56000, v136
	v_lshl_add_u32 v138, v137, 4, v138
	s_mul_i32 s3, s1, 0x2b00000
	s_nop 1
	s_add_u32 s48, s48, s3
	s_addc_u32 s49, s49, 0
	s_mov_b32 s0, s72
	s_cmp_ge_u32 s0, 0x560
	s_cbranch_scc1 .Lc16_ffn1_done
	s_lshl_b32 s3, s0, 6
	s_add_u32 s56, s48, s3
	s_addc_u32 s57, s49, 0
	global_load_dwordx4 v[6:9], v138, s[56:57] nt
	s_add_u32 s56, s56, 0x15800
	s_addc_u32 s57, s57, 0
	global_load_dwordx4 v[10:13], v138, s[56:57] nt
	s_add_u32 s56, s56, 0x15800
	s_addc_u32 s57, s57, 0
	global_load_dwordx4 v[14:17], v138, s[56:57] nt
	s_add_u32 s56, s56, 0x15800
	s_addc_u32 s57, s57, 0
	global_load_dwordx4 v[18:21], v138, s[56:57] nt
	s_add_u32 s56, s56, 0x51f800
	s_addc_u32 s57, s57, 0
	global_load_dwordx4 v[22:25], v138, s[56:57] nt
	s_add_u32 s56, s56, 0x15800
	s_addc_u32 s57, s57, 0
	global_load_dwordx4 v[26:29], v138, s[56:57] nt
	s_add_u32 s56, s56, 0x15800
	s_addc_u32 s57, s57, 0
	global_load_dwordx4 v[30:33], v138, s[56:57] nt
	s_add_u32 s56, s56, 0x15800
	s_addc_u32 s57, s57, 0
	global_load_dwordx4 v[34:37], v138, s[56:57] nt
	s_add_u32 s56, s56, 0x51f800
	s_addc_u32 s57, s57, 0
	global_load_dwordx4 v[38:41], v138, s[56:57] nt
	s_add_u32 s56, s56, 0x15800
	s_addc_u32 s57, s57, 0
	global_load_dwordx4 v[42:45], v138, s[56:57] nt
	s_add_u32 s56, s56, 0x15800
	s_addc_u32 s57, s57, 0
	global_load_dwordx4 v[46:49], v138, s[56:57] nt
	s_add_u32 s56, s56, 0x15800
	s_addc_u32 s57, s57, 0
	global_load_dwordx4 v[50:53], v138, s[56:57] nt
	s_add_u32 s56, s56, 0x51f800
	s_addc_u32 s57, s57, 0
	global_load_dwordx4 v[54:57], v138, s[56:57] nt
	s_add_u32 s56, s56, 0x15800
	s_addc_u32 s57, s57, 0
	global_load_dwordx4 v[58:61], v138, s[56:57] nt
	s_add_u32 s56, s56, 0x15800
	s_addc_u32 s57, s57, 0
	global_load_dwordx4 v[62:65], v138, s[56:57] nt
	s_add_u32 s56, s56, 0x15800
	s_addc_u32 s57, s57, 0
	global_load_dwordx4 v[66:69], v138, s[56:57] nt
	s_add_u32 s56, s56, 0x51f800
	s_addc_u32 s57, s57, 0
	global_load_dwordx4 v[70:73], v138, s[56:57] nt
	s_add_u32 s56, s56, 0x15800
	s_addc_u32 s57, s57, 0
	global_load_dwordx4 v[74:77], v138, s[56:57] nt
	s_add_u32 s56, s56, 0x15800
	s_addc_u32 s57, s57, 0
	global_load_dwordx4 v[78:81], v138, s[56:57] nt
	s_add_u32 s56, s56, 0x15800
	s_addc_u32 s57, s57, 0
	global_load_dwordx4 v[82:85], v138, s[56:57] nt
	s_add_u32 s56, s56, 0x51f800
	s_addc_u32 s57, s57, 0
	global_load_dwordx4 v[86:89], v138, s[56:57] nt
	s_add_u32 s56, s56, 0x15800
	s_addc_u32 s57, s57, 0
	global_load_dwordx4 v[90:93], v138, s[56:57] nt
	s_add_u32 s56, s56, 0x15800
	s_addc_u32 s57, s57, 0
	global_load_dwordx4 v[94:97], v138, s[56:57] nt
	s_add_u32 s56, s56, 0x15800
	s_addc_u32 s57, s57, 0
	global_load_dwordx4 v[98:101], v138, s[56:57] nt
	s_add_u32 s56, s56, 0x51f800
	s_addc_u32 s57, s57, 0
	global_load_dwordx4 v[102:105], v138, s[56:57] nt
	s_add_u32 s56, s56, 0x15800
	s_addc_u32 s57, s57, 0
	global_load_dwordx4 v[106:109], v138, s[56:57] nt
	s_add_u32 s56, s56, 0x15800
	s_addc_u32 s57, s57, 0
	global_load_dwordx4 v[110:113], v138, s[56:57] nt
	s_add_u32 s56, s56, 0x15800
	s_addc_u32 s57, s57, 0
	global_load_dwordx4 v[114:117], v138, s[56:57] nt
	s_add_u32 s56, s56, 0x51f800
	s_addc_u32 s57, s57, 0
	global_load_dwordx4 v[118:121], v138, s[56:57] nt
	s_add_u32 s56, s56, 0x15800
	s_addc_u32 s57, s57, 0
	global_load_dwordx4 v[122:125], v138, s[56:57] nt
	s_add_u32 s56, s56, 0x15800
	s_addc_u32 s57, s57, 0
	global_load_dwordx4 v[126:129], v138, s[56:57] nt
	s_add_u32 s56, s56, 0x15800
	s_addc_u32 s57, s57, 0
	global_load_dwordx4 v[130:133], v138, s[56:57] nt
.Lc16_ffn1_loop:
	s_lshl_b32 s2, s0, 4
	s_cmp_ge_u32 s2, 0x2b00
	s_cselect_b32 s75, 128, 0
	s_cselect_b32 s3, 0x2b00, 0
	s_sub_u32 s3, s2, s3
	s_lshr_b32 s60, s3, 7
	s_lshl_b32 s60, s60, 8
	s_and_b32 s3, s3, 127
	s_add_u32 s60, s60, s3
	s_add_u32 s60, s60, s75
	s_lshl_b32 s63, s11, 9
	s_add_u32 s63, s63, 0x21000
	s_lshl_b32 s3, s1, 6
	s_add_u32 s3, s3, s63
	v_add_u32_e32 v172, s3, v230
	v_add_u32_e32 v173, s63, v230
	s_waitcnt vmcnt(0)
	v_max3_f32 v216, |v6|, |v10|, |v14|
	v_max3_f32 v216, v216, |v18|, |v22|
	v_max3_f32 v216, v216, |v26|, |v30|
	v_max3_f32 v216, v216, |v34|, |v38|
	v_max3_f32 v216, v216, |v42|, |v46|
	v_max3_f32 v216, v216, |v50|, |v54|
	v_max3_f32 v216, v216, |v58|, |v62|
	v_max3_f32 v216, v216, |v66|, |v70|
	v_max3_f32 v216, v216, |v74|, |v78|
	v_max3_f32 v216, v216, |v82|, |v86|
	v_max3_f32 v216, v216, |v90|, |v94|
	v_max3_f32 v216, v216, |v98|, |v102|
	v_max3_f32 v216, v216, |v106|, |v110|
	v_max3_f32 v216, v216, |v114|, |v118|
	v_max3_f32 v216, v216, |v122|, |v126|
	v_max_f32_e64 v216, v216, |v130|
	v_max3_f32 v217, |v7|, |v11|, |v15|
	v_max3_f32 v217, v217, |v19|, |v23|
	v_max3_f32 v217, v217, |v27|, |v31|
	v_max3_f32 v217, v217, |v35|, |v39|
	v_max3_f32 v217, v217, |v43|, |v47|
	v_max3_f32 v217, v217, |v51|, |v55|
	v_max3_f32 v217, v217, |v59|, |v63|
	v_max3_f32 v217, v217, |v67|, |v71|
	v_max3_f32 v217, v217, |v75|, |v79|
	v_max3_f32 v217, v217, |v83|, |v87|
	v_max3_f32 v217, v217, |v91|, |v95|
	v_max3_f32 v217, v217, |v99|, |v103|
	v_max3_f32 v217, v217, |v107|, |v111|
	v_max3_f32 v217, v217, |v115|, |v119|
	v_max3_f32 v217, v217, |v123|, |v127|
	v_max_f32_e64 v217, v217, |v131|
	v_max3_f32 v218, |v8|, |v12|, |v16|
	v_max3_f32 v218, v218, |v20|, |v24|
	v_max3_f32 v218, v218, |v28|, |v32|
	v_max3_f32 v218, v218, |v36|, |v40|
	v_max3_f32 v218, v218, |v44|, |v48|
	v_max3_f32 v218, v218, |v52|, |v56|
	v_max3_f32 v218, v218, |v60|, |v64|
	v_max3_f32 v218, v218, |v68|, |v72|
	v_max3_f32 v218, v218, |v76|, |v80|
	v_max3_f32 v218, v218, |v84|, |v88|
	v_max3_f32 v218, v218, |v92|, |v96|
	v_max3_f32 v218, v218, |v100|, |v104|
	v_max3_f32 v218, v218, |v108|, |v112|
	v_max3_f32 v218, v218, |v116|, |v120|
	v_max3_f32 v218, v218, |v124|, |v128|
	v_max_f32_e64 v218, v218, |v132|
	v_max3_f32 v219, |v9|, |v13|, |v17|
	v_max3_f32 v219, v219, |v21|, |v25|
	v_max3_f32 v219, v219, |v29|, |v33|
	v_max3_f32 v219, v219, |v37|, |v41|
	v_max3_f32 v219, v219, |v45|, |v49|
	v_max3_f32 v219, v219, |v53|, |v57|
	v_max3_f32 v219, v219, |v61|, |v65|
	v_max3_f32 v219, v219, |v69|, |v73|
	v_max3_f32 v219, v219, |v77|, |v81|
	v_max3_f32 v219, v219, |v85|, |v89|
	v_max3_f32 v219, v219, |v93|, |v97|
	v_max3_f32 v219, v219, |v101|, |v105|
	v_max3_f32 v219, v219, |v109|, |v113|
	v_max3_f32 v219, v219, |v117|, |v121|
	v_max3_f32 v219, v219, |v125|, |v129|
	v_max_f32_e64 v219, v219, |v133|
	ds_bpermute_b32 v174, v192, v216
	ds_bpermute_b32 v175, v192, v217
	ds_bpermute_b32 v176, v192, v218
	ds_bpermute_b32 v177, v192, v219
	s_waitcnt lgkmcnt(0)
	v_max_f32_e32 v216, v216, v174
	v_max_f32_e32 v217, v217, v175
	v_max_f32_e32 v218, v218, v176
	v_max_f32_e32 v219, v219, v177
	ds_bpermute_b32 v174, v193, v216
	ds_bpermute_b32 v175, v193, v217
	ds_bpermute_b32 v176, v193, v218
	ds_bpermute_b32 v177, v193, v219
	s_waitcnt lgkmcnt(0)
	v_max_f32_e32 v216, v216, v174
	v_max_f32_e32 v217, v217, v175
	v_max_f32_e32 v218, v218, v176
	v_max_f32_e32 v219, v219, v177
	ds_bpermute_b32 v174, v194, v216
	ds_bpermute_b32 v175, v194, v217
	ds_bpermute_b32 v176, v194, v218
	ds_bpermute_b32 v177, v194, v219
	s_waitcnt lgkmcnt(0)
	v_max_f32_e32 v216, v216, v174
	v_max_f32_e32 v217, v217, v175
	v_max_f32_e32 v218, v218, v176
	v_max_f32_e32 v219, v219, v177
	ds_bpermute_b32 v174, v195, v216
	ds_bpermute_b32 v175, v195, v217
	ds_bpermute_b32 v176, v195, v218
	ds_bpermute_b32 v177, v195, v219
	s_waitcnt lgkmcnt(0)
	v_max_f32_e32 v216, v216, v174
	v_max_f32_e32 v217, v217, v175
	v_max_f32_e32 v218, v218, v176
	v_max_f32_e32 v219, v219, v177
	s_mov_b64 s[70:71], exec
	s_mov_b64 exec, 15
	ds_write_b128 v172, v[216:219]
	s_mov_b64 exec, s[70:71]
	s_waitcnt lgkmcnt(0)
	s_barrier
	ds_read_b128 v[140:143], v173 offset:0
	ds_read_b128 v[144:147], v173 offset:64
	ds_read_b128 v[148:151], v173 offset:128
	ds_read_b128 v[152:155], v173 offset:192
	ds_read_b128 v[156:159], v173 offset:256
	ds_read_b128 v[160:163], v173 offset:320
	ds_read_b128 v[164:167], v173 offset:384
	ds_read_b128 v[232:235], v173 offset:448
	s_waitcnt lgkmcnt(0)
	v_max3_f32 v220, v140, v144, v148
	v_max3_f32 v220, v220, v152, v156
	v_max3_f32 v220, v220, v160, v164
	v_max_f32_e32 v220, v220, v232
	v_max3_f32 v221, v141, v145, v149
	v_max3_f32 v221, v221, v153, v157
	v_max3_f32 v221, v221, v161, v165
	v_max_f32_e32 v221, v221, v233
	v_max3_f32 v222, v142, v146, v150
	v_max3_f32 v222, v222, v154, v158
	v_max3_f32 v222, v222, v162, v166
	v_max_f32_e32 v222, v222, v234
	v_max3_f32 v223, v143, v147, v151
	v_max3_f32 v223, v223, v155, v159
	v_max3_f32 v223, v223, v163, v167
	v_max_f32_e32 v223, v223, v235
	s_cmp_lg_u32 s1, 0
	s_cbranch_scc1 .Lc16_ffn1_nocm
	s_lshl_b32 s3, s2, 2
	s_add_u32 s56, s34, s3
	s_addc_u32 s57, s35, 0
	s_add_u32 s56, s56, 0x40000
	s_addc_u32 s57, s57, 0
	s_mov_b64 s[70:71], exec
	s_mov_b64 exec, 15
	global_store_dwordx4 v230, v[220:223], s[56:57]
	s_mov_b64 exec, s[70:71]
.Lc16_ffn1_nocm:
	v_div_scale_f32 v175, s[70:71], v220, v220, s74
	v_rcp_f32_e32 v176, v175
	s_nop 0
	v_fma_f32 v177, -v175, v176, 1.0
	v_fmac_f32_e32 v176, v177, v176
	v_div_scale_f32 v177, vcc, s74, v220, s74
	v_mul_f32_e32 v178, v177, v176
	v_fma_f32 v180, -v175, v178, v177
	v_fmac_f32_e32 v178, v180, v176
	v_fma_f32 v175, -v175, v178, v177
	s_nop 0
	v_div_fmas_f32 v175, v175, v176, v178
	v_div_fixup_f32 v175, v175, v220, s74
	v_cmp_lt_f32_e32 vcc, 0, v220
	s_nop 1
	v_cndmask_b32_e32 v226, 0, v175, vcc
	v_div_scale_f32 v175, s[70:71], v221, v221, s74
	v_rcp_f32_e32 v176, v175
	s_nop 0
	v_fma_f32 v177, -v175, v176, 1.0
	v_fmac_f32_e32 v176, v177, v176
	v_div_scale_f32 v177, vcc, s74, v221, s74
	v_mul_f32_e32 v178, v177, v176
	v_fma_f32 v180, -v175, v178, v177
	v_fmac_f32_e32 v178, v180, v176
	v_fma_f32 v175, -v175, v178, v177
	s_nop 0
	v_div_fmas_f32 v175, v175, v176, v178
	v_div_fixup_f32 v175, v175, v221, s74
	v_cmp_lt_f32_e32 vcc, 0, v221
	s_nop 1
	v_cndmask_b32_e32 v227, 0, v175, vcc
	v_div_scale_f32 v175, s[70:71], v222, v222, s74
	v_rcp_f32_e32 v176, v175
	s_nop 0
	v_fma_f32 v177, -v175, v176, 1.0
	v_fmac_f32_e32 v176, v177, v176
	v_div_scale_f32 v177, vcc, s74, v222, s74
	v_mul_f32_e32 v178, v177, v176
	v_fma_f32 v180, -v175, v178, v177
	v_fmac_f32_e32 v178, v180, v176
	v_fma_f32 v175, -v175, v178, v177
	s_nop 0
	v_div_fmas_f32 v175, v175, v176, v178
	v_div_fixup_f32 v175, v175, v222, s74
	v_cmp_lt_f32_e32 vcc, 0, v222
	s_nop 1
	v_cndmask_b32_e32 v228, 0, v175, vcc
	v_div_scale_f32 v175, s[70:71], v223, v223, s74
	v_rcp_f32_e32 v176, v175
	s_nop 0
	v_fma_f32 v177, -v175, v176, 1.0
	v_fmac_f32_e32 v176, v177, v176
	v_div_scale_f32 v177, vcc, s74, v223, s74
	v_mul_f32_e32 v178, v177, v176
	v_fma_f32 v180, -v175, v178, v177
	v_fmac_f32_e32 v178, v180, v176
	v_fma_f32 v175, -v175, v178, v177
	s_nop 0
	v_div_fmas_f32 v175, v175, v176, v178
	v_div_fixup_f32 v175, v175, v223, s74
	v_cmp_lt_f32_e32 vcc, 0, v223
	s_nop 1
	v_cndmask_b32_e32 v229, 0, v175, vcc
	s_add_u32 s10, s0, s33
	s_lshl_b32 s3, s10, 6
	s_add_u32 s56, s48, s3
	s_addc_u32 s57, s49, 0
	v_mul_f32_e32 v186, v6, v226
	v_rndne_f32_e32 v186, v186
	v_cvt_i32_f32_e32 v186, v186
	v_mul_f32_e32 v187, v10, v226
	v_rndne_f32_e32 v187, v187
	v_cvt_i32_f32_e32 v187, v187
	v_mul_f32_e32 v188, v14, v226
	v_rndne_f32_e32 v188, v188
	v_cvt_i32_f32_e32 v188, v188
	v_mul_f32_e32 v189, v18, v226
	v_rndne_f32_e32 v189, v189
	v_cvt_i32_f32_e32 v189, v189
	v_and_b32_e32 v186, 0xff, v186
	v_and_b32_e32 v187, 0xff, v187
	v_and_b32_e32 v188, 0xff, v188
	v_lshl_or_b32 v190, v187, 8, v186
	v_lshl_or_b32 v190, v188, 16, v190
	v_lshl_or_b32 v190, v189, 24, v190
	ds_write_b32 v139, v190 offset:0
	v_mul_f32_e32 v186, v7, v227
	v_rndne_f32_e32 v186, v186
	v_cvt_i32_f32_e32 v186, v186
	v_mul_f32_e32 v187, v11, v227
	v_rndne_f32_e32 v187, v187
	v_cvt_i32_f32_e32 v187, v187
	v_mul_f32_e32 v188, v15, v227
	v_rndne_f32_e32 v188, v188
	v_cvt_i32_f32_e32 v188, v188
	v_mul_f32_e32 v189, v19, v227
	v_rndne_f32_e32 v189, v189
	v_cvt_i32_f32_e32 v189, v189
	v_and_b32_e32 v186, 0xff, v186
	v_and_b32_e32 v187, 0xff, v187
	v_and_b32_e32 v188, 0xff, v188
	v_lshl_or_b32 v190, v187, 8, v186
	v_lshl_or_b32 v190, v188, 16, v190
	v_lshl_or_b32 v190, v189, 24, v190
	ds_write_b32 v139, v190 offset:512
	v_mul_f32_e32 v186, v8, v228
	v_rndne_f32_e32 v186, v186
	v_cvt_i32_f32_e32 v186, v186
	v_mul_f32_e32 v187, v12, v228
	v_rndne_f32_e32 v187, v187
	v_cvt_i32_f32_e32 v187, v187
	v_mul_f32_e32 v188, v16, v228
	v_rndne_f32_e32 v188, v188
	v_cvt_i32_f32_e32 v188, v188
	v_mul_f32_e32 v189, v20, v228
	v_rndne_f32_e32 v189, v189
	v_cvt_i32_f32_e32 v189, v189
	v_and_b32_e32 v186, 0xff, v186
	v_and_b32_e32 v187, 0xff, v187
	v_and_b32_e32 v188, 0xff, v188
	v_lshl_or_b32 v190, v187, 8, v186
	v_lshl_or_b32 v190, v188, 16, v190
	v_lshl_or_b32 v190, v189, 24, v190
	ds_write_b32 v139, v190 offset:1024
	v_mul_f32_e32 v186, v9, v229
	v_rndne_f32_e32 v186, v186
	v_cvt_i32_f32_e32 v186, v186
	v_mul_f32_e32 v187, v13, v229
	v_rndne_f32_e32 v187, v187
	v_cvt_i32_f32_e32 v187, v187
	v_mul_f32_e32 v188, v17, v229
	v_rndne_f32_e32 v188, v188
	v_cvt_i32_f32_e32 v188, v188
	v_mul_f32_e32 v189, v21, v229
	v_rndne_f32_e32 v189, v189
	v_cvt_i32_f32_e32 v189, v189
	v_and_b32_e32 v186, 0xff, v186
	v_and_b32_e32 v187, 0xff, v187
	v_and_b32_e32 v188, 0xff, v188
	v_lshl_or_b32 v190, v187, 8, v186
	v_lshl_or_b32 v190, v188, 16, v190
	v_lshl_or_b32 v190, v189, 24, v190
	ds_write_b32 v139, v190 offset:1536
	s_cmp_ge_u32 s10, 0x560
	s_cbranch_scc1 .Lc16_ffn1_nopf_0
	global_load_dwordx4 v[6:9], v138, s[56:57] nt
	s_add_u32 s56, s56, 0x15800
	s_addc_u32 s57, s57, 0
	global_load_dwordx4 v[10:13], v138, s[56:57] nt
	s_add_u32 s56, s56, 0x15800
	s_addc_u32 s57, s57, 0
	global_load_dwordx4 v[14:17], v138, s[56:57] nt
	s_add_u32 s56, s56, 0x15800
	s_addc_u32 s57, s57, 0
	global_load_dwordx4 v[18:21], v138, s[56:57] nt
	s_add_u32 s56, s56, 0x51f800
	s_addc_u32 s57, s57, 0
.Lc16_ffn1_nopf_0:
	v_mul_f32_e32 v186, v22, v226
	v_rndne_f32_e32 v186, v186
	v_cvt_i32_f32_e32 v186, v186
	v_mul_f32_e32 v187, v26, v226
	v_rndne_f32_e32 v187, v187
	v_cvt_i32_f32_e32 v187, v187
	v_mul_f32_e32 v188, v30, v226
	v_rndne_f32_e32 v188, v188
	v_cvt_i32_f32_e32 v188, v188
	v_mul_f32_e32 v189, v34, v226
	v_rndne_f32_e32 v189, v189
	v_cvt_i32_f32_e32 v189, v189
	v_and_b32_e32 v186, 0xff, v186
	v_and_b32_e32 v187, 0xff, v187
	v_and_b32_e32 v188, 0xff, v188
	v_lshl_or_b32 v190, v187, 8, v186
	v_lshl_or_b32 v190, v188, 16, v190
	v_lshl_or_b32 v190, v189, 24, v190
	ds_write_b32 v139, v190 offset:64
	v_mul_f32_e32 v186, v23, v227
	v_rndne_f32_e32 v186, v186
	v_cvt_i32_f32_e32 v186, v186
	v_mul_f32_e32 v187, v27, v227
	v_rndne_f32_e32 v187, v187
	v_cvt_i32_f32_e32 v187, v187
	v_mul_f32_e32 v188, v31, v227
	v_rndne_f32_e32 v188, v188
	v_cvt_i32_f32_e32 v188, v188
	v_mul_f32_e32 v189, v35, v227
	v_rndne_f32_e32 v189, v189
	v_cvt_i32_f32_e32 v189, v189
	v_and_b32_e32 v186, 0xff, v186
	v_and_b32_e32 v187, 0xff, v187
	v_and_b32_e32 v188, 0xff, v188
	v_lshl_or_b32 v190, v187, 8, v186
	v_lshl_or_b32 v190, v188, 16, v190
	v_lshl_or_b32 v190, v189, 24, v190
	ds_write_b32 v139, v190 offset:576
	v_mul_f32_e32 v186, v24, v228
	v_rndne_f32_e32 v186, v186
	v_cvt_i32_f32_e32 v186, v186
	v_mul_f32_e32 v187, v28, v228
	v_rndne_f32_e32 v187, v187
	v_cvt_i32_f32_e32 v187, v187
	v_mul_f32_e32 v188, v32, v228
	v_rndne_f32_e32 v188, v188
	v_cvt_i32_f32_e32 v188, v188
	v_mul_f32_e32 v189, v36, v228
	v_rndne_f32_e32 v189, v189
	v_cvt_i32_f32_e32 v189, v189
	v_and_b32_e32 v186, 0xff, v186
	v_and_b32_e32 v187, 0xff, v187
	v_and_b32_e32 v188, 0xff, v188
	v_lshl_or_b32 v190, v187, 8, v186
	v_lshl_or_b32 v190, v188, 16, v190
	v_lshl_or_b32 v190, v189, 24, v190
	ds_write_b32 v139, v190 offset:1088
	v_mul_f32_e32 v186, v25, v229
	v_rndne_f32_e32 v186, v186
	v_cvt_i32_f32_e32 v186, v186
	v_mul_f32_e32 v187, v29, v229
	v_rndne_f32_e32 v187, v187
	v_cvt_i32_f32_e32 v187, v187
	v_mul_f32_e32 v188, v33, v229
	v_rndne_f32_e32 v188, v188
	v_cvt_i32_f32_e32 v188, v188
	v_mul_f32_e32 v189, v37, v229
	v_rndne_f32_e32 v189, v189
	v_cvt_i32_f32_e32 v189, v189
	v_and_b32_e32 v186, 0xff, v186
	v_and_b32_e32 v187, 0xff, v187
	v_and_b32_e32 v188, 0xff, v188
	v_lshl_or_b32 v190, v187, 8, v186
	v_lshl_or_b32 v190, v188, 16, v190
	v_lshl_or_b32 v190, v189, 24, v190
	ds_write_b32 v139, v190 offset:1600
	s_cmp_ge_u32 s10, 0x560
	s_cbranch_scc1 .Lc16_ffn1_nopf_1
	global_load_dwordx4 v[22:25], v138, s[56:57] nt
	s_add_u32 s56, s56, 0x15800
	s_addc_u32 s57, s57, 0
	global_load_dwordx4 v[26:29], v138, s[56:57] nt
	s_add_u32 s56, s56, 0x15800
	s_addc_u32 s57, s57, 0
	global_load_dwordx4 v[30:33], v138, s[56:57] nt
	s_add_u32 s56, s56, 0x15800
	s_addc_u32 s57, s57, 0
	global_load_dwordx4 v[34:37], v138, s[56:57] nt
	s_add_u32 s56, s56, 0x51f800
	s_addc_u32 s57, s57, 0
.Lc16_ffn1_nopf_1:
	v_mul_f32_e32 v186, v38, v226
	v_rndne_f32_e32 v186, v186
	v_cvt_i32_f32_e32 v186, v186
	v_mul_f32_e32 v187, v42, v226
	v_rndne_f32_e32 v187, v187
	v_cvt_i32_f32_e32 v187, v187
	v_mul_f32_e32 v188, v46, v226
	v_rndne_f32_e32 v188, v188
	v_cvt_i32_f32_e32 v188, v188
	v_mul_f32_e32 v189, v50, v226
	v_rndne_f32_e32 v189, v189
	v_cvt_i32_f32_e32 v189, v189
	v_and_b32_e32 v186, 0xff, v186
	v_and_b32_e32 v187, 0xff, v187
	v_and_b32_e32 v188, 0xff, v188
	v_lshl_or_b32 v190, v187, 8, v186
	v_lshl_or_b32 v190, v188, 16, v190
	v_lshl_or_b32 v190, v189, 24, v190
	ds_write_b32 v139, v190 offset:128
	v_mul_f32_e32 v186, v39, v227
	v_rndne_f32_e32 v186, v186
	v_cvt_i32_f32_e32 v186, v186
	v_mul_f32_e32 v187, v43, v227
	v_rndne_f32_e32 v187, v187
	v_cvt_i32_f32_e32 v187, v187
	v_mul_f32_e32 v188, v47, v227
	v_rndne_f32_e32 v188, v188
	v_cvt_i32_f32_e32 v188, v188
	v_mul_f32_e32 v189, v51, v227
	v_rndne_f32_e32 v189, v189
	v_cvt_i32_f32_e32 v189, v189
	v_and_b32_e32 v186, 0xff, v186
	v_and_b32_e32 v187, 0xff, v187
	v_and_b32_e32 v188, 0xff, v188
	v_lshl_or_b32 v190, v187, 8, v186
	v_lshl_or_b32 v190, v188, 16, v190
	v_lshl_or_b32 v190, v189, 24, v190
	ds_write_b32 v139, v190 offset:640
	v_mul_f32_e32 v186, v40, v228
	v_rndne_f32_e32 v186, v186
	v_cvt_i32_f32_e32 v186, v186
	v_mul_f32_e32 v187, v44, v228
	v_rndne_f32_e32 v187, v187
	v_cvt_i32_f32_e32 v187, v187
	v_mul_f32_e32 v188, v48, v228
	v_rndne_f32_e32 v188, v188
	v_cvt_i32_f32_e32 v188, v188
	v_mul_f32_e32 v189, v52, v228
	v_rndne_f32_e32 v189, v189
	v_cvt_i32_f32_e32 v189, v189
	v_and_b32_e32 v186, 0xff, v186
	v_and_b32_e32 v187, 0xff, v187
	v_and_b32_e32 v188, 0xff, v188
	v_lshl_or_b32 v190, v187, 8, v186
	v_lshl_or_b32 v190, v188, 16, v190
	v_lshl_or_b32 v190, v189, 24, v190
	ds_write_b32 v139, v190 offset:1152
	v_mul_f32_e32 v186, v41, v229
	v_rndne_f32_e32 v186, v186
	v_cvt_i32_f32_e32 v186, v186
	v_mul_f32_e32 v187, v45, v229
	v_rndne_f32_e32 v187, v187
	v_cvt_i32_f32_e32 v187, v187
	v_mul_f32_e32 v188, v49, v229
	v_rndne_f32_e32 v188, v188
	v_cvt_i32_f32_e32 v188, v188
	v_mul_f32_e32 v189, v53, v229
	v_rndne_f32_e32 v189, v189
	v_cvt_i32_f32_e32 v189, v189
	v_and_b32_e32 v186, 0xff, v186
	v_and_b32_e32 v187, 0xff, v187
	v_and_b32_e32 v188, 0xff, v188
	v_lshl_or_b32 v190, v187, 8, v186
	v_lshl_or_b32 v190, v188, 16, v190
	v_lshl_or_b32 v190, v189, 24, v190
	ds_write_b32 v139, v190 offset:1664
	s_cmp_ge_u32 s10, 0x560
	s_cbranch_scc1 .Lc16_ffn1_nopf_2
	global_load_dwordx4 v[38:41], v138, s[56:57] nt
	s_add_u32 s56, s56, 0x15800
	s_addc_u32 s57, s57, 0
	global_load_dwordx4 v[42:45], v138, s[56:57] nt
	s_add_u32 s56, s56, 0x15800
	s_addc_u32 s57, s57, 0
	global_load_dwordx4 v[46:49], v138, s[56:57] nt
	s_add_u32 s56, s56, 0x15800
	s_addc_u32 s57, s57, 0
	global_load_dwordx4 v[50:53], v138, s[56:57] nt
	s_add_u32 s56, s56, 0x51f800
	s_addc_u32 s57, s57, 0
.Lc16_ffn1_nopf_2:
	v_mul_f32_e32 v186, v54, v226
	v_rndne_f32_e32 v186, v186
	v_cvt_i32_f32_e32 v186, v186
	v_mul_f32_e32 v187, v58, v226
	v_rndne_f32_e32 v187, v187
	v_cvt_i32_f32_e32 v187, v187
	v_mul_f32_e32 v188, v62, v226
	v_rndne_f32_e32 v188, v188
	v_cvt_i32_f32_e32 v188, v188
	v_mul_f32_e32 v189, v66, v226
	v_rndne_f32_e32 v189, v189
	v_cvt_i32_f32_e32 v189, v189
	v_and_b32_e32 v186, 0xff, v186
	v_and_b32_e32 v187, 0xff, v187
	v_and_b32_e32 v188, 0xff, v188
	v_lshl_or_b32 v190, v187, 8, v186
	v_lshl_or_b32 v190, v188, 16, v190
	v_lshl_or_b32 v190, v189, 24, v190
	ds_write_b32 v139, v190 offset:192
	v_mul_f32_e32 v186, v55, v227
	v_rndne_f32_e32 v186, v186
	v_cvt_i32_f32_e32 v186, v186
	v_mul_f32_e32 v187, v59, v227
	v_rndne_f32_e32 v187, v187
	v_cvt_i32_f32_e32 v187, v187
	v_mul_f32_e32 v188, v63, v227
	v_rndne_f32_e32 v188, v188
	v_cvt_i32_f32_e32 v188, v188
	v_mul_f32_e32 v189, v67, v227
	v_rndne_f32_e32 v189, v189
	v_cvt_i32_f32_e32 v189, v189
	v_and_b32_e32 v186, 0xff, v186
	v_and_b32_e32 v187, 0xff, v187
	v_and_b32_e32 v188, 0xff, v188
	v_lshl_or_b32 v190, v187, 8, v186
	v_lshl_or_b32 v190, v188, 16, v190
	v_lshl_or_b32 v190, v189, 24, v190
	ds_write_b32 v139, v190 offset:704
	v_mul_f32_e32 v186, v56, v228
	v_rndne_f32_e32 v186, v186
	v_cvt_i32_f32_e32 v186, v186
	v_mul_f32_e32 v187, v60, v228
	v_rndne_f32_e32 v187, v187
	v_cvt_i32_f32_e32 v187, v187
	v_mul_f32_e32 v188, v64, v228
	v_rndne_f32_e32 v188, v188
	v_cvt_i32_f32_e32 v188, v188
	v_mul_f32_e32 v189, v68, v228
	v_rndne_f32_e32 v189, v189
	v_cvt_i32_f32_e32 v189, v189
	v_and_b32_e32 v186, 0xff, v186
	v_and_b32_e32 v187, 0xff, v187
	v_and_b32_e32 v188, 0xff, v188
	v_lshl_or_b32 v190, v187, 8, v186
	v_lshl_or_b32 v190, v188, 16, v190
	v_lshl_or_b32 v190, v189, 24, v190
	ds_write_b32 v139, v190 offset:1216
	v_mul_f32_e32 v186, v57, v229
	v_rndne_f32_e32 v186, v186
	v_cvt_i32_f32_e32 v186, v186
	v_mul_f32_e32 v187, v61, v229
	v_rndne_f32_e32 v187, v187
	v_cvt_i32_f32_e32 v187, v187
	v_mul_f32_e32 v188, v65, v229
	v_rndne_f32_e32 v188, v188
	v_cvt_i32_f32_e32 v188, v188
	v_mul_f32_e32 v189, v69, v229
	v_rndne_f32_e32 v189, v189
	v_cvt_i32_f32_e32 v189, v189
	v_and_b32_e32 v186, 0xff, v186
	v_and_b32_e32 v187, 0xff, v187
	v_and_b32_e32 v188, 0xff, v188
	v_lshl_or_b32 v190, v187, 8, v186
	v_lshl_or_b32 v190, v188, 16, v190
	v_lshl_or_b32 v190, v189, 24, v190
	ds_write_b32 v139, v190 offset:1728
	s_cmp_ge_u32 s10, 0x560
	s_cbranch_scc1 .Lc16_ffn1_nopf_3
	global_load_dwordx4 v[54:57], v138, s[56:57] nt
	s_add_u32 s56, s56, 0x15800
	s_addc_u32 s57, s57, 0
	global_load_dwordx4 v[58:61], v138, s[56:57] nt
	s_add_u32 s56, s56, 0x15800
	s_addc_u32 s57, s57, 0
	global_load_dwordx4 v[62:65], v138, s[56:57] nt
	s_add_u32 s56, s56, 0x15800
	s_addc_u32 s57, s57, 0
	global_load_dwordx4 v[66:69], v138, s[56:57] nt
	s_add_u32 s56, s56, 0x51f800
	s_addc_u32 s57, s57, 0
.Lc16_ffn1_nopf_3:
	v_mul_f32_e32 v186, v70, v226
	v_rndne_f32_e32 v186, v186
	v_cvt_i32_f32_e32 v186, v186
	v_mul_f32_e32 v187, v74, v226
	v_rndne_f32_e32 v187, v187
	v_cvt_i32_f32_e32 v187, v187
	v_mul_f32_e32 v188, v78, v226
	v_rndne_f32_e32 v188, v188
	v_cvt_i32_f32_e32 v188, v188
	v_mul_f32_e32 v189, v82, v226
	v_rndne_f32_e32 v189, v189
	v_cvt_i32_f32_e32 v189, v189
	v_and_b32_e32 v186, 0xff, v186
	v_and_b32_e32 v187, 0xff, v187
	v_and_b32_e32 v188, 0xff, v188
	v_lshl_or_b32 v190, v187, 8, v186
	v_lshl_or_b32 v190, v188, 16, v190
	v_lshl_or_b32 v190, v189, 24, v190
	ds_write_b32 v139, v190 offset:256
	v_mul_f32_e32 v186, v71, v227
	v_rndne_f32_e32 v186, v186
	v_cvt_i32_f32_e32 v186, v186
	v_mul_f32_e32 v187, v75, v227
	v_rndne_f32_e32 v187, v187
	v_cvt_i32_f32_e32 v187, v187
	v_mul_f32_e32 v188, v79, v227
	v_rndne_f32_e32 v188, v188
	v_cvt_i32_f32_e32 v188, v188
	v_mul_f32_e32 v189, v83, v227
	v_rndne_f32_e32 v189, v189
	v_cvt_i32_f32_e32 v189, v189
	v_and_b32_e32 v186, 0xff, v186
	v_and_b32_e32 v187, 0xff, v187
	v_and_b32_e32 v188, 0xff, v188
	v_lshl_or_b32 v190, v187, 8, v186
	v_lshl_or_b32 v190, v188, 16, v190
	v_lshl_or_b32 v190, v189, 24, v190
	ds_write_b32 v139, v190 offset:768
	v_mul_f32_e32 v186, v72, v228
	v_rndne_f32_e32 v186, v186
	v_cvt_i32_f32_e32 v186, v186
	v_mul_f32_e32 v187, v76, v228
	v_rndne_f32_e32 v187, v187
	v_cvt_i32_f32_e32 v187, v187
	v_mul_f32_e32 v188, v80, v228
	v_rndne_f32_e32 v188, v188
	v_cvt_i32_f32_e32 v188, v188
	v_mul_f32_e32 v189, v84, v228
	v_rndne_f32_e32 v189, v189
	v_cvt_i32_f32_e32 v189, v189
	v_and_b32_e32 v186, 0xff, v186
	v_and_b32_e32 v187, 0xff, v187
	v_and_b32_e32 v188, 0xff, v188
	v_lshl_or_b32 v190, v187, 8, v186
	v_lshl_or_b32 v190, v188, 16, v190
	v_lshl_or_b32 v190, v189, 24, v190
	ds_write_b32 v139, v190 offset:1280
	v_mul_f32_e32 v186, v73, v229
	v_rndne_f32_e32 v186, v186
	v_cvt_i32_f32_e32 v186, v186
	v_mul_f32_e32 v187, v77, v229
	v_rndne_f32_e32 v187, v187
	v_cvt_i32_f32_e32 v187, v187
	v_mul_f32_e32 v188, v81, v229
	v_rndne_f32_e32 v188, v188
	v_cvt_i32_f32_e32 v188, v188
	v_mul_f32_e32 v189, v85, v229
	v_rndne_f32_e32 v189, v189
	v_cvt_i32_f32_e32 v189, v189
	v_and_b32_e32 v186, 0xff, v186
	v_and_b32_e32 v187, 0xff, v187
	v_and_b32_e32 v188, 0xff, v188
	v_lshl_or_b32 v190, v187, 8, v186
	v_lshl_or_b32 v190, v188, 16, v190
	v_lshl_or_b32 v190, v189, 24, v190
	ds_write_b32 v139, v190 offset:1792
	s_cmp_ge_u32 s10, 0x560
	s_cbranch_scc1 .Lc16_ffn1_nopf_4
	global_load_dwordx4 v[70:73], v138, s[56:57] nt
	s_add_u32 s56, s56, 0x15800
	s_addc_u32 s57, s57, 0
	global_load_dwordx4 v[74:77], v138, s[56:57] nt
	s_add_u32 s56, s56, 0x15800
	s_addc_u32 s57, s57, 0
	global_load_dwordx4 v[78:81], v138, s[56:57] nt
	s_add_u32 s56, s56, 0x15800
	s_addc_u32 s57, s57, 0
	global_load_dwordx4 v[82:85], v138, s[56:57] nt
	s_add_u32 s56, s56, 0x51f800
	s_addc_u32 s57, s57, 0
.Lc16_ffn1_nopf_4:
	v_mul_f32_e32 v186, v86, v226
	v_rndne_f32_e32 v186, v186
	v_cvt_i32_f32_e32 v186, v186
	v_mul_f32_e32 v187, v90, v226
	v_rndne_f32_e32 v187, v187
	v_cvt_i32_f32_e32 v187, v187
	v_mul_f32_e32 v188, v94, v226
	v_rndne_f32_e32 v188, v188
	v_cvt_i32_f32_e32 v188, v188
	v_mul_f32_e32 v189, v98, v226
	v_rndne_f32_e32 v189, v189
	v_cvt_i32_f32_e32 v189, v189
	v_and_b32_e32 v186, 0xff, v186
	v_and_b32_e32 v187, 0xff, v187
	v_and_b32_e32 v188, 0xff, v188
	v_lshl_or_b32 v190, v187, 8, v186
	v_lshl_or_b32 v190, v188, 16, v190
	v_lshl_or_b32 v190, v189, 24, v190
	ds_write_b32 v139, v190 offset:320
	v_mul_f32_e32 v186, v87, v227
	v_rndne_f32_e32 v186, v186
	v_cvt_i32_f32_e32 v186, v186
	v_mul_f32_e32 v187, v91, v227
	v_rndne_f32_e32 v187, v187
	v_cvt_i32_f32_e32 v187, v187
	v_mul_f32_e32 v188, v95, v227
	v_rndne_f32_e32 v188, v188
	v_cvt_i32_f32_e32 v188, v188
	v_mul_f32_e32 v189, v99, v227
	v_rndne_f32_e32 v189, v189
	v_cvt_i32_f32_e32 v189, v189
	v_and_b32_e32 v186, 0xff, v186
	v_and_b32_e32 v187, 0xff, v187
	v_and_b32_e32 v188, 0xff, v188
	v_lshl_or_b32 v190, v187, 8, v186
	v_lshl_or_b32 v190, v188, 16, v190
	v_lshl_or_b32 v190, v189, 24, v190
	ds_write_b32 v139, v190 offset:832
	v_mul_f32_e32 v186, v88, v228
	v_rndne_f32_e32 v186, v186
	v_cvt_i32_f32_e32 v186, v186
	v_mul_f32_e32 v187, v92, v228
	v_rndne_f32_e32 v187, v187
	v_cvt_i32_f32_e32 v187, v187
	v_mul_f32_e32 v188, v96, v228
	v_rndne_f32_e32 v188, v188
	v_cvt_i32_f32_e32 v188, v188
	v_mul_f32_e32 v189, v100, v228
	v_rndne_f32_e32 v189, v189
	v_cvt_i32_f32_e32 v189, v189
	v_and_b32_e32 v186, 0xff, v186
	v_and_b32_e32 v187, 0xff, v187
	v_and_b32_e32 v188, 0xff, v188
	v_lshl_or_b32 v190, v187, 8, v186
	v_lshl_or_b32 v190, v188, 16, v190
	v_lshl_or_b32 v190, v189, 24, v190
	ds_write_b32 v139, v190 offset:1344
	v_mul_f32_e32 v186, v89, v229
	v_rndne_f32_e32 v186, v186
	v_cvt_i32_f32_e32 v186, v186
	v_mul_f32_e32 v187, v93, v229
	v_rndne_f32_e32 v187, v187
	v_cvt_i32_f32_e32 v187, v187
	v_mul_f32_e32 v188, v97, v229
	v_rndne_f32_e32 v188, v188
	v_cvt_i32_f32_e32 v188, v188
	v_mul_f32_e32 v189, v101, v229
	v_rndne_f32_e32 v189, v189
	v_cvt_i32_f32_e32 v189, v189
	v_and_b32_e32 v186, 0xff, v186
	v_and_b32_e32 v187, 0xff, v187
	v_and_b32_e32 v188, 0xff, v188
	v_lshl_or_b32 v190, v187, 8, v186
	v_lshl_or_b32 v190, v188, 16, v190
	v_lshl_or_b32 v190, v189, 24, v190
	ds_write_b32 v139, v190 offset:1856
	s_cmp_ge_u32 s10, 0x560
	s_cbranch_scc1 .Lc16_ffn1_nopf_5
	global_load_dwordx4 v[86:89], v138, s[56:57] nt
	s_add_u32 s56, s56, 0x15800
	s_addc_u32 s57, s57, 0
	global_load_dwordx4 v[90:93], v138, s[56:57] nt
	s_add_u32 s56, s56, 0x15800
	s_addc_u32 s57, s57, 0
	global_load_dwordx4 v[94:97], v138, s[56:57] nt
	s_add_u32 s56, s56, 0x15800
	s_addc_u32 s57, s57, 0
	global_load_dwordx4 v[98:101], v138, s[56:57] nt
	s_add_u32 s56, s56, 0x51f800
	s_addc_u32 s57, s57, 0
.Lc16_ffn1_nopf_5:
	v_mul_f32_e32 v186, v102, v226
	v_rndne_f32_e32 v186, v186
	v_cvt_i32_f32_e32 v186, v186
	v_mul_f32_e32 v187, v106, v226
	v_rndne_f32_e32 v187, v187
	v_cvt_i32_f32_e32 v187, v187
	v_mul_f32_e32 v188, v110, v226
	v_rndne_f32_e32 v188, v188
	v_cvt_i32_f32_e32 v188, v188
	v_mul_f32_e32 v189, v114, v226
	v_rndne_f32_e32 v189, v189
	v_cvt_i32_f32_e32 v189, v189
	v_and_b32_e32 v186, 0xff, v186
	v_and_b32_e32 v187, 0xff, v187
	v_and_b32_e32 v188, 0xff, v188
	v_lshl_or_b32 v190, v187, 8, v186
	v_lshl_or_b32 v190, v188, 16, v190
	v_lshl_or_b32 v190, v189, 24, v190
	ds_write_b32 v139, v190 offset:384
	v_mul_f32_e32 v186, v103, v227
	v_rndne_f32_e32 v186, v186
	v_cvt_i32_f32_e32 v186, v186
	v_mul_f32_e32 v187, v107, v227
	v_rndne_f32_e32 v187, v187
	v_cvt_i32_f32_e32 v187, v187
	v_mul_f32_e32 v188, v111, v227
	v_rndne_f32_e32 v188, v188
	v_cvt_i32_f32_e32 v188, v188
	v_mul_f32_e32 v189, v115, v227
	v_rndne_f32_e32 v189, v189
	v_cvt_i32_f32_e32 v189, v189
	v_and_b32_e32 v186, 0xff, v186
	v_and_b32_e32 v187, 0xff, v187
	v_and_b32_e32 v188, 0xff, v188
	v_lshl_or_b32 v190, v187, 8, v186
	v_lshl_or_b32 v190, v188, 16, v190
	v_lshl_or_b32 v190, v189, 24, v190
	ds_write_b32 v139, v190 offset:896
	v_mul_f32_e32 v186, v104, v228
	v_rndne_f32_e32 v186, v186
	v_cvt_i32_f32_e32 v186, v186
	v_mul_f32_e32 v187, v108, v228
	v_rndne_f32_e32 v187, v187
	v_cvt_i32_f32_e32 v187, v187
	v_mul_f32_e32 v188, v112, v228
	v_rndne_f32_e32 v188, v188
	v_cvt_i32_f32_e32 v188, v188
	v_mul_f32_e32 v189, v116, v228
	v_rndne_f32_e32 v189, v189
	v_cvt_i32_f32_e32 v189, v189
	v_and_b32_e32 v186, 0xff, v186
	v_and_b32_e32 v187, 0xff, v187
	v_and_b32_e32 v188, 0xff, v188
	v_lshl_or_b32 v190, v187, 8, v186
	v_lshl_or_b32 v190, v188, 16, v190
	v_lshl_or_b32 v190, v189, 24, v190
	ds_write_b32 v139, v190 offset:1408
	v_mul_f32_e32 v186, v105, v229
	v_rndne_f32_e32 v186, v186
	v_cvt_i32_f32_e32 v186, v186
	v_mul_f32_e32 v187, v109, v229
	v_rndne_f32_e32 v187, v187
	v_cvt_i32_f32_e32 v187, v187
	v_mul_f32_e32 v188, v113, v229
	v_rndne_f32_e32 v188, v188
	v_cvt_i32_f32_e32 v188, v188
	v_mul_f32_e32 v189, v117, v229
	v_rndne_f32_e32 v189, v189
	v_cvt_i32_f32_e32 v189, v189
	v_and_b32_e32 v186, 0xff, v186
	v_and_b32_e32 v187, 0xff, v187
	v_and_b32_e32 v188, 0xff, v188
	v_lshl_or_b32 v190, v187, 8, v186
	v_lshl_or_b32 v190, v188, 16, v190
	v_lshl_or_b32 v190, v189, 24, v190
	ds_write_b32 v139, v190 offset:1920
	s_cmp_ge_u32 s10, 0x560
	s_cbranch_scc1 .Lc16_ffn1_nopf_6
	global_load_dwordx4 v[102:105], v138, s[56:57] nt
	s_add_u32 s56, s56, 0x15800
	s_addc_u32 s57, s57, 0
	global_load_dwordx4 v[106:109], v138, s[56:57] nt
	s_add_u32 s56, s56, 0x15800
	s_addc_u32 s57, s57, 0
	global_load_dwordx4 v[110:113], v138, s[56:57] nt
	s_add_u32 s56, s56, 0x15800
	s_addc_u32 s57, s57, 0
	global_load_dwordx4 v[114:117], v138, s[56:57] nt
	s_add_u32 s56, s56, 0x51f800
	s_addc_u32 s57, s57, 0
.Lc16_ffn1_nopf_6:
	v_mul_f32_e32 v186, v118, v226
	v_rndne_f32_e32 v186, v186
	v_cvt_i32_f32_e32 v186, v186
	v_mul_f32_e32 v187, v122, v226
	v_rndne_f32_e32 v187, v187
	v_cvt_i32_f32_e32 v187, v187
	v_mul_f32_e32 v188, v126, v226
	v_rndne_f32_e32 v188, v188
	v_cvt_i32_f32_e32 v188, v188
	v_mul_f32_e32 v189, v130, v226
	v_rndne_f32_e32 v189, v189
	v_cvt_i32_f32_e32 v189, v189
	v_and_b32_e32 v186, 0xff, v186
	v_and_b32_e32 v187, 0xff, v187
	v_and_b32_e32 v188, 0xff, v188
	v_lshl_or_b32 v190, v187, 8, v186
	v_lshl_or_b32 v190, v188, 16, v190
	v_lshl_or_b32 v190, v189, 24, v190
	ds_write_b32 v139, v190 offset:448
	v_mul_f32_e32 v186, v119, v227
	v_rndne_f32_e32 v186, v186
	v_cvt_i32_f32_e32 v186, v186
	v_mul_f32_e32 v187, v123, v227
	v_rndne_f32_e32 v187, v187
	v_cvt_i32_f32_e32 v187, v187
	v_mul_f32_e32 v188, v127, v227
	v_rndne_f32_e32 v188, v188
	v_cvt_i32_f32_e32 v188, v188
	v_mul_f32_e32 v189, v131, v227
	v_rndne_f32_e32 v189, v189
	v_cvt_i32_f32_e32 v189, v189
	v_and_b32_e32 v186, 0xff, v186
	v_and_b32_e32 v187, 0xff, v187
	v_and_b32_e32 v188, 0xff, v188
	v_lshl_or_b32 v190, v187, 8, v186
	v_lshl_or_b32 v190, v188, 16, v190
	v_lshl_or_b32 v190, v189, 24, v190
	ds_write_b32 v139, v190 offset:960
	v_mul_f32_e32 v186, v120, v228
	v_rndne_f32_e32 v186, v186
	v_cvt_i32_f32_e32 v186, v186
	v_mul_f32_e32 v187, v124, v228
	v_rndne_f32_e32 v187, v187
	v_cvt_i32_f32_e32 v187, v187
	v_mul_f32_e32 v188, v128, v228
	v_rndne_f32_e32 v188, v188
	v_cvt_i32_f32_e32 v188, v188
	v_mul_f32_e32 v189, v132, v228
	v_rndne_f32_e32 v189, v189
	v_cvt_i32_f32_e32 v189, v189
	v_and_b32_e32 v186, 0xff, v186
	v_and_b32_e32 v187, 0xff, v187
	v_and_b32_e32 v188, 0xff, v188
	v_lshl_or_b32 v190, v187, 8, v186
	v_lshl_or_b32 v190, v188, 16, v190
	v_lshl_or_b32 v190, v189, 24, v190
	ds_write_b32 v139, v190 offset:1472
	v_mul_f32_e32 v186, v121, v229
	v_rndne_f32_e32 v186, v186
	v_cvt_i32_f32_e32 v186, v186
	v_mul_f32_e32 v187, v125, v229
	v_rndne_f32_e32 v187, v187
	v_cvt_i32_f32_e32 v187, v187
	v_mul_f32_e32 v188, v129, v229
	v_rndne_f32_e32 v188, v188
	v_cvt_i32_f32_e32 v188, v188
	v_mul_f32_e32 v189, v133, v229
	v_rndne_f32_e32 v189, v189
	v_cvt_i32_f32_e32 v189, v189
	v_and_b32_e32 v186, 0xff, v186
	v_and_b32_e32 v187, 0xff, v187
	v_and_b32_e32 v188, 0xff, v188
	v_lshl_or_b32 v190, v187, 8, v186
	v_lshl_or_b32 v190, v188, 16, v190
	v_lshl_or_b32 v190, v189, 24, v190
	ds_write_b32 v139, v190 offset:1984
	s_cmp_ge_u32 s10, 0x560
	s_cbranch_scc1 .Lc16_ffn1_nopf_7
	global_load_dwordx4 v[118:121], v138, s[56:57] nt
	s_add_u32 s56, s56, 0x15800
	s_addc_u32 s57, s57, 0
	global_load_dwordx4 v[122:125], v138, s[56:57] nt
	s_add_u32 s56, s56, 0x15800
	s_addc_u32 s57, s57, 0
	global_load_dwordx4 v[126:129], v138, s[56:57] nt
	s_add_u32 s56, s56, 0x15800
	s_addc_u32 s57, s57, 0
	global_load_dwordx4 v[130:133], v138, s[56:57] nt
.Lc16_ffn1_nopf_7:
	s_waitcnt lgkmcnt(0)
	s_lshl_b32 s3, s60, 12
	s_lshl_b32 s10, s1, 9
	s_add_u32 s3, s3, s10
	s_add_u32 s58, s34, s3
	s_addc_u32 s59, s35, 0
	s_add_u32 s58, s58, 0xe700000
	s_addc_u32 s59, s59, 0
	ds_read_b128 v[204:207], v212 offset:0
	s_waitcnt lgkmcnt(0)
	global_store_dwordx4 v213, v[204:207], s[58:59]
	s_add_u32 s58, s58, 0x2000
	s_addc_u32 s59, s59, 0
	ds_read_b128 v[208:211], v212 offset:1024
	s_waitcnt lgkmcnt(0)
	global_store_dwordx4 v213, v[208:211], s[58:59]
	s_add_u32 s58, s58, 0x2000
	s_addc_u32 s59, s59, 0
	ds_read_b128 v[204:207], v212 offset:2048
	s_waitcnt lgkmcnt(0)
	global_store_dwordx4 v213, v[204:207], s[58:59]
	s_add_u32 s58, s58, 0x2000
	s_addc_u32 s59, s59, 0
	ds_read_b128 v[208:211], v212 offset:3072
	s_waitcnt lgkmcnt(0)
	global_store_dwordx4 v213, v[208:211], s[58:59]
	s_add_u32 s58, s58, 0x2000
	s_addc_u32 s59, s59, 0
	ds_read_b128 v[204:207], v212 offset:4096
	s_waitcnt lgkmcnt(0)
	global_store_dwordx4 v213, v[204:207], s[58:59]
	s_add_u32 s58, s58, 0x2000
	s_addc_u32 s59, s59, 0
	ds_read_b128 v[208:211], v212 offset:5120
	s_waitcnt lgkmcnt(0)
	global_store_dwordx4 v213, v[208:211], s[58:59]
	s_add_u32 s58, s58, 0x2000
	s_addc_u32 s59, s59, 0
	ds_read_b128 v[204:207], v212 offset:6144
	s_waitcnt lgkmcnt(0)
	global_store_dwordx4 v213, v[204:207], s[58:59]
	s_add_u32 s58, s58, 0x2000
	s_addc_u32 s59, s59, 0
	ds_read_b128 v[208:211], v212 offset:7168
	s_waitcnt lgkmcnt(0)
	global_store_dwordx4 v213, v[208:211], s[58:59]
	s_xor_b32 s11, s11, 1
	s_add_u32 s0, s0, s33
	s_cmp_lt_u32 s0, 0x560
	s_cbranch_scc1 .Lc16_ffn1_loop
.Lc16_ffn1_done:
	v_readlane_b32 s48, v255, 27
	v_readlane_b32 s49, v255, 28
	v_mul_u32_u24_e32 v138, 0x28000, v136
	v_lshl_add_u32 v138, v137, 4, v138
	s_mul_i32 s3, s1, 0x1400000
	s_nop 1
	s_add_u32 s48, s48, s3
	s_addc_u32 s49, s49, 0
	s_mov_b32 s0, s72
	s_cmp_ge_u32 s0, 0x280
	s_cbranch_scc1 .Lc16_mixer_done
	s_lshl_b32 s3, s0, 6
	s_add_u32 s56, s48, s3
	s_addc_u32 s57, s49, 0
	global_load_dwordx4 v[6:9], v138, s[56:57]
	s_add_u32 s56, s56, 0xa000
	s_addc_u32 s57, s57, 0
	global_load_dwordx4 v[10:13], v138, s[56:57]
	s_add_u32 s56, s56, 0xa000
	s_addc_u32 s57, s57, 0
	global_load_dwordx4 v[14:17], v138, s[56:57]
	s_add_u32 s56, s56, 0xa000
	s_addc_u32 s57, s57, 0
	global_load_dwordx4 v[18:21], v138, s[56:57]
	s_add_u32 s56, s56, 0x262000
	s_addc_u32 s57, s57, 0
	global_load_dwordx4 v[22:25], v138, s[56:57]
	s_add_u32 s56, s56, 0xa000
	s_addc_u32 s57, s57, 0
	global_load_dwordx4 v[26:29], v138, s[56:57]
	s_add_u32 s56, s56, 0xa000
	s_addc_u32 s57, s57, 0
	global_load_dwordx4 v[30:33], v138, s[56:57]
	s_add_u32 s56, s56, 0xa000
	s_addc_u32 s57, s57, 0
	global_load_dwordx4 v[34:37], v138, s[56:57]
	s_add_u32 s56, s56, 0x262000
	s_addc_u32 s57, s57, 0
	global_load_dwordx4 v[38:41], v138, s[56:57]
	s_add_u32 s56, s56, 0xa000
	s_addc_u32 s57, s57, 0
	global_load_dwordx4 v[42:45], v138, s[56:57]
	s_add_u32 s56, s56, 0xa000
	s_addc_u32 s57, s57, 0
	global_load_dwordx4 v[46:49], v138, s[56:57]
	s_add_u32 s56, s56, 0xa000
	s_addc_u32 s57, s57, 0
	global_load_dwordx4 v[50:53], v138, s[56:57]
	s_add_u32 s56, s56, 0x262000
	s_addc_u32 s57, s57, 0
	global_load_dwordx4 v[54:57], v138, s[56:57]
	s_add_u32 s56, s56, 0xa000
	s_addc_u32 s57, s57, 0
	global_load_dwordx4 v[58:61], v138, s[56:57]
	s_add_u32 s56, s56, 0xa000
	s_addc_u32 s57, s57, 0
	global_load_dwordx4 v[62:65], v138, s[56:57]
	s_add_u32 s56, s56, 0xa000
	s_addc_u32 s57, s57, 0
	global_load_dwordx4 v[66:69], v138, s[56:57]
	s_add_u32 s56, s56, 0x262000
	s_addc_u32 s57, s57, 0
	global_load_dwordx4 v[70:73], v138, s[56:57]
	s_add_u32 s56, s56, 0xa000
	s_addc_u32 s57, s57, 0
	global_load_dwordx4 v[74:77], v138, s[56:57]
	s_add_u32 s56, s56, 0xa000
	s_addc_u32 s57, s57, 0
	global_load_dwordx4 v[78:81], v138, s[56:57]
	s_add_u32 s56, s56, 0xa000
	s_addc_u32 s57, s57, 0
	global_load_dwordx4 v[82:85], v138, s[56:57]
	s_add_u32 s56, s56, 0x262000
	s_addc_u32 s57, s57, 0
	global_load_dwordx4 v[86:89], v138, s[56:57]
	s_add_u32 s56, s56, 0xa000
	s_addc_u32 s57, s57, 0
	global_load_dwordx4 v[90:93], v138, s[56:57]
	s_add_u32 s56, s56, 0xa000
	s_addc_u32 s57, s57, 0
	global_load_dwordx4 v[94:97], v138, s[56:57]
	s_add_u32 s56, s56, 0xa000
	s_addc_u32 s57, s57, 0
	global_load_dwordx4 v[98:101], v138, s[56:57]
	s_add_u32 s56, s56, 0x262000
	s_addc_u32 s57, s57, 0
	global_load_dwordx4 v[102:105], v138, s[56:57]
	s_add_u32 s56, s56, 0xa000
	s_addc_u32 s57, s57, 0
	global_load_dwordx4 v[106:109], v138, s[56:57]
	s_add_u32 s56, s56, 0xa000
	s_addc_u32 s57, s57, 0
	global_load_dwordx4 v[110:113], v138, s[56:57]
	s_add_u32 s56, s56, 0xa000
	s_addc_u32 s57, s57, 0
	global_load_dwordx4 v[114:117], v138, s[56:57]
	s_add_u32 s56, s56, 0x262000
	s_addc_u32 s57, s57, 0
	global_load_dwordx4 v[118:121], v138, s[56:57]
	s_add_u32 s56, s56, 0xa000
	s_addc_u32 s57, s57, 0
	global_load_dwordx4 v[122:125], v138, s[56:57]
	s_add_u32 s56, s56, 0xa000
	s_addc_u32 s57, s57, 0
	global_load_dwordx4 v[126:129], v138, s[56:57]
	s_add_u32 s56, s56, 0xa000
	s_addc_u32 s57, s57, 0
	global_load_dwordx4 v[130:133], v138, s[56:57]
.Lc16_mixer_loop:
	s_lshl_b32 s2, s0, 4
	s_mov_b32 s60, s2
	s_lshl_b32 s63, s11, 9
	s_add_u32 s63, s63, 0x21000
	s_lshl_b32 s3, s1, 6
	s_add_u32 s3, s3, s63
	v_add_u32_e32 v172, s3, v230
	v_add_u32_e32 v173, s63, v230
	s_waitcnt vmcnt(0)
	v_max3_f32 v216, |v6|, |v10|, |v14|
	v_max3_f32 v216, v216, |v18|, |v22|
	v_max3_f32 v216, v216, |v26|, |v30|
	v_max3_f32 v216, v216, |v34|, |v38|
	v_max3_f32 v216, v216, |v42|, |v46|
	v_max3_f32 v216, v216, |v50|, |v54|
	v_max3_f32 v216, v216, |v58|, |v62|
	v_max3_f32 v216, v216, |v66|, |v70|
	v_max3_f32 v216, v216, |v74|, |v78|
	v_max3_f32 v216, v216, |v82|, |v86|
	v_max3_f32 v216, v216, |v90|, |v94|
	v_max3_f32 v216, v216, |v98|, |v102|
	v_max3_f32 v216, v216, |v106|, |v110|
	v_max3_f32 v216, v216, |v114|, |v118|
	v_max3_f32 v216, v216, |v122|, |v126|
	v_max_f32_e64 v216, v216, |v130|
	v_max3_f32 v217, |v7|, |v11|, |v15|
	v_max3_f32 v217, v217, |v19|, |v23|
	v_max3_f32 v217, v217, |v27|, |v31|
	v_max3_f32 v217, v217, |v35|, |v39|
	v_max3_f32 v217, v217, |v43|, |v47|
	v_max3_f32 v217, v217, |v51|, |v55|
	v_max3_f32 v217, v217, |v59|, |v63|
	v_max3_f32 v217, v217, |v67|, |v71|
	v_max3_f32 v217, v217, |v75|, |v79|
	v_max3_f32 v217, v217, |v83|, |v87|
	v_max3_f32 v217, v217, |v91|, |v95|
	v_max3_f32 v217, v217, |v99|, |v103|
	v_max3_f32 v217, v217, |v107|, |v111|
	v_max3_f32 v217, v217, |v115|, |v119|
	v_max3_f32 v217, v217, |v123|, |v127|
	v_max_f32_e64 v217, v217, |v131|
	v_max3_f32 v218, |v8|, |v12|, |v16|
	v_max3_f32 v218, v218, |v20|, |v24|
	v_max3_f32 v218, v218, |v28|, |v32|
	v_max3_f32 v218, v218, |v36|, |v40|
	v_max3_f32 v218, v218, |v44|, |v48|
	v_max3_f32 v218, v218, |v52|, |v56|
	v_max3_f32 v218, v218, |v60|, |v64|
	v_max3_f32 v218, v218, |v68|, |v72|
	v_max3_f32 v218, v218, |v76|, |v80|
	v_max3_f32 v218, v218, |v84|, |v88|
	v_max3_f32 v218, v218, |v92|, |v96|
	v_max3_f32 v218, v218, |v100|, |v104|
	v_max3_f32 v218, v218, |v108|, |v112|
	v_max3_f32 v218, v218, |v116|, |v120|
	v_max3_f32 v218, v218, |v124|, |v128|
	v_max_f32_e64 v218, v218, |v132|
	v_max3_f32 v219, |v9|, |v13|, |v17|
	v_max3_f32 v219, v219, |v21|, |v25|
	v_max3_f32 v219, v219, |v29|, |v33|
	v_max3_f32 v219, v219, |v37|, |v41|
	v_max3_f32 v219, v219, |v45|, |v49|
	v_max3_f32 v219, v219, |v53|, |v57|
	v_max3_f32 v219, v219, |v61|, |v65|
	v_max3_f32 v219, v219, |v69|, |v73|
	v_max3_f32 v219, v219, |v77|, |v81|
	v_max3_f32 v219, v219, |v85|, |v89|
	v_max3_f32 v219, v219, |v93|, |v97|
	v_max3_f32 v219, v219, |v101|, |v105|
	v_max3_f32 v219, v219, |v109|, |v113|
	v_max3_f32 v219, v219, |v117|, |v121|
	v_max3_f32 v219, v219, |v125|, |v129|
	v_max_f32_e64 v219, v219, |v133|
	ds_bpermute_b32 v174, v192, v216
	ds_bpermute_b32 v175, v192, v217
	ds_bpermute_b32 v176, v192, v218
	ds_bpermute_b32 v177, v192, v219
	s_waitcnt lgkmcnt(0)
	v_max_f32_e32 v216, v216, v174
	v_max_f32_e32 v217, v217, v175
	v_max_f32_e32 v218, v218, v176
	v_max_f32_e32 v219, v219, v177
	ds_bpermute_b32 v174, v193, v216
	ds_bpermute_b32 v175, v193, v217
	ds_bpermute_b32 v176, v193, v218
	ds_bpermute_b32 v177, v193, v219
	s_waitcnt lgkmcnt(0)
	v_max_f32_e32 v216, v216, v174
	v_max_f32_e32 v217, v217, v175
	v_max_f32_e32 v218, v218, v176
	v_max_f32_e32 v219, v219, v177
	ds_bpermute_b32 v174, v194, v216
	ds_bpermute_b32 v175, v194, v217
	ds_bpermute_b32 v176, v194, v218
	ds_bpermute_b32 v177, v194, v219
	s_waitcnt lgkmcnt(0)
	v_max_f32_e32 v216, v216, v174
	v_max_f32_e32 v217, v217, v175
	v_max_f32_e32 v218, v218, v176
	v_max_f32_e32 v219, v219, v177
	ds_bpermute_b32 v174, v195, v216
	ds_bpermute_b32 v175, v195, v217
	ds_bpermute_b32 v176, v195, v218
	ds_bpermute_b32 v177, v195, v219
	s_waitcnt lgkmcnt(0)
	v_max_f32_e32 v216, v216, v174
	v_max_f32_e32 v217, v217, v175
	v_max_f32_e32 v218, v218, v176
	v_max_f32_e32 v219, v219, v177
	s_mov_b64 s[70:71], exec
	s_mov_b64 exec, 15
	ds_write_b128 v172, v[216:219]
	s_mov_b64 exec, s[70:71]
	s_waitcnt lgkmcnt(0)
	s_barrier
	ds_read_b128 v[140:143], v173 offset:0
	ds_read_b128 v[144:147], v173 offset:64
	ds_read_b128 v[148:151], v173 offset:128
	ds_read_b128 v[152:155], v173 offset:192
	ds_read_b128 v[156:159], v173 offset:256
	ds_read_b128 v[160:163], v173 offset:320
	ds_read_b128 v[164:167], v173 offset:384
	ds_read_b128 v[232:235], v173 offset:448
	s_waitcnt lgkmcnt(0)
	v_max3_f32 v220, v140, v144, v148
	v_max3_f32 v220, v220, v152, v156
	v_max3_f32 v220, v220, v160, v164
	v_max_f32_e32 v220, v220, v232
	v_max3_f32 v221, v141, v145, v149
	v_max3_f32 v221, v221, v153, v157
	v_max3_f32 v221, v221, v161, v165
	v_max_f32_e32 v221, v221, v233
	v_max3_f32 v222, v142, v146, v150
	v_max3_f32 v222, v222, v154, v158
	v_max3_f32 v222, v222, v162, v166
	v_max_f32_e32 v222, v222, v234
	v_max3_f32 v223, v143, v147, v151
	v_max3_f32 v223, v223, v155, v159
	v_max3_f32 v223, v223, v163, v167
	v_max_f32_e32 v223, v223, v235
	s_cmp_lg_u32 s1, 0
	s_cbranch_scc1 .Lc16_mixer_nocm
	s_lshl_b32 s3, s2, 2
	s_add_u32 s56, s34, s3
	s_addc_u32 s57, s35, 0
	s_add_u32 s56, s56, 0xe0000
	s_addc_u32 s57, s57, 0
	s_mov_b64 s[70:71], exec
	s_mov_b64 exec, 15
	global_store_dwordx4 v230, v[220:223], s[56:57]
	s_mov_b64 exec, s[70:71]
.Lc16_mixer_nocm:
	v_div_scale_f32 v175, s[70:71], v220, v220, s74
	v_rcp_f32_e32 v176, v175
	s_nop 0
	v_fma_f32 v177, -v175, v176, 1.0
	v_fmac_f32_e32 v176, v177, v176
	v_div_scale_f32 v177, vcc, s74, v220, s74
	v_mul_f32_e32 v178, v177, v176
	v_fma_f32 v180, -v175, v178, v177
	v_fmac_f32_e32 v178, v180, v176
	v_fma_f32 v175, -v175, v178, v177
	s_nop 0
	v_div_fmas_f32 v175, v175, v176, v178
	v_div_fixup_f32 v175, v175, v220, s74
	v_cmp_lt_f32_e32 vcc, 0, v220
	s_nop 1
	v_cndmask_b32_e32 v226, 0, v175, vcc
	v_div_scale_f32 v175, s[70:71], v221, v221, s74
	v_rcp_f32_e32 v176, v175
	s_nop 0
	v_fma_f32 v177, -v175, v176, 1.0
	v_fmac_f32_e32 v176, v177, v176
	v_div_scale_f32 v177, vcc, s74, v221, s74
	v_mul_f32_e32 v178, v177, v176
	v_fma_f32 v180, -v175, v178, v177
	v_fmac_f32_e32 v178, v180, v176
	v_fma_f32 v175, -v175, v178, v177
	s_nop 0
	v_div_fmas_f32 v175, v175, v176, v178
	v_div_fixup_f32 v175, v175, v221, s74
	v_cmp_lt_f32_e32 vcc, 0, v221
	s_nop 1
	v_cndmask_b32_e32 v227, 0, v175, vcc
	v_div_scale_f32 v175, s[70:71], v222, v222, s74
	v_rcp_f32_e32 v176, v175
	s_nop 0
	v_fma_f32 v177, -v175, v176, 1.0
	v_fmac_f32_e32 v176, v177, v176
	v_div_scale_f32 v177, vcc, s74, v222, s74
	v_mul_f32_e32 v178, v177, v176
	v_fma_f32 v180, -v175, v178, v177
	v_fmac_f32_e32 v178, v180, v176
	v_fma_f32 v175, -v175, v178, v177
	s_nop 0
	v_div_fmas_f32 v175, v175, v176, v178
	v_div_fixup_f32 v175, v175, v222, s74
	v_cmp_lt_f32_e32 vcc, 0, v222
	s_nop 1
	v_cndmask_b32_e32 v228, 0, v175, vcc
	v_div_scale_f32 v175, s[70:71], v223, v223, s74
	v_rcp_f32_e32 v176, v175
	s_nop 0
	v_fma_f32 v177, -v175, v176, 1.0
	v_fmac_f32_e32 v176, v177, v176
	v_div_scale_f32 v177, vcc, s74, v223, s74
	v_mul_f32_e32 v178, v177, v176
	v_fma_f32 v180, -v175, v178, v177
	v_fmac_f32_e32 v178, v180, v176
	v_fma_f32 v175, -v175, v178, v177
	s_nop 0
	v_div_fmas_f32 v175, v175, v176, v178
	v_div_fixup_f32 v175, v175, v223, s74
	v_cmp_lt_f32_e32 vcc, 0, v223
	s_nop 1
	v_cndmask_b32_e32 v229, 0, v175, vcc
	s_add_u32 s10, s0, s33
	s_lshl_b32 s3, s10, 6
	s_add_u32 s56, s48, s3
	s_addc_u32 s57, s49, 0
	v_mul_f32_e32 v186, v6, v226
	v_rndne_f32_e32 v186, v186
	v_cvt_i32_f32_e32 v186, v186
	v_mul_f32_e32 v187, v10, v226
	v_rndne_f32_e32 v187, v187
	v_cvt_i32_f32_e32 v187, v187
	v_mul_f32_e32 v188, v14, v226
	v_rndne_f32_e32 v188, v188
	v_cvt_i32_f32_e32 v188, v188
	v_mul_f32_e32 v189, v18, v226
	v_rndne_f32_e32 v189, v189
	v_cvt_i32_f32_e32 v189, v189
	v_and_b32_e32 v186, 0xff, v186
	v_and_b32_e32 v187, 0xff, v187
	v_and_b32_e32 v188, 0xff, v188
	v_lshl_or_b32 v190, v187, 8, v186
	v_lshl_or_b32 v190, v188, 16, v190
	v_lshl_or_b32 v190, v189, 24, v190
	ds_write_b32 v139, v190 offset:0
	v_mul_f32_e32 v186, v7, v227
	v_rndne_f32_e32 v186, v186
	v_cvt_i32_f32_e32 v186, v186
	v_mul_f32_e32 v187, v11, v227
	v_rndne_f32_e32 v187, v187
	v_cvt_i32_f32_e32 v187, v187
	v_mul_f32_e32 v188, v15, v227
	v_rndne_f32_e32 v188, v188
	v_cvt_i32_f32_e32 v188, v188
	v_mul_f32_e32 v189, v19, v227
	v_rndne_f32_e32 v189, v189
	v_cvt_i32_f32_e32 v189, v189
	v_and_b32_e32 v186, 0xff, v186
	v_and_b32_e32 v187, 0xff, v187
	v_and_b32_e32 v188, 0xff, v188
	v_lshl_or_b32 v190, v187, 8, v186
	v_lshl_or_b32 v190, v188, 16, v190
	v_lshl_or_b32 v190, v189, 24, v190
	ds_write_b32 v139, v190 offset:512
	v_mul_f32_e32 v186, v8, v228
	v_rndne_f32_e32 v186, v186
	v_cvt_i32_f32_e32 v186, v186
	v_mul_f32_e32 v187, v12, v228
	v_rndne_f32_e32 v187, v187
	v_cvt_i32_f32_e32 v187, v187
	v_mul_f32_e32 v188, v16, v228
	v_rndne_f32_e32 v188, v188
	v_cvt_i32_f32_e32 v188, v188
	v_mul_f32_e32 v189, v20, v228
	v_rndne_f32_e32 v189, v189
	v_cvt_i32_f32_e32 v189, v189
	v_and_b32_e32 v186, 0xff, v186
	v_and_b32_e32 v187, 0xff, v187
	v_and_b32_e32 v188, 0xff, v188
	v_lshl_or_b32 v190, v187, 8, v186
	v_lshl_or_b32 v190, v188, 16, v190
	v_lshl_or_b32 v190, v189, 24, v190
	ds_write_b32 v139, v190 offset:1024
	v_mul_f32_e32 v186, v9, v229
	v_rndne_f32_e32 v186, v186
	v_cvt_i32_f32_e32 v186, v186
	v_mul_f32_e32 v187, v13, v229
	v_rndne_f32_e32 v187, v187
	v_cvt_i32_f32_e32 v187, v187
	v_mul_f32_e32 v188, v17, v229
	v_rndne_f32_e32 v188, v188
	v_cvt_i32_f32_e32 v188, v188
	v_mul_f32_e32 v189, v21, v229
	v_rndne_f32_e32 v189, v189
	v_cvt_i32_f32_e32 v189, v189
	v_and_b32_e32 v186, 0xff, v186
	v_and_b32_e32 v187, 0xff, v187
	v_and_b32_e32 v188, 0xff, v188
	v_lshl_or_b32 v190, v187, 8, v186
	v_lshl_or_b32 v190, v188, 16, v190
	v_lshl_or_b32 v190, v189, 24, v190
	ds_write_b32 v139, v190 offset:1536
	s_cmp_ge_u32 s10, 0x280
	s_cbranch_scc1 .Lc16_mixer_nopf_0
	global_load_dwordx4 v[6:9], v138, s[56:57]
	s_add_u32 s56, s56, 0xa000
	s_addc_u32 s57, s57, 0
	global_load_dwordx4 v[10:13], v138, s[56:57]
	s_add_u32 s56, s56, 0xa000
	s_addc_u32 s57, s57, 0
	global_load_dwordx4 v[14:17], v138, s[56:57]
	s_add_u32 s56, s56, 0xa000
	s_addc_u32 s57, s57, 0
	global_load_dwordx4 v[18:21], v138, s[56:57]
	s_add_u32 s56, s56, 0x262000
	s_addc_u32 s57, s57, 0
.Lc16_mixer_nopf_0:
	v_mul_f32_e32 v186, v22, v226
	v_rndne_f32_e32 v186, v186
	v_cvt_i32_f32_e32 v186, v186
	v_mul_f32_e32 v187, v26, v226
	v_rndne_f32_e32 v187, v187
	v_cvt_i32_f32_e32 v187, v187
	v_mul_f32_e32 v188, v30, v226
	v_rndne_f32_e32 v188, v188
	v_cvt_i32_f32_e32 v188, v188
	v_mul_f32_e32 v189, v34, v226
	v_rndne_f32_e32 v189, v189
	v_cvt_i32_f32_e32 v189, v189
	v_and_b32_e32 v186, 0xff, v186
	v_and_b32_e32 v187, 0xff, v187
	v_and_b32_e32 v188, 0xff, v188
	v_lshl_or_b32 v190, v187, 8, v186
	v_lshl_or_b32 v190, v188, 16, v190
	v_lshl_or_b32 v190, v189, 24, v190
	ds_write_b32 v139, v190 offset:64
	v_mul_f32_e32 v186, v23, v227
	v_rndne_f32_e32 v186, v186
	v_cvt_i32_f32_e32 v186, v186
	v_mul_f32_e32 v187, v27, v227
	v_rndne_f32_e32 v187, v187
	v_cvt_i32_f32_e32 v187, v187
	v_mul_f32_e32 v188, v31, v227
	v_rndne_f32_e32 v188, v188
	v_cvt_i32_f32_e32 v188, v188
	v_mul_f32_e32 v189, v35, v227
	v_rndne_f32_e32 v189, v189
	v_cvt_i32_f32_e32 v189, v189
	v_and_b32_e32 v186, 0xff, v186
	v_and_b32_e32 v187, 0xff, v187
	v_and_b32_e32 v188, 0xff, v188
	v_lshl_or_b32 v190, v187, 8, v186
	v_lshl_or_b32 v190, v188, 16, v190
	v_lshl_or_b32 v190, v189, 24, v190
	ds_write_b32 v139, v190 offset:576
	v_mul_f32_e32 v186, v24, v228
	v_rndne_f32_e32 v186, v186
	v_cvt_i32_f32_e32 v186, v186
	v_mul_f32_e32 v187, v28, v228
	v_rndne_f32_e32 v187, v187
	v_cvt_i32_f32_e32 v187, v187
	v_mul_f32_e32 v188, v32, v228
	v_rndne_f32_e32 v188, v188
	v_cvt_i32_f32_e32 v188, v188
	v_mul_f32_e32 v189, v36, v228
	v_rndne_f32_e32 v189, v189
	v_cvt_i32_f32_e32 v189, v189
	v_and_b32_e32 v186, 0xff, v186
	v_and_b32_e32 v187, 0xff, v187
	v_and_b32_e32 v188, 0xff, v188
	v_lshl_or_b32 v190, v187, 8, v186
	v_lshl_or_b32 v190, v188, 16, v190
	v_lshl_or_b32 v190, v189, 24, v190
	ds_write_b32 v139, v190 offset:1088
	v_mul_f32_e32 v186, v25, v229
	v_rndne_f32_e32 v186, v186
	v_cvt_i32_f32_e32 v186, v186
	v_mul_f32_e32 v187, v29, v229
	v_rndne_f32_e32 v187, v187
	v_cvt_i32_f32_e32 v187, v187
	v_mul_f32_e32 v188, v33, v229
	v_rndne_f32_e32 v188, v188
	v_cvt_i32_f32_e32 v188, v188
	v_mul_f32_e32 v189, v37, v229
	v_rndne_f32_e32 v189, v189
	v_cvt_i32_f32_e32 v189, v189
	v_and_b32_e32 v186, 0xff, v186
	v_and_b32_e32 v187, 0xff, v187
	v_and_b32_e32 v188, 0xff, v188
	v_lshl_or_b32 v190, v187, 8, v186
	v_lshl_or_b32 v190, v188, 16, v190
	v_lshl_or_b32 v190, v189, 24, v190
	ds_write_b32 v139, v190 offset:1600
	s_cmp_ge_u32 s10, 0x280
	s_cbranch_scc1 .Lc16_mixer_nopf_1
	global_load_dwordx4 v[22:25], v138, s[56:57]
	s_add_u32 s56, s56, 0xa000
	s_addc_u32 s57, s57, 0
	global_load_dwordx4 v[26:29], v138, s[56:57]
	s_add_u32 s56, s56, 0xa000
	s_addc_u32 s57, s57, 0
	global_load_dwordx4 v[30:33], v138, s[56:57]
	s_add_u32 s56, s56, 0xa000
	s_addc_u32 s57, s57, 0
	global_load_dwordx4 v[34:37], v138, s[56:57]
	s_add_u32 s56, s56, 0x262000
	s_addc_u32 s57, s57, 0
.Lc16_mixer_nopf_1:
	v_mul_f32_e32 v186, v38, v226
	v_rndne_f32_e32 v186, v186
	v_cvt_i32_f32_e32 v186, v186
	v_mul_f32_e32 v187, v42, v226
	v_rndne_f32_e32 v187, v187
	v_cvt_i32_f32_e32 v187, v187
	v_mul_f32_e32 v188, v46, v226
	v_rndne_f32_e32 v188, v188
	v_cvt_i32_f32_e32 v188, v188
	v_mul_f32_e32 v189, v50, v226
	v_rndne_f32_e32 v189, v189
	v_cvt_i32_f32_e32 v189, v189
	v_and_b32_e32 v186, 0xff, v186
	v_and_b32_e32 v187, 0xff, v187
	v_and_b32_e32 v188, 0xff, v188
	v_lshl_or_b32 v190, v187, 8, v186
	v_lshl_or_b32 v190, v188, 16, v190
	v_lshl_or_b32 v190, v189, 24, v190
	ds_write_b32 v139, v190 offset:128
	v_mul_f32_e32 v186, v39, v227
	v_rndne_f32_e32 v186, v186
	v_cvt_i32_f32_e32 v186, v186
	v_mul_f32_e32 v187, v43, v227
	v_rndne_f32_e32 v187, v187
	v_cvt_i32_f32_e32 v187, v187
	v_mul_f32_e32 v188, v47, v227
	v_rndne_f32_e32 v188, v188
	v_cvt_i32_f32_e32 v188, v188
	v_mul_f32_e32 v189, v51, v227
	v_rndne_f32_e32 v189, v189
	v_cvt_i32_f32_e32 v189, v189
	v_and_b32_e32 v186, 0xff, v186
	v_and_b32_e32 v187, 0xff, v187
	v_and_b32_e32 v188, 0xff, v188
	v_lshl_or_b32 v190, v187, 8, v186
	v_lshl_or_b32 v190, v188, 16, v190
	v_lshl_or_b32 v190, v189, 24, v190
	ds_write_b32 v139, v190 offset:640
	v_mul_f32_e32 v186, v40, v228
	v_rndne_f32_e32 v186, v186
	v_cvt_i32_f32_e32 v186, v186
	v_mul_f32_e32 v187, v44, v228
	v_rndne_f32_e32 v187, v187
	v_cvt_i32_f32_e32 v187, v187
	v_mul_f32_e32 v188, v48, v228
	v_rndne_f32_e32 v188, v188
	v_cvt_i32_f32_e32 v188, v188
	v_mul_f32_e32 v189, v52, v228
	v_rndne_f32_e32 v189, v189
	v_cvt_i32_f32_e32 v189, v189
	v_and_b32_e32 v186, 0xff, v186
	v_and_b32_e32 v187, 0xff, v187
	v_and_b32_e32 v188, 0xff, v188
	v_lshl_or_b32 v190, v187, 8, v186
	v_lshl_or_b32 v190, v188, 16, v190
	v_lshl_or_b32 v190, v189, 24, v190
	ds_write_b32 v139, v190 offset:1152
	v_mul_f32_e32 v186, v41, v229
	v_rndne_f32_e32 v186, v186
	v_cvt_i32_f32_e32 v186, v186
	v_mul_f32_e32 v187, v45, v229
	v_rndne_f32_e32 v187, v187
	v_cvt_i32_f32_e32 v187, v187
	v_mul_f32_e32 v188, v49, v229
	v_rndne_f32_e32 v188, v188
	v_cvt_i32_f32_e32 v188, v188
	v_mul_f32_e32 v189, v53, v229
	v_rndne_f32_e32 v189, v189
	v_cvt_i32_f32_e32 v189, v189
	v_and_b32_e32 v186, 0xff, v186
	v_and_b32_e32 v187, 0xff, v187
	v_and_b32_e32 v188, 0xff, v188
	v_lshl_or_b32 v190, v187, 8, v186
	v_lshl_or_b32 v190, v188, 16, v190
	v_lshl_or_b32 v190, v189, 24, v190
	ds_write_b32 v139, v190 offset:1664
	s_cmp_ge_u32 s10, 0x280
	s_cbranch_scc1 .Lc16_mixer_nopf_2
	global_load_dwordx4 v[38:41], v138, s[56:57]
	s_add_u32 s56, s56, 0xa000
	s_addc_u32 s57, s57, 0
	global_load_dwordx4 v[42:45], v138, s[56:57]
	s_add_u32 s56, s56, 0xa000
	s_addc_u32 s57, s57, 0
	global_load_dwordx4 v[46:49], v138, s[56:57]
	s_add_u32 s56, s56, 0xa000
	s_addc_u32 s57, s57, 0
	global_load_dwordx4 v[50:53], v138, s[56:57]
	s_add_u32 s56, s56, 0x262000
	s_addc_u32 s57, s57, 0
.Lc16_mixer_nopf_2:
	v_mul_f32_e32 v186, v54, v226
	v_rndne_f32_e32 v186, v186
	v_cvt_i32_f32_e32 v186, v186
	v_mul_f32_e32 v187, v58, v226
	v_rndne_f32_e32 v187, v187
	v_cvt_i32_f32_e32 v187, v187
	v_mul_f32_e32 v188, v62, v226
	v_rndne_f32_e32 v188, v188
	v_cvt_i32_f32_e32 v188, v188
	v_mul_f32_e32 v189, v66, v226
	v_rndne_f32_e32 v189, v189
	v_cvt_i32_f32_e32 v189, v189
	v_and_b32_e32 v186, 0xff, v186
	v_and_b32_e32 v187, 0xff, v187
	v_and_b32_e32 v188, 0xff, v188
	v_lshl_or_b32 v190, v187, 8, v186
	v_lshl_or_b32 v190, v188, 16, v190
	v_lshl_or_b32 v190, v189, 24, v190
	ds_write_b32 v139, v190 offset:192
	v_mul_f32_e32 v186, v55, v227
	v_rndne_f32_e32 v186, v186
	v_cvt_i32_f32_e32 v186, v186
	v_mul_f32_e32 v187, v59, v227
	v_rndne_f32_e32 v187, v187
	v_cvt_i32_f32_e32 v187, v187
	v_mul_f32_e32 v188, v63, v227
	v_rndne_f32_e32 v188, v188
	v_cvt_i32_f32_e32 v188, v188
	v_mul_f32_e32 v189, v67, v227
	v_rndne_f32_e32 v189, v189
	v_cvt_i32_f32_e32 v189, v189
	v_and_b32_e32 v186, 0xff, v186
	v_and_b32_e32 v187, 0xff, v187
	v_and_b32_e32 v188, 0xff, v188
	v_lshl_or_b32 v190, v187, 8, v186
	v_lshl_or_b32 v190, v188, 16, v190
	v_lshl_or_b32 v190, v189, 24, v190
	ds_write_b32 v139, v190 offset:704
	v_mul_f32_e32 v186, v56, v228
	v_rndne_f32_e32 v186, v186
	v_cvt_i32_f32_e32 v186, v186
	v_mul_f32_e32 v187, v60, v228
	v_rndne_f32_e32 v187, v187
	v_cvt_i32_f32_e32 v187, v187
	v_mul_f32_e32 v188, v64, v228
	v_rndne_f32_e32 v188, v188
	v_cvt_i32_f32_e32 v188, v188
	v_mul_f32_e32 v189, v68, v228
	v_rndne_f32_e32 v189, v189
	v_cvt_i32_f32_e32 v189, v189
	v_and_b32_e32 v186, 0xff, v186
	v_and_b32_e32 v187, 0xff, v187
	v_and_b32_e32 v188, 0xff, v188
	v_lshl_or_b32 v190, v187, 8, v186
	v_lshl_or_b32 v190, v188, 16, v190
	v_lshl_or_b32 v190, v189, 24, v190
	ds_write_b32 v139, v190 offset:1216
	v_mul_f32_e32 v186, v57, v229
	v_rndne_f32_e32 v186, v186
	v_cvt_i32_f32_e32 v186, v186
	v_mul_f32_e32 v187, v61, v229
	v_rndne_f32_e32 v187, v187
	v_cvt_i32_f32_e32 v187, v187
	v_mul_f32_e32 v188, v65, v229
	v_rndne_f32_e32 v188, v188
	v_cvt_i32_f32_e32 v188, v188
	v_mul_f32_e32 v189, v69, v229
	v_rndne_f32_e32 v189, v189
	v_cvt_i32_f32_e32 v189, v189
	v_and_b32_e32 v186, 0xff, v186
	v_and_b32_e32 v187, 0xff, v187
	v_and_b32_e32 v188, 0xff, v188
	v_lshl_or_b32 v190, v187, 8, v186
	v_lshl_or_b32 v190, v188, 16, v190
	v_lshl_or_b32 v190, v189, 24, v190
	ds_write_b32 v139, v190 offset:1728
	s_cmp_ge_u32 s10, 0x280
	s_cbranch_scc1 .Lc16_mixer_nopf_3
	global_load_dwordx4 v[54:57], v138, s[56:57]
	s_add_u32 s56, s56, 0xa000
	s_addc_u32 s57, s57, 0
	global_load_dwordx4 v[58:61], v138, s[56:57]
	s_add_u32 s56, s56, 0xa000
	s_addc_u32 s57, s57, 0
	global_load_dwordx4 v[62:65], v138, s[56:57]
	s_add_u32 s56, s56, 0xa000
	s_addc_u32 s57, s57, 0
	global_load_dwordx4 v[66:69], v138, s[56:57]
	s_add_u32 s56, s56, 0x262000
	s_addc_u32 s57, s57, 0
.Lc16_mixer_nopf_3:
	v_mul_f32_e32 v186, v70, v226
	v_rndne_f32_e32 v186, v186
	v_cvt_i32_f32_e32 v186, v186
	v_mul_f32_e32 v187, v74, v226
	v_rndne_f32_e32 v187, v187
	v_cvt_i32_f32_e32 v187, v187
	v_mul_f32_e32 v188, v78, v226
	v_rndne_f32_e32 v188, v188
	v_cvt_i32_f32_e32 v188, v188
	v_mul_f32_e32 v189, v82, v226
	v_rndne_f32_e32 v189, v189
	v_cvt_i32_f32_e32 v189, v189
	v_and_b32_e32 v186, 0xff, v186
	v_and_b32_e32 v187, 0xff, v187
	v_and_b32_e32 v188, 0xff, v188
	v_lshl_or_b32 v190, v187, 8, v186
	v_lshl_or_b32 v190, v188, 16, v190
	v_lshl_or_b32 v190, v189, 24, v190
	ds_write_b32 v139, v190 offset:256
	v_mul_f32_e32 v186, v71, v227
	v_rndne_f32_e32 v186, v186
	v_cvt_i32_f32_e32 v186, v186
	v_mul_f32_e32 v187, v75, v227
	v_rndne_f32_e32 v187, v187
	v_cvt_i32_f32_e32 v187, v187
	v_mul_f32_e32 v188, v79, v227
	v_rndne_f32_e32 v188, v188
	v_cvt_i32_f32_e32 v188, v188
	v_mul_f32_e32 v189, v83, v227
	v_rndne_f32_e32 v189, v189
	v_cvt_i32_f32_e32 v189, v189
	v_and_b32_e32 v186, 0xff, v186
	v_and_b32_e32 v187, 0xff, v187
	v_and_b32_e32 v188, 0xff, v188
	v_lshl_or_b32 v190, v187, 8, v186
	v_lshl_or_b32 v190, v188, 16, v190
	v_lshl_or_b32 v190, v189, 24, v190
	ds_write_b32 v139, v190 offset:768
	v_mul_f32_e32 v186, v72, v228
	v_rndne_f32_e32 v186, v186
	v_cvt_i32_f32_e32 v186, v186
	v_mul_f32_e32 v187, v76, v228
	v_rndne_f32_e32 v187, v187
	v_cvt_i32_f32_e32 v187, v187
	v_mul_f32_e32 v188, v80, v228
	v_rndne_f32_e32 v188, v188
	v_cvt_i32_f32_e32 v188, v188
	v_mul_f32_e32 v189, v84, v228
	v_rndne_f32_e32 v189, v189
	v_cvt_i32_f32_e32 v189, v189
	v_and_b32_e32 v186, 0xff, v186
	v_and_b32_e32 v187, 0xff, v187
	v_and_b32_e32 v188, 0xff, v188
	v_lshl_or_b32 v190, v187, 8, v186
	v_lshl_or_b32 v190, v188, 16, v190
	v_lshl_or_b32 v190, v189, 24, v190
	ds_write_b32 v139, v190 offset:1280
	v_mul_f32_e32 v186, v73, v229
	v_rndne_f32_e32 v186, v186
	v_cvt_i32_f32_e32 v186, v186
	v_mul_f32_e32 v187, v77, v229
	v_rndne_f32_e32 v187, v187
	v_cvt_i32_f32_e32 v187, v187
	v_mul_f32_e32 v188, v81, v229
	v_rndne_f32_e32 v188, v188
	v_cvt_i32_f32_e32 v188, v188
	v_mul_f32_e32 v189, v85, v229
	v_rndne_f32_e32 v189, v189
	v_cvt_i32_f32_e32 v189, v189
	v_and_b32_e32 v186, 0xff, v186
	v_and_b32_e32 v187, 0xff, v187
	v_and_b32_e32 v188, 0xff, v188
	v_lshl_or_b32 v190, v187, 8, v186
	v_lshl_or_b32 v190, v188, 16, v190
	v_lshl_or_b32 v190, v189, 24, v190
	ds_write_b32 v139, v190 offset:1792
	s_cmp_ge_u32 s10, 0x280
	s_cbranch_scc1 .Lc16_mixer_nopf_4
	global_load_dwordx4 v[70:73], v138, s[56:57]
	s_add_u32 s56, s56, 0xa000
	s_addc_u32 s57, s57, 0
	global_load_dwordx4 v[74:77], v138, s[56:57]
	s_add_u32 s56, s56, 0xa000
	s_addc_u32 s57, s57, 0
	global_load_dwordx4 v[78:81], v138, s[56:57]
	s_add_u32 s56, s56, 0xa000
	s_addc_u32 s57, s57, 0
	global_load_dwordx4 v[82:85], v138, s[56:57]
	s_add_u32 s56, s56, 0x262000
	s_addc_u32 s57, s57, 0
.Lc16_mixer_nopf_4:
	v_mul_f32_e32 v186, v86, v226
	v_rndne_f32_e32 v186, v186
	v_cvt_i32_f32_e32 v186, v186
	v_mul_f32_e32 v187, v90, v226
	v_rndne_f32_e32 v187, v187
	v_cvt_i32_f32_e32 v187, v187
	v_mul_f32_e32 v188, v94, v226
	v_rndne_f32_e32 v188, v188
	v_cvt_i32_f32_e32 v188, v188
	v_mul_f32_e32 v189, v98, v226
	v_rndne_f32_e32 v189, v189
	v_cvt_i32_f32_e32 v189, v189
	v_and_b32_e32 v186, 0xff, v186
	v_and_b32_e32 v187, 0xff, v187
	v_and_b32_e32 v188, 0xff, v188
	v_lshl_or_b32 v190, v187, 8, v186
	v_lshl_or_b32 v190, v188, 16, v190
	v_lshl_or_b32 v190, v189, 24, v190
	ds_write_b32 v139, v190 offset:320
	v_mul_f32_e32 v186, v87, v227
	v_rndne_f32_e32 v186, v186
	v_cvt_i32_f32_e32 v186, v186
	v_mul_f32_e32 v187, v91, v227
	v_rndne_f32_e32 v187, v187
	v_cvt_i32_f32_e32 v187, v187
	v_mul_f32_e32 v188, v95, v227
	v_rndne_f32_e32 v188, v188
	v_cvt_i32_f32_e32 v188, v188
	v_mul_f32_e32 v189, v99, v227
	v_rndne_f32_e32 v189, v189
	v_cvt_i32_f32_e32 v189, v189
	v_and_b32_e32 v186, 0xff, v186
	v_and_b32_e32 v187, 0xff, v187
	v_and_b32_e32 v188, 0xff, v188
	v_lshl_or_b32 v190, v187, 8, v186
	v_lshl_or_b32 v190, v188, 16, v190
	v_lshl_or_b32 v190, v189, 24, v190
	ds_write_b32 v139, v190 offset:832
	v_mul_f32_e32 v186, v88, v228
	v_rndne_f32_e32 v186, v186
	v_cvt_i32_f32_e32 v186, v186
	v_mul_f32_e32 v187, v92, v228
	v_rndne_f32_e32 v187, v187
	v_cvt_i32_f32_e32 v187, v187
	v_mul_f32_e32 v188, v96, v228
	v_rndne_f32_e32 v188, v188
	v_cvt_i32_f32_e32 v188, v188
	v_mul_f32_e32 v189, v100, v228
	v_rndne_f32_e32 v189, v189
	v_cvt_i32_f32_e32 v189, v189
	v_and_b32_e32 v186, 0xff, v186
	v_and_b32_e32 v187, 0xff, v187
	v_and_b32_e32 v188, 0xff, v188
	v_lshl_or_b32 v190, v187, 8, v186
	v_lshl_or_b32 v190, v188, 16, v190
	v_lshl_or_b32 v190, v189, 24, v190
	ds_write_b32 v139, v190 offset:1344
	v_mul_f32_e32 v186, v89, v229
	v_rndne_f32_e32 v186, v186
	v_cvt_i32_f32_e32 v186, v186
	v_mul_f32_e32 v187, v93, v229
	v_rndne_f32_e32 v187, v187
	v_cvt_i32_f32_e32 v187, v187
	v_mul_f32_e32 v188, v97, v229
	v_rndne_f32_e32 v188, v188
	v_cvt_i32_f32_e32 v188, v188
	v_mul_f32_e32 v189, v101, v229
	v_rndne_f32_e32 v189, v189
	v_cvt_i32_f32_e32 v189, v189
	v_and_b32_e32 v186, 0xff, v186
	v_and_b32_e32 v187, 0xff, v187
	v_and_b32_e32 v188, 0xff, v188
	v_lshl_or_b32 v190, v187, 8, v186
	v_lshl_or_b32 v190, v188, 16, v190
	v_lshl_or_b32 v190, v189, 24, v190
	ds_write_b32 v139, v190 offset:1856
	s_cmp_ge_u32 s10, 0x280
	s_cbranch_scc1 .Lc16_mixer_nopf_5
	global_load_dwordx4 v[86:89], v138, s[56:57]
	s_add_u32 s56, s56, 0xa000
	s_addc_u32 s57, s57, 0
	global_load_dwordx4 v[90:93], v138, s[56:57]
	s_add_u32 s56, s56, 0xa000
	s_addc_u32 s57, s57, 0
	global_load_dwordx4 v[94:97], v138, s[56:57]
	s_add_u32 s56, s56, 0xa000
	s_addc_u32 s57, s57, 0
	global_load_dwordx4 v[98:101], v138, s[56:57]
	s_add_u32 s56, s56, 0x262000
	s_addc_u32 s57, s57, 0
.Lc16_mixer_nopf_5:
	v_mul_f32_e32 v186, v102, v226
	v_rndne_f32_e32 v186, v186
	v_cvt_i32_f32_e32 v186, v186
	v_mul_f32_e32 v187, v106, v226
	v_rndne_f32_e32 v187, v187
	v_cvt_i32_f32_e32 v187, v187
	v_mul_f32_e32 v188, v110, v226
	v_rndne_f32_e32 v188, v188
	v_cvt_i32_f32_e32 v188, v188
	v_mul_f32_e32 v189, v114, v226
	v_rndne_f32_e32 v189, v189
	v_cvt_i32_f32_e32 v189, v189
	v_and_b32_e32 v186, 0xff, v186
	v_and_b32_e32 v187, 0xff, v187
	v_and_b32_e32 v188, 0xff, v188
	v_lshl_or_b32 v190, v187, 8, v186
	v_lshl_or_b32 v190, v188, 16, v190
	v_lshl_or_b32 v190, v189, 24, v190
	ds_write_b32 v139, v190 offset:384
	v_mul_f32_e32 v186, v103, v227
	v_rndne_f32_e32 v186, v186
	v_cvt_i32_f32_e32 v186, v186
	v_mul_f32_e32 v187, v107, v227
	v_rndne_f32_e32 v187, v187
	v_cvt_i32_f32_e32 v187, v187
	v_mul_f32_e32 v188, v111, v227
	v_rndne_f32_e32 v188, v188
	v_cvt_i32_f32_e32 v188, v188
	v_mul_f32_e32 v189, v115, v227
	v_rndne_f32_e32 v189, v189
	v_cvt_i32_f32_e32 v189, v189
	v_and_b32_e32 v186, 0xff, v186
	v_and_b32_e32 v187, 0xff, v187
	v_and_b32_e32 v188, 0xff, v188
	v_lshl_or_b32 v190, v187, 8, v186
	v_lshl_or_b32 v190, v188, 16, v190
	v_lshl_or_b32 v190, v189, 24, v190
	ds_write_b32 v139, v190 offset:896
	v_mul_f32_e32 v186, v104, v228
	v_rndne_f32_e32 v186, v186
	v_cvt_i32_f32_e32 v186, v186
	v_mul_f32_e32 v187, v108, v228
	v_rndne_f32_e32 v187, v187
	v_cvt_i32_f32_e32 v187, v187
	v_mul_f32_e32 v188, v112, v228
	v_rndne_f32_e32 v188, v188
	v_cvt_i32_f32_e32 v188, v188
	v_mul_f32_e32 v189, v116, v228
	v_rndne_f32_e32 v189, v189
	v_cvt_i32_f32_e32 v189, v189
	v_and_b32_e32 v186, 0xff, v186
	v_and_b32_e32 v187, 0xff, v187
	v_and_b32_e32 v188, 0xff, v188
	v_lshl_or_b32 v190, v187, 8, v186
	v_lshl_or_b32 v190, v188, 16, v190
	v_lshl_or_b32 v190, v189, 24, v190
	ds_write_b32 v139, v190 offset:1408
	v_mul_f32_e32 v186, v105, v229
	v_rndne_f32_e32 v186, v186
	v_cvt_i32_f32_e32 v186, v186
	v_mul_f32_e32 v187, v109, v229
	v_rndne_f32_e32 v187, v187
	v_cvt_i32_f32_e32 v187, v187
	v_mul_f32_e32 v188, v113, v229
	v_rndne_f32_e32 v188, v188
	v_cvt_i32_f32_e32 v188, v188
	v_mul_f32_e32 v189, v117, v229
	v_rndne_f32_e32 v189, v189
	v_cvt_i32_f32_e32 v189, v189
	v_and_b32_e32 v186, 0xff, v186
	v_and_b32_e32 v187, 0xff, v187
	v_and_b32_e32 v188, 0xff, v188
	v_lshl_or_b32 v190, v187, 8, v186
	v_lshl_or_b32 v190, v188, 16, v190
	v_lshl_or_b32 v190, v189, 24, v190
	ds_write_b32 v139, v190 offset:1920
	s_cmp_ge_u32 s10, 0x280
	s_cbranch_scc1 .Lc16_mixer_nopf_6
	global_load_dwordx4 v[102:105], v138, s[56:57]
	s_add_u32 s56, s56, 0xa000
	s_addc_u32 s57, s57, 0
	global_load_dwordx4 v[106:109], v138, s[56:57]
	s_add_u32 s56, s56, 0xa000
	s_addc_u32 s57, s57, 0
	global_load_dwordx4 v[110:113], v138, s[56:57]
	s_add_u32 s56, s56, 0xa000
	s_addc_u32 s57, s57, 0
	global_load_dwordx4 v[114:117], v138, s[56:57]
	s_add_u32 s56, s56, 0x262000
	s_addc_u32 s57, s57, 0
.Lc16_mixer_nopf_6:
	v_mul_f32_e32 v186, v118, v226
	v_rndne_f32_e32 v186, v186
	v_cvt_i32_f32_e32 v186, v186
	v_mul_f32_e32 v187, v122, v226
	v_rndne_f32_e32 v187, v187
	v_cvt_i32_f32_e32 v187, v187
	v_mul_f32_e32 v188, v126, v226
	v_rndne_f32_e32 v188, v188
	v_cvt_i32_f32_e32 v188, v188
	v_mul_f32_e32 v189, v130, v226
	v_rndne_f32_e32 v189, v189
	v_cvt_i32_f32_e32 v189, v189
	v_and_b32_e32 v186, 0xff, v186
	v_and_b32_e32 v187, 0xff, v187
	v_and_b32_e32 v188, 0xff, v188
	v_lshl_or_b32 v190, v187, 8, v186
	v_lshl_or_b32 v190, v188, 16, v190
	v_lshl_or_b32 v190, v189, 24, v190
	ds_write_b32 v139, v190 offset:448
	v_mul_f32_e32 v186, v119, v227
	v_rndne_f32_e32 v186, v186
	v_cvt_i32_f32_e32 v186, v186
	v_mul_f32_e32 v187, v123, v227
	v_rndne_f32_e32 v187, v187
	v_cvt_i32_f32_e32 v187, v187
	v_mul_f32_e32 v188, v127, v227
	v_rndne_f32_e32 v188, v188
	v_cvt_i32_f32_e32 v188, v188
	v_mul_f32_e32 v189, v131, v227
	v_rndne_f32_e32 v189, v189
	v_cvt_i32_f32_e32 v189, v189
	v_and_b32_e32 v186, 0xff, v186
	v_and_b32_e32 v187, 0xff, v187
	v_and_b32_e32 v188, 0xff, v188
	v_lshl_or_b32 v190, v187, 8, v186
	v_lshl_or_b32 v190, v188, 16, v190
	v_lshl_or_b32 v190, v189, 24, v190
	ds_write_b32 v139, v190 offset:960
	v_mul_f32_e32 v186, v120, v228
	v_rndne_f32_e32 v186, v186
	v_cvt_i32_f32_e32 v186, v186
	v_mul_f32_e32 v187, v124, v228
	v_rndne_f32_e32 v187, v187
	v_cvt_i32_f32_e32 v187, v187
	v_mul_f32_e32 v188, v128, v228
	v_rndne_f32_e32 v188, v188
	v_cvt_i32_f32_e32 v188, v188
	v_mul_f32_e32 v189, v132, v228
	v_rndne_f32_e32 v189, v189
	v_cvt_i32_f32_e32 v189, v189
	v_and_b32_e32 v186, 0xff, v186
	v_and_b32_e32 v187, 0xff, v187
	v_and_b32_e32 v188, 0xff, v188
	v_lshl_or_b32 v190, v187, 8, v186
	v_lshl_or_b32 v190, v188, 16, v190
	v_lshl_or_b32 v190, v189, 24, v190
	ds_write_b32 v139, v190 offset:1472
	v_mul_f32_e32 v186, v121, v229
	v_rndne_f32_e32 v186, v186
	v_cvt_i32_f32_e32 v186, v186
	v_mul_f32_e32 v187, v125, v229
	v_rndne_f32_e32 v187, v187
	v_cvt_i32_f32_e32 v187, v187
	v_mul_f32_e32 v188, v129, v229
	v_rndne_f32_e32 v188, v188
	v_cvt_i32_f32_e32 v188, v188
	v_mul_f32_e32 v189, v133, v229
	v_rndne_f32_e32 v189, v189
	v_cvt_i32_f32_e32 v189, v189
	v_and_b32_e32 v186, 0xff, v186
	v_and_b32_e32 v187, 0xff, v187
	v_and_b32_e32 v188, 0xff, v188
	v_lshl_or_b32 v190, v187, 8, v186
	v_lshl_or_b32 v190, v188, 16, v190
	v_lshl_or_b32 v190, v189, 24, v190
	ds_write_b32 v139, v190 offset:1984
	s_cmp_ge_u32 s10, 0x280
	s_cbranch_scc1 .Lc16_mixer_nopf_7
	global_load_dwordx4 v[118:121], v138, s[56:57]
	s_add_u32 s56, s56, 0xa000
	s_addc_u32 s57, s57, 0
	global_load_dwordx4 v[122:125], v138, s[56:57]
	s_add_u32 s56, s56, 0xa000
	s_addc_u32 s57, s57, 0
	global_load_dwordx4 v[126:129], v138, s[56:57]
	s_add_u32 s56, s56, 0xa000
	s_addc_u32 s57, s57, 0
	global_load_dwordx4 v[130:133], v138, s[56:57]
.Lc16_mixer_nopf_7:
	s_waitcnt lgkmcnt(0)
	s_lshl_b32 s3, s60, 12
	s_lshl_b32 s10, s1, 9
	s_add_u32 s3, s3, s10
	s_add_u32 s58, s34, s3
	s_addc_u32 s59, s35, 0
	s_add_u32 s58, s58, 0x100000
	s_addc_u32 s59, s59, 0
	ds_read_b128 v[204:207], v212 offset:0
	s_waitcnt lgkmcnt(0)
	global_store_dwordx4 v213, v[204:207], s[58:59]
	s_add_u32 s58, s58, 0x2000
	s_addc_u32 s59, s59, 0
	ds_read_b128 v[208:211], v212 offset:1024
	s_waitcnt lgkmcnt(0)
	global_store_dwordx4 v213, v[208:211], s[58:59]
	s_add_u32 s58, s58, 0x2000
	s_addc_u32 s59, s59, 0
	ds_read_b128 v[204:207], v212 offset:2048
	s_waitcnt lgkmcnt(0)
	global_store_dwordx4 v213, v[204:207], s[58:59]
	s_add_u32 s58, s58, 0x2000
	s_addc_u32 s59, s59, 0
	ds_read_b128 v[208:211], v212 offset:3072
	s_waitcnt lgkmcnt(0)
	global_store_dwordx4 v213, v[208:211], s[58:59]
	s_add_u32 s58, s58, 0x2000
	s_addc_u32 s59, s59, 0
	ds_read_b128 v[204:207], v212 offset:4096
	s_waitcnt lgkmcnt(0)
	global_store_dwordx4 v213, v[204:207], s[58:59]
	s_add_u32 s58, s58, 0x2000
	s_addc_u32 s59, s59, 0
	ds_read_b128 v[208:211], v212 offset:5120
	s_waitcnt lgkmcnt(0)
	global_store_dwordx4 v213, v[208:211], s[58:59]
	s_add_u32 s58, s58, 0x2000
	s_addc_u32 s59, s59, 0
	ds_read_b128 v[204:207], v212 offset:6144
	s_waitcnt lgkmcnt(0)
	global_store_dwordx4 v213, v[204:207], s[58:59]
	s_add_u32 s58, s58, 0x2000
	s_addc_u32 s59, s59, 0
	ds_read_b128 v[208:211], v212 offset:7168
	s_waitcnt lgkmcnt(0)
	global_store_dwordx4 v213, v[208:211], s[58:59]
	s_xor_b32 s11, s11, 1
	s_add_u32 s0, s0, s33
	s_cmp_lt_u32 s0, 0x280
	s_cbranch_scc1 .Lc16_mixer_loop

.LBB0_484:
	v_mbcnt_lo_u32_b32 v135, -1, 0
	v_mbcnt_hi_u32_b32 v135, -1, v135
	v_lshrrev_b32_e32 v136, 2, v135
	v_and_b32_e32 v137, 3, v135
	v_lshlrev_b32_e32 v230, 4, v137
	v_readlane_b32 s7, v254, 17
	v_readlane_b32 s1, v254, 16
	v_readlane_b32 s13, v254, 15
	s_mov_b32 s11, 0x42fe0000
	s_mov_b32 s5, 0
	v_lshlrev_b32_e32 v139, 11, v137
	v_lshl_add_u32 v139, v136, 2, v139
	s_nop 1
	v_add_u32_e32 v139, s7, v139
	v_lshlrev_b32_e32 v174, 2, v135
	v_xor_b32_e32 v192, 0x10, v174
	v_xor_b32_e32 v193, 0x20, v174
	v_xor_b32_e32 v194, 0x40, v174
	v_xor_b32_e32 v195, 0x80, v174
	v_lshrrev_b32_e32 v175, 5, v135
	v_and_b32_e32 v176, 31, v135
	v_lshlrev_b32_e32 v212, 9, v175
	v_lshl_add_u32 v212, v176, 4, v212
	v_add_u32_e32 v212, s7, v212
	v_lshlrev_b32_e32 v213, 12, v175
	v_lshl_add_u32 v213, v176, 4, v213
	v_readlane_b32 s52, v255, 61
	v_readlane_b32 s53, v255, 62
	v_mul_u32_u24_e32 v138, 0x56000, v136
	v_lshl_add_u32 v138, v137, 4, v138
	s_mul_i32 s3, s1, 0x2b00000
	s_nop 1
	s_add_u32 s52, s52, s3
	s_addc_u32 s53, s53, 0
	s_mov_b32 s0, s13
	s_cmp_ge_u32 s0, 0x560
	s_cbranch_scc1 .Lc16p3_ffn2_done
	s_lshl_b32 s3, s0, 6
	s_add_u32 s54, s52, s3
	s_addc_u32 s55, s53, 0
	global_load_dwordx4 v[6:9], v138, s[54:55] nt
	s_add_u32 s54, s54, 0x15800
	s_addc_u32 s55, s55, 0
	global_load_dwordx4 v[10:13], v138, s[54:55] nt
	s_add_u32 s54, s54, 0x15800
	s_addc_u32 s55, s55, 0
	global_load_dwordx4 v[14:17], v138, s[54:55] nt
	s_add_u32 s54, s54, 0x15800
	s_addc_u32 s55, s55, 0
	global_load_dwordx4 v[18:21], v138, s[54:55] nt
	s_add_u32 s54, s54, 0x51f800
	s_addc_u32 s55, s55, 0
	global_load_dwordx4 v[22:25], v138, s[54:55] nt
	s_add_u32 s54, s54, 0x15800
	s_addc_u32 s55, s55, 0
	global_load_dwordx4 v[26:29], v138, s[54:55] nt
	s_add_u32 s54, s54, 0x15800
	s_addc_u32 s55, s55, 0
	global_load_dwordx4 v[30:33], v138, s[54:55] nt
	s_add_u32 s54, s54, 0x15800
	s_addc_u32 s55, s55, 0
	global_load_dwordx4 v[34:37], v138, s[54:55] nt
	s_add_u32 s54, s54, 0x51f800
	s_addc_u32 s55, s55, 0
	global_load_dwordx4 v[38:41], v138, s[54:55] nt
	s_add_u32 s54, s54, 0x15800
	s_addc_u32 s55, s55, 0
	global_load_dwordx4 v[42:45], v138, s[54:55] nt
	s_add_u32 s54, s54, 0x15800
	s_addc_u32 s55, s55, 0
	global_load_dwordx4 v[46:49], v138, s[54:55] nt
	s_add_u32 s54, s54, 0x15800
	s_addc_u32 s55, s55, 0
	global_load_dwordx4 v[50:53], v138, s[54:55] nt
	s_add_u32 s54, s54, 0x51f800
	s_addc_u32 s55, s55, 0
	global_load_dwordx4 v[54:57], v138, s[54:55] nt
	s_add_u32 s54, s54, 0x15800
	s_addc_u32 s55, s55, 0
	global_load_dwordx4 v[58:61], v138, s[54:55] nt
	s_add_u32 s54, s54, 0x15800
	s_addc_u32 s55, s55, 0
	global_load_dwordx4 v[62:65], v138, s[54:55] nt
	s_add_u32 s54, s54, 0x15800
	s_addc_u32 s55, s55, 0
	global_load_dwordx4 v[66:69], v138, s[54:55] nt
	s_add_u32 s54, s54, 0x51f800
	s_addc_u32 s55, s55, 0
	global_load_dwordx4 v[70:73], v138, s[54:55] nt
	s_add_u32 s54, s54, 0x15800
	s_addc_u32 s55, s55, 0
	global_load_dwordx4 v[74:77], v138, s[54:55] nt
	s_add_u32 s54, s54, 0x15800
	s_addc_u32 s55, s55, 0
	global_load_dwordx4 v[78:81], v138, s[54:55] nt
	s_add_u32 s54, s54, 0x15800
	s_addc_u32 s55, s55, 0
	global_load_dwordx4 v[82:85], v138, s[54:55] nt
	s_add_u32 s54, s54, 0x51f800
	s_addc_u32 s55, s55, 0
	global_load_dwordx4 v[86:89], v138, s[54:55] nt
	s_add_u32 s54, s54, 0x15800
	s_addc_u32 s55, s55, 0
	global_load_dwordx4 v[90:93], v138, s[54:55] nt
	s_add_u32 s54, s54, 0x15800
	s_addc_u32 s55, s55, 0
	global_load_dwordx4 v[94:97], v138, s[54:55] nt
	s_add_u32 s54, s54, 0x15800
	s_addc_u32 s55, s55, 0
	global_load_dwordx4 v[98:101], v138, s[54:55] nt
	s_add_u32 s54, s54, 0x51f800
	s_addc_u32 s55, s55, 0
	global_load_dwordx4 v[102:105], v138, s[54:55] nt
	s_add_u32 s54, s54, 0x15800
	s_addc_u32 s55, s55, 0
	global_load_dwordx4 v[106:109], v138, s[54:55] nt
	s_add_u32 s54, s54, 0x15800
	s_addc_u32 s55, s55, 0
	global_load_dwordx4 v[110:113], v138, s[54:55] nt
	s_add_u32 s54, s54, 0x15800
	s_addc_u32 s55, s55, 0
	global_load_dwordx4 v[114:117], v138, s[54:55] nt
	s_add_u32 s54, s54, 0x51f800
	s_addc_u32 s55, s55, 0
	global_load_dwordx4 v[118:121], v138, s[54:55] nt
	s_add_u32 s54, s54, 0x15800
	s_addc_u32 s55, s55, 0
	global_load_dwordx4 v[122:125], v138, s[54:55] nt
	s_add_u32 s54, s54, 0x15800
	s_addc_u32 s55, s55, 0
	global_load_dwordx4 v[126:129], v138, s[54:55] nt
	s_add_u32 s54, s54, 0x15800
	s_addc_u32 s55, s55, 0
	global_load_dwordx4 v[130:133], v138, s[54:55] nt
.Lc16p3_ffn2_loop:
	s_lshl_b32 s2, s0, 4
	s_cmp_ge_u32 s2, 0x2b00
	s_cselect_b32 s12, 128, 0
	s_cselect_b32 s3, 0x2b00, 0
	s_sub_u32 s3, s2, s3
	s_lshr_b32 s6, s3, 7
	s_lshl_b32 s6, s6, 8
	s_and_b32 s3, s3, 127
	s_add_u32 s6, s6, s3
	s_add_u32 s6, s6, s12
	s_lshl_b32 s10, s5, 9
	s_add_u32 s10, s10, 0x21000
	s_lshl_b32 s3, s1, 6
	s_add_u32 s3, s3, s10
	v_add_u32_e32 v172, s3, v230
	v_add_u32_e32 v173, s10, v230
	s_waitcnt vmcnt(0)
	v_max3_f32 v216, |v6|, |v10|, |v14|
	v_max3_f32 v216, v216, |v18|, |v22|
	v_max3_f32 v216, v216, |v26|, |v30|
	v_max3_f32 v216, v216, |v34|, |v38|
	v_max3_f32 v216, v216, |v42|, |v46|
	v_max3_f32 v216, v216, |v50|, |v54|
	v_max3_f32 v216, v216, |v58|, |v62|
	v_max3_f32 v216, v216, |v66|, |v70|
	v_max3_f32 v216, v216, |v74|, |v78|
	v_max3_f32 v216, v216, |v82|, |v86|
	v_max3_f32 v216, v216, |v90|, |v94|
	v_max3_f32 v216, v216, |v98|, |v102|
	v_max3_f32 v216, v216, |v106|, |v110|
	v_max3_f32 v216, v216, |v114|, |v118|
	v_max3_f32 v216, v216, |v122|, |v126|
	v_max_f32_e64 v216, v216, |v130|
	v_max3_f32 v217, |v7|, |v11|, |v15|
	v_max3_f32 v217, v217, |v19|, |v23|
	v_max3_f32 v217, v217, |v27|, |v31|
	v_max3_f32 v217, v217, |v35|, |v39|
	v_max3_f32 v217, v217, |v43|, |v47|
	v_max3_f32 v217, v217, |v51|, |v55|
	v_max3_f32 v217, v217, |v59|, |v63|
	v_max3_f32 v217, v217, |v67|, |v71|
	v_max3_f32 v217, v217, |v75|, |v79|
	v_max3_f32 v217, v217, |v83|, |v87|
	v_max3_f32 v217, v217, |v91|, |v95|
	v_max3_f32 v217, v217, |v99|, |v103|
	v_max3_f32 v217, v217, |v107|, |v111|
	v_max3_f32 v217, v217, |v115|, |v119|
	v_max3_f32 v217, v217, |v123|, |v127|
	v_max_f32_e64 v217, v217, |v131|
	v_max3_f32 v218, |v8|, |v12|, |v16|
	v_max3_f32 v218, v218, |v20|, |v24|
	v_max3_f32 v218, v218, |v28|, |v32|
	v_max3_f32 v218, v218, |v36|, |v40|
	v_max3_f32 v218, v218, |v44|, |v48|
	v_max3_f32 v218, v218, |v52|, |v56|
	v_max3_f32 v218, v218, |v60|, |v64|
	v_max3_f32 v218, v218, |v68|, |v72|
	v_max3_f32 v218, v218, |v76|, |v80|
	v_max3_f32 v218, v218, |v84|, |v88|
	v_max3_f32 v218, v218, |v92|, |v96|
	v_max3_f32 v218, v218, |v100|, |v104|
	v_max3_f32 v218, v218, |v108|, |v112|
	v_max3_f32 v218, v218, |v116|, |v120|
	v_max3_f32 v218, v218, |v124|, |v128|
	v_max_f32_e64 v218, v218, |v132|
	v_max3_f32 v219, |v9|, |v13|, |v17|
	v_max3_f32 v219, v219, |v21|, |v25|
	v_max3_f32 v219, v219, |v29|, |v33|
	v_max3_f32 v219, v219, |v37|, |v41|
	v_max3_f32 v219, v219, |v45|, |v49|
	v_max3_f32 v219, v219, |v53|, |v57|
	v_max3_f32 v219, v219, |v61|, |v65|
	v_max3_f32 v219, v219, |v69|, |v73|
	v_max3_f32 v219, v219, |v77|, |v81|
	v_max3_f32 v219, v219, |v85|, |v89|
	v_max3_f32 v219, v219, |v93|, |v97|
	v_max3_f32 v219, v219, |v101|, |v105|
	v_max3_f32 v219, v219, |v109|, |v113|
	v_max3_f32 v219, v219, |v117|, |v121|
	v_max3_f32 v219, v219, |v125|, |v129|
	v_max_f32_e64 v219, v219, |v133|
	ds_bpermute_b32 v174, v192, v216
	ds_bpermute_b32 v175, v192, v217
	ds_bpermute_b32 v176, v192, v218
	ds_bpermute_b32 v177, v192, v219
	s_waitcnt lgkmcnt(0)
	v_max_f32_e32 v216, v216, v174
	v_max_f32_e32 v217, v217, v175
	v_max_f32_e32 v218, v218, v176
	v_max_f32_e32 v219, v219, v177
	ds_bpermute_b32 v174, v193, v216
	ds_bpermute_b32 v175, v193, v217
	ds_bpermute_b32 v176, v193, v218
	ds_bpermute_b32 v177, v193, v219
	s_waitcnt lgkmcnt(0)
	v_max_f32_e32 v216, v216, v174
	v_max_f32_e32 v217, v217, v175
	v_max_f32_e32 v218, v218, v176
	v_max_f32_e32 v219, v219, v177
	ds_bpermute_b32 v174, v194, v216
	ds_bpermute_b32 v175, v194, v217
	ds_bpermute_b32 v176, v194, v218
	ds_bpermute_b32 v177, v194, v219
	s_waitcnt lgkmcnt(0)
	v_max_f32_e32 v216, v216, v174
	v_max_f32_e32 v217, v217, v175
	v_max_f32_e32 v218, v218, v176
	v_max_f32_e32 v219, v219, v177
	ds_bpermute_b32 v174, v195, v216
	ds_bpermute_b32 v175, v195, v217
	ds_bpermute_b32 v176, v195, v218
	ds_bpermute_b32 v177, v195, v219
	s_waitcnt lgkmcnt(0)
	v_max_f32_e32 v216, v216, v174
	v_max_f32_e32 v217, v217, v175
	v_max_f32_e32 v218, v218, v176
	v_max_f32_e32 v219, v219, v177
	s_mov_b64 s[58:59], exec
	s_mov_b64 exec, 15
	ds_write_b128 v172, v[216:219]
	s_mov_b64 exec, s[58:59]
	s_waitcnt lgkmcnt(0)
	s_barrier
	ds_read_b128 v[140:143], v173 offset:0
	ds_read_b128 v[144:147], v173 offset:64
	ds_read_b128 v[148:151], v173 offset:128
	ds_read_b128 v[152:155], v173 offset:192
	ds_read_b128 v[156:159], v173 offset:256
	ds_read_b128 v[160:163], v173 offset:320
	ds_read_b128 v[164:167], v173 offset:384
	ds_read_b128 v[232:235], v173 offset:448
	s_waitcnt lgkmcnt(0)
	v_max3_f32 v220, v140, v144, v148
	v_max3_f32 v220, v220, v152, v156
	v_max3_f32 v220, v220, v160, v164
	v_max_f32_e32 v220, v220, v232
	v_max3_f32 v221, v141, v145, v149
	v_max3_f32 v221, v221, v153, v157
	v_max3_f32 v221, v221, v161, v165
	v_max_f32_e32 v221, v221, v233
	v_max3_f32 v222, v142, v146, v150
	v_max3_f32 v222, v222, v154, v158
	v_max3_f32 v222, v222, v162, v166
	v_max_f32_e32 v222, v222, v234
	v_max3_f32 v223, v143, v147, v151
	v_max3_f32 v223, v223, v155, v159
	v_max3_f32 v223, v223, v163, v167
	v_max_f32_e32 v223, v223, v235
	s_cmp_lg_u32 s1, 0
	s_cbranch_scc1 .Lc16p3_ffn2_nocm
	s_lshl_b32 s3, s2, 2
	s_add_u32 s54, s34, s3
	s_addc_u32 s55, s35, 0
	s_add_u32 s54, s54, 0x60000
	s_addc_u32 s55, s55, 0
	s_mov_b64 s[58:59], exec
	s_mov_b64 exec, 15
	global_store_dwordx4 v230, v[220:223], s[54:55]
	s_mov_b64 exec, s[58:59]
.Lc16p3_ffn2_nocm:
	v_div_scale_f32 v175, s[58:59], v220, v220, s11
	v_rcp_f32_e32 v176, v175
	s_nop 0
	v_fma_f32 v177, -v175, v176, 1.0
	v_fmac_f32_e32 v176, v177, v176
	v_div_scale_f32 v177, vcc, s11, v220, s11
	v_mul_f32_e32 v178, v177, v176
	v_fma_f32 v180, -v175, v178, v177
	v_fmac_f32_e32 v178, v180, v176
	v_fma_f32 v175, -v175, v178, v177
	s_nop 0
	v_div_fmas_f32 v175, v175, v176, v178
	v_div_fixup_f32 v175, v175, v220, s11
	v_cmp_lt_f32_e32 vcc, 0, v220
	s_nop 1
	v_cndmask_b32_e32 v226, 0, v175, vcc
	v_div_scale_f32 v175, s[58:59], v221, v221, s11
	v_rcp_f32_e32 v176, v175
	s_nop 0
	v_fma_f32 v177, -v175, v176, 1.0
	v_fmac_f32_e32 v176, v177, v176
	v_div_scale_f32 v177, vcc, s11, v221, s11
	v_mul_f32_e32 v178, v177, v176
	v_fma_f32 v180, -v175, v178, v177
	v_fmac_f32_e32 v178, v180, v176
	v_fma_f32 v175, -v175, v178, v177
	s_nop 0
	v_div_fmas_f32 v175, v175, v176, v178
	v_div_fixup_f32 v175, v175, v221, s11
	v_cmp_lt_f32_e32 vcc, 0, v221
	s_nop 1
	v_cndmask_b32_e32 v227, 0, v175, vcc
	v_div_scale_f32 v175, s[58:59], v222, v222, s11
	v_rcp_f32_e32 v176, v175
	s_nop 0
	v_fma_f32 v177, -v175, v176, 1.0
	v_fmac_f32_e32 v176, v177, v176
	v_div_scale_f32 v177, vcc, s11, v222, s11
	v_mul_f32_e32 v178, v177, v176
	v_fma_f32 v180, -v175, v178, v177
	v_fmac_f32_e32 v178, v180, v176
	v_fma_f32 v175, -v175, v178, v177
	s_nop 0
	v_div_fmas_f32 v175, v175, v176, v178
	v_div_fixup_f32 v175, v175, v222, s11
	v_cmp_lt_f32_e32 vcc, 0, v222
	s_nop 1
	v_cndmask_b32_e32 v228, 0, v175, vcc
	v_div_scale_f32 v175, s[58:59], v223, v223, s11
	v_rcp_f32_e32 v176, v175
	s_nop 0
	v_fma_f32 v177, -v175, v176, 1.0
	v_fmac_f32_e32 v176, v177, v176
	v_div_scale_f32 v177, vcc, s11, v223, s11
	v_mul_f32_e32 v178, v177, v176
	v_fma_f32 v180, -v175, v178, v177
	v_fmac_f32_e32 v178, v180, v176
	v_fma_f32 v175, -v175, v178, v177
	s_nop 0
	v_div_fmas_f32 v175, v175, v176, v178
	v_div_fixup_f32 v175, v175, v223, s11
	v_cmp_lt_f32_e32 vcc, 0, v223
	s_nop 1
	v_cndmask_b32_e32 v229, 0, v175, vcc
	s_add_u32 s4, s0, s33
	s_lshl_b32 s3, s4, 6
	s_add_u32 s54, s52, s3
	s_addc_u32 s55, s53, 0
	v_mul_f32_e32 v186, v6, v226
	v_rndne_f32_e32 v186, v186
	v_cvt_i32_f32_e32 v186, v186
	v_mul_f32_e32 v187, v10, v226
	v_rndne_f32_e32 v187, v187
	v_cvt_i32_f32_e32 v187, v187
	v_mul_f32_e32 v188, v14, v226
	v_rndne_f32_e32 v188, v188
	v_cvt_i32_f32_e32 v188, v188
	v_mul_f32_e32 v189, v18, v226
	v_rndne_f32_e32 v189, v189
	v_cvt_i32_f32_e32 v189, v189
	v_and_b32_e32 v186, 0xff, v186
	v_and_b32_e32 v187, 0xff, v187
	v_and_b32_e32 v188, 0xff, v188
	v_lshl_or_b32 v190, v187, 8, v186
	v_lshl_or_b32 v190, v188, 16, v190
	v_lshl_or_b32 v190, v189, 24, v190
	ds_write_b32 v139, v190 offset:0
	v_mul_f32_e32 v186, v7, v227
	v_rndne_f32_e32 v186, v186
	v_cvt_i32_f32_e32 v186, v186
	v_mul_f32_e32 v187, v11, v227
	v_rndne_f32_e32 v187, v187
	v_cvt_i32_f32_e32 v187, v187
	v_mul_f32_e32 v188, v15, v227
	v_rndne_f32_e32 v188, v188
	v_cvt_i32_f32_e32 v188, v188
	v_mul_f32_e32 v189, v19, v227
	v_rndne_f32_e32 v189, v189
	v_cvt_i32_f32_e32 v189, v189
	v_and_b32_e32 v186, 0xff, v186
	v_and_b32_e32 v187, 0xff, v187
	v_and_b32_e32 v188, 0xff, v188
	v_lshl_or_b32 v190, v187, 8, v186
	v_lshl_or_b32 v190, v188, 16, v190
	v_lshl_or_b32 v190, v189, 24, v190
	ds_write_b32 v139, v190 offset:512
	v_mul_f32_e32 v186, v8, v228
	v_rndne_f32_e32 v186, v186
	v_cvt_i32_f32_e32 v186, v186
	v_mul_f32_e32 v187, v12, v228
	v_rndne_f32_e32 v187, v187
	v_cvt_i32_f32_e32 v187, v187
	v_mul_f32_e32 v188, v16, v228
	v_rndne_f32_e32 v188, v188
	v_cvt_i32_f32_e32 v188, v188
	v_mul_f32_e32 v189, v20, v228
	v_rndne_f32_e32 v189, v189
	v_cvt_i32_f32_e32 v189, v189
	v_and_b32_e32 v186, 0xff, v186
	v_and_b32_e32 v187, 0xff, v187
	v_and_b32_e32 v188, 0xff, v188
	v_lshl_or_b32 v190, v187, 8, v186
	v_lshl_or_b32 v190, v188, 16, v190
	v_lshl_or_b32 v190, v189, 24, v190
	ds_write_b32 v139, v190 offset:1024
	v_mul_f32_e32 v186, v9, v229
	v_rndne_f32_e32 v186, v186
	v_cvt_i32_f32_e32 v186, v186
	v_mul_f32_e32 v187, v13, v229
	v_rndne_f32_e32 v187, v187
	v_cvt_i32_f32_e32 v187, v187
	v_mul_f32_e32 v188, v17, v229
	v_rndne_f32_e32 v188, v188
	v_cvt_i32_f32_e32 v188, v188
	v_mul_f32_e32 v189, v21, v229
	v_rndne_f32_e32 v189, v189
	v_cvt_i32_f32_e32 v189, v189
	v_and_b32_e32 v186, 0xff, v186
	v_and_b32_e32 v187, 0xff, v187
	v_and_b32_e32 v188, 0xff, v188
	v_lshl_or_b32 v190, v187, 8, v186
	v_lshl_or_b32 v190, v188, 16, v190
	v_lshl_or_b32 v190, v189, 24, v190
	ds_write_b32 v139, v190 offset:1536
	s_cmp_ge_u32 s4, 0x560
	s_cbranch_scc1 .Lc16p3_ffn2_nopf_0
	global_load_dwordx4 v[6:9], v138, s[54:55] nt
	s_add_u32 s54, s54, 0x15800
	s_addc_u32 s55, s55, 0
	global_load_dwordx4 v[10:13], v138, s[54:55] nt
	s_add_u32 s54, s54, 0x15800
	s_addc_u32 s55, s55, 0
	global_load_dwordx4 v[14:17], v138, s[54:55] nt
	s_add_u32 s54, s54, 0x15800
	s_addc_u32 s55, s55, 0
	global_load_dwordx4 v[18:21], v138, s[54:55] nt
	s_add_u32 s54, s54, 0x51f800
	s_addc_u32 s55, s55, 0
.Lc16p3_ffn2_nopf_0:
	v_mul_f32_e32 v186, v22, v226
	v_rndne_f32_e32 v186, v186
	v_cvt_i32_f32_e32 v186, v186
	v_mul_f32_e32 v187, v26, v226
	v_rndne_f32_e32 v187, v187
	v_cvt_i32_f32_e32 v187, v187
	v_mul_f32_e32 v188, v30, v226
	v_rndne_f32_e32 v188, v188
	v_cvt_i32_f32_e32 v188, v188
	v_mul_f32_e32 v189, v34, v226
	v_rndne_f32_e32 v189, v189
	v_cvt_i32_f32_e32 v189, v189
	v_and_b32_e32 v186, 0xff, v186
	v_and_b32_e32 v187, 0xff, v187
	v_and_b32_e32 v188, 0xff, v188
	v_lshl_or_b32 v190, v187, 8, v186
	v_lshl_or_b32 v190, v188, 16, v190
	v_lshl_or_b32 v190, v189, 24, v190
	ds_write_b32 v139, v190 offset:64
	v_mul_f32_e32 v186, v23, v227
	v_rndne_f32_e32 v186, v186
	v_cvt_i32_f32_e32 v186, v186
	v_mul_f32_e32 v187, v27, v227
	v_rndne_f32_e32 v187, v187
	v_cvt_i32_f32_e32 v187, v187
	v_mul_f32_e32 v188, v31, v227
	v_rndne_f32_e32 v188, v188
	v_cvt_i32_f32_e32 v188, v188
	v_mul_f32_e32 v189, v35, v227
	v_rndne_f32_e32 v189, v189
	v_cvt_i32_f32_e32 v189, v189
	v_and_b32_e32 v186, 0xff, v186
	v_and_b32_e32 v187, 0xff, v187
	v_and_b32_e32 v188, 0xff, v188
	v_lshl_or_b32 v190, v187, 8, v186
	v_lshl_or_b32 v190, v188, 16, v190
	v_lshl_or_b32 v190, v189, 24, v190
	ds_write_b32 v139, v190 offset:576
	v_mul_f32_e32 v186, v24, v228
	v_rndne_f32_e32 v186, v186
	v_cvt_i32_f32_e32 v186, v186
	v_mul_f32_e32 v187, v28, v228
	v_rndne_f32_e32 v187, v187
	v_cvt_i32_f32_e32 v187, v187
	v_mul_f32_e32 v188, v32, v228
	v_rndne_f32_e32 v188, v188
	v_cvt_i32_f32_e32 v188, v188
	v_mul_f32_e32 v189, v36, v228
	v_rndne_f32_e32 v189, v189
	v_cvt_i32_f32_e32 v189, v189
	v_and_b32_e32 v186, 0xff, v186
	v_and_b32_e32 v187, 0xff, v187
	v_and_b32_e32 v188, 0xff, v188
	v_lshl_or_b32 v190, v187, 8, v186
	v_lshl_or_b32 v190, v188, 16, v190
	v_lshl_or_b32 v190, v189, 24, v190
	ds_write_b32 v139, v190 offset:1088
	v_mul_f32_e32 v186, v25, v229
	v_rndne_f32_e32 v186, v186
	v_cvt_i32_f32_e32 v186, v186
	v_mul_f32_e32 v187, v29, v229
	v_rndne_f32_e32 v187, v187
	v_cvt_i32_f32_e32 v187, v187
	v_mul_f32_e32 v188, v33, v229
	v_rndne_f32_e32 v188, v188
	v_cvt_i32_f32_e32 v188, v188
	v_mul_f32_e32 v189, v37, v229
	v_rndne_f32_e32 v189, v189
	v_cvt_i32_f32_e32 v189, v189
	v_and_b32_e32 v186, 0xff, v186
	v_and_b32_e32 v187, 0xff, v187
	v_and_b32_e32 v188, 0xff, v188
	v_lshl_or_b32 v190, v187, 8, v186
	v_lshl_or_b32 v190, v188, 16, v190
	v_lshl_or_b32 v190, v189, 24, v190
	ds_write_b32 v139, v190 offset:1600
	s_cmp_ge_u32 s4, 0x560
	s_cbranch_scc1 .Lc16p3_ffn2_nopf_1
	global_load_dwordx4 v[22:25], v138, s[54:55] nt
	s_add_u32 s54, s54, 0x15800
	s_addc_u32 s55, s55, 0
	global_load_dwordx4 v[26:29], v138, s[54:55] nt
	s_add_u32 s54, s54, 0x15800
	s_addc_u32 s55, s55, 0
	global_load_dwordx4 v[30:33], v138, s[54:55] nt
	s_add_u32 s54, s54, 0x15800
	s_addc_u32 s55, s55, 0
	global_load_dwordx4 v[34:37], v138, s[54:55] nt
	s_add_u32 s54, s54, 0x51f800
	s_addc_u32 s55, s55, 0
.Lc16p3_ffn2_nopf_1:
	v_mul_f32_e32 v186, v38, v226
	v_rndne_f32_e32 v186, v186
	v_cvt_i32_f32_e32 v186, v186
	v_mul_f32_e32 v187, v42, v226
	v_rndne_f32_e32 v187, v187
	v_cvt_i32_f32_e32 v187, v187
	v_mul_f32_e32 v188, v46, v226
	v_rndne_f32_e32 v188, v188
	v_cvt_i32_f32_e32 v188, v188
	v_mul_f32_e32 v189, v50, v226
	v_rndne_f32_e32 v189, v189
	v_cvt_i32_f32_e32 v189, v189
	v_and_b32_e32 v186, 0xff, v186
	v_and_b32_e32 v187, 0xff, v187
	v_and_b32_e32 v188, 0xff, v188
	v_lshl_or_b32 v190, v187, 8, v186
	v_lshl_or_b32 v190, v188, 16, v190
	v_lshl_or_b32 v190, v189, 24, v190
	ds_write_b32 v139, v190 offset:128
	v_mul_f32_e32 v186, v39, v227
	v_rndne_f32_e32 v186, v186
	v_cvt_i32_f32_e32 v186, v186
	v_mul_f32_e32 v187, v43, v227
	v_rndne_f32_e32 v187, v187
	v_cvt_i32_f32_e32 v187, v187
	v_mul_f32_e32 v188, v47, v227
	v_rndne_f32_e32 v188, v188
	v_cvt_i32_f32_e32 v188, v188
	v_mul_f32_e32 v189, v51, v227
	v_rndne_f32_e32 v189, v189
	v_cvt_i32_f32_e32 v189, v189
	v_and_b32_e32 v186, 0xff, v186
	v_and_b32_e32 v187, 0xff, v187
	v_and_b32_e32 v188, 0xff, v188
	v_lshl_or_b32 v190, v187, 8, v186
	v_lshl_or_b32 v190, v188, 16, v190
	v_lshl_or_b32 v190, v189, 24, v190
	ds_write_b32 v139, v190 offset:640
	v_mul_f32_e32 v186, v40, v228
	v_rndne_f32_e32 v186, v186
	v_cvt_i32_f32_e32 v186, v186
	v_mul_f32_e32 v187, v44, v228
	v_rndne_f32_e32 v187, v187
	v_cvt_i32_f32_e32 v187, v187
	v_mul_f32_e32 v188, v48, v228
	v_rndne_f32_e32 v188, v188
	v_cvt_i32_f32_e32 v188, v188
	v_mul_f32_e32 v189, v52, v228
	v_rndne_f32_e32 v189, v189
	v_cvt_i32_f32_e32 v189, v189
	v_and_b32_e32 v186, 0xff, v186
	v_and_b32_e32 v187, 0xff, v187
	v_and_b32_e32 v188, 0xff, v188
	v_lshl_or_b32 v190, v187, 8, v186
	v_lshl_or_b32 v190, v188, 16, v190
	v_lshl_or_b32 v190, v189, 24, v190
	ds_write_b32 v139, v190 offset:1152
	v_mul_f32_e32 v186, v41, v229
	v_rndne_f32_e32 v186, v186
	v_cvt_i32_f32_e32 v186, v186
	v_mul_f32_e32 v187, v45, v229
	v_rndne_f32_e32 v187, v187
	v_cvt_i32_f32_e32 v187, v187
	v_mul_f32_e32 v188, v49, v229
	v_rndne_f32_e32 v188, v188
	v_cvt_i32_f32_e32 v188, v188
	v_mul_f32_e32 v189, v53, v229
	v_rndne_f32_e32 v189, v189
	v_cvt_i32_f32_e32 v189, v189
	v_and_b32_e32 v186, 0xff, v186
	v_and_b32_e32 v187, 0xff, v187
	v_and_b32_e32 v188, 0xff, v188
	v_lshl_or_b32 v190, v187, 8, v186
	v_lshl_or_b32 v190, v188, 16, v190
	v_lshl_or_b32 v190, v189, 24, v190
	ds_write_b32 v139, v190 offset:1664
	s_cmp_ge_u32 s4, 0x560
	s_cbranch_scc1 .Lc16p3_ffn2_nopf_2
	global_load_dwordx4 v[38:41], v138, s[54:55] nt
	s_add_u32 s54, s54, 0x15800
	s_addc_u32 s55, s55, 0
	global_load_dwordx4 v[42:45], v138, s[54:55] nt
	s_add_u32 s54, s54, 0x15800
	s_addc_u32 s55, s55, 0
	global_load_dwordx4 v[46:49], v138, s[54:55] nt
	s_add_u32 s54, s54, 0x15800
	s_addc_u32 s55, s55, 0
	global_load_dwordx4 v[50:53], v138, s[54:55] nt
	s_add_u32 s54, s54, 0x51f800
	s_addc_u32 s55, s55, 0
.Lc16p3_ffn2_nopf_2:
	v_mul_f32_e32 v186, v54, v226
	v_rndne_f32_e32 v186, v186
	v_cvt_i32_f32_e32 v186, v186
	v_mul_f32_e32 v187, v58, v226
	v_rndne_f32_e32 v187, v187
	v_cvt_i32_f32_e32 v187, v187
	v_mul_f32_e32 v188, v62, v226
	v_rndne_f32_e32 v188, v188
	v_cvt_i32_f32_e32 v188, v188
	v_mul_f32_e32 v189, v66, v226
	v_rndne_f32_e32 v189, v189
	v_cvt_i32_f32_e32 v189, v189
	v_and_b32_e32 v186, 0xff, v186
	v_and_b32_e32 v187, 0xff, v187
	v_and_b32_e32 v188, 0xff, v188
	v_lshl_or_b32 v190, v187, 8, v186
	v_lshl_or_b32 v190, v188, 16, v190
	v_lshl_or_b32 v190, v189, 24, v190
	ds_write_b32 v139, v190 offset:192
	v_mul_f32_e32 v186, v55, v227
	v_rndne_f32_e32 v186, v186
	v_cvt_i32_f32_e32 v186, v186
	v_mul_f32_e32 v187, v59, v227
	v_rndne_f32_e32 v187, v187
	v_cvt_i32_f32_e32 v187, v187
	v_mul_f32_e32 v188, v63, v227
	v_rndne_f32_e32 v188, v188
	v_cvt_i32_f32_e32 v188, v188
	v_mul_f32_e32 v189, v67, v227
	v_rndne_f32_e32 v189, v189
	v_cvt_i32_f32_e32 v189, v189
	v_and_b32_e32 v186, 0xff, v186
	v_and_b32_e32 v187, 0xff, v187
	v_and_b32_e32 v188, 0xff, v188
	v_lshl_or_b32 v190, v187, 8, v186
	v_lshl_or_b32 v190, v188, 16, v190
	v_lshl_or_b32 v190, v189, 24, v190
	ds_write_b32 v139, v190 offset:704
	v_mul_f32_e32 v186, v56, v228
	v_rndne_f32_e32 v186, v186
	v_cvt_i32_f32_e32 v186, v186
	v_mul_f32_e32 v187, v60, v228
	v_rndne_f32_e32 v187, v187
	v_cvt_i32_f32_e32 v187, v187
	v_mul_f32_e32 v188, v64, v228
	v_rndne_f32_e32 v188, v188
	v_cvt_i32_f32_e32 v188, v188
	v_mul_f32_e32 v189, v68, v228
	v_rndne_f32_e32 v189, v189
	v_cvt_i32_f32_e32 v189, v189
	v_and_b32_e32 v186, 0xff, v186
	v_and_b32_e32 v187, 0xff, v187
	v_and_b32_e32 v188, 0xff, v188
	v_lshl_or_b32 v190, v187, 8, v186
	v_lshl_or_b32 v190, v188, 16, v190
	v_lshl_or_b32 v190, v189, 24, v190
	ds_write_b32 v139, v190 offset:1216
	v_mul_f32_e32 v186, v57, v229
	v_rndne_f32_e32 v186, v186
	v_cvt_i32_f32_e32 v186, v186
	v_mul_f32_e32 v187, v61, v229
	v_rndne_f32_e32 v187, v187
	v_cvt_i32_f32_e32 v187, v187
	v_mul_f32_e32 v188, v65, v229
	v_rndne_f32_e32 v188, v188
	v_cvt_i32_f32_e32 v188, v188
	v_mul_f32_e32 v189, v69, v229
	v_rndne_f32_e32 v189, v189
	v_cvt_i32_f32_e32 v189, v189
	v_and_b32_e32 v186, 0xff, v186
	v_and_b32_e32 v187, 0xff, v187
	v_and_b32_e32 v188, 0xff, v188
	v_lshl_or_b32 v190, v187, 8, v186
	v_lshl_or_b32 v190, v188, 16, v190
	v_lshl_or_b32 v190, v189, 24, v190
	ds_write_b32 v139, v190 offset:1728
	s_cmp_ge_u32 s4, 0x560
	s_cbranch_scc1 .Lc16p3_ffn2_nopf_3
	global_load_dwordx4 v[54:57], v138, s[54:55] nt
	s_add_u32 s54, s54, 0x15800
	s_addc_u32 s55, s55, 0
	global_load_dwordx4 v[58:61], v138, s[54:55] nt
	s_add_u32 s54, s54, 0x15800
	s_addc_u32 s55, s55, 0
	global_load_dwordx4 v[62:65], v138, s[54:55] nt
	s_add_u32 s54, s54, 0x15800
	s_addc_u32 s55, s55, 0
	global_load_dwordx4 v[66:69], v138, s[54:55] nt
	s_add_u32 s54, s54, 0x51f800
	s_addc_u32 s55, s55, 0
.Lc16p3_ffn2_nopf_3:
	v_mul_f32_e32 v186, v70, v226
	v_rndne_f32_e32 v186, v186
	v_cvt_i32_f32_e32 v186, v186
	v_mul_f32_e32 v187, v74, v226
	v_rndne_f32_e32 v187, v187
	v_cvt_i32_f32_e32 v187, v187
	v_mul_f32_e32 v188, v78, v226
	v_rndne_f32_e32 v188, v188
	v_cvt_i32_f32_e32 v188, v188
	v_mul_f32_e32 v189, v82, v226
	v_rndne_f32_e32 v189, v189
	v_cvt_i32_f32_e32 v189, v189
	v_and_b32_e32 v186, 0xff, v186
	v_and_b32_e32 v187, 0xff, v187
	v_and_b32_e32 v188, 0xff, v188
	v_lshl_or_b32 v190, v187, 8, v186
	v_lshl_or_b32 v190, v188, 16, v190
	v_lshl_or_b32 v190, v189, 24, v190
	ds_write_b32 v139, v190 offset:256
	v_mul_f32_e32 v186, v71, v227
	v_rndne_f32_e32 v186, v186
	v_cvt_i32_f32_e32 v186, v186
	v_mul_f32_e32 v187, v75, v227
	v_rndne_f32_e32 v187, v187
	v_cvt_i32_f32_e32 v187, v187
	v_mul_f32_e32 v188, v79, v227
	v_rndne_f32_e32 v188, v188
	v_cvt_i32_f32_e32 v188, v188
	v_mul_f32_e32 v189, v83, v227
	v_rndne_f32_e32 v189, v189
	v_cvt_i32_f32_e32 v189, v189
	v_and_b32_e32 v186, 0xff, v186
	v_and_b32_e32 v187, 0xff, v187
	v_and_b32_e32 v188, 0xff, v188
	v_lshl_or_b32 v190, v187, 8, v186
	v_lshl_or_b32 v190, v188, 16, v190
	v_lshl_or_b32 v190, v189, 24, v190
	ds_write_b32 v139, v190 offset:768
	v_mul_f32_e32 v186, v72, v228
	v_rndne_f32_e32 v186, v186
	v_cvt_i32_f32_e32 v186, v186
	v_mul_f32_e32 v187, v76, v228
	v_rndne_f32_e32 v187, v187
	v_cvt_i32_f32_e32 v187, v187
	v_mul_f32_e32 v188, v80, v228
	v_rndne_f32_e32 v188, v188
	v_cvt_i32_f32_e32 v188, v188
	v_mul_f32_e32 v189, v84, v228
	v_rndne_f32_e32 v189, v189
	v_cvt_i32_f32_e32 v189, v189
	v_and_b32_e32 v186, 0xff, v186
	v_and_b32_e32 v187, 0xff, v187
	v_and_b32_e32 v188, 0xff, v188
	v_lshl_or_b32 v190, v187, 8, v186
	v_lshl_or_b32 v190, v188, 16, v190
	v_lshl_or_b32 v190, v189, 24, v190
	ds_write_b32 v139, v190 offset:1280
	v_mul_f32_e32 v186, v73, v229
	v_rndne_f32_e32 v186, v186
	v_cvt_i32_f32_e32 v186, v186
	v_mul_f32_e32 v187, v77, v229
	v_rndne_f32_e32 v187, v187
	v_cvt_i32_f32_e32 v187, v187
	v_mul_f32_e32 v188, v81, v229
	v_rndne_f32_e32 v188, v188
	v_cvt_i32_f32_e32 v188, v188
	v_mul_f32_e32 v189, v85, v229
	v_rndne_f32_e32 v189, v189
	v_cvt_i32_f32_e32 v189, v189
	v_and_b32_e32 v186, 0xff, v186
	v_and_b32_e32 v187, 0xff, v187
	v_and_b32_e32 v188, 0xff, v188
	v_lshl_or_b32 v190, v187, 8, v186
	v_lshl_or_b32 v190, v188, 16, v190
	v_lshl_or_b32 v190, v189, 24, v190
	ds_write_b32 v139, v190 offset:1792
	s_cmp_ge_u32 s4, 0x560
	s_cbranch_scc1 .Lc16p3_ffn2_nopf_4
	global_load_dwordx4 v[70:73], v138, s[54:55] nt
	s_add_u32 s54, s54, 0x15800
	s_addc_u32 s55, s55, 0
	global_load_dwordx4 v[74:77], v138, s[54:55] nt
	s_add_u32 s54, s54, 0x15800
	s_addc_u32 s55, s55, 0
	global_load_dwordx4 v[78:81], v138, s[54:55] nt
	s_add_u32 s54, s54, 0x15800
	s_addc_u32 s55, s55, 0
	global_load_dwordx4 v[82:85], v138, s[54:55] nt
	s_add_u32 s54, s54, 0x51f800
	s_addc_u32 s55, s55, 0
.Lc16p3_ffn2_nopf_4:
	v_mul_f32_e32 v186, v86, v226
	v_rndne_f32_e32 v186, v186
	v_cvt_i32_f32_e32 v186, v186
	v_mul_f32_e32 v187, v90, v226
	v_rndne_f32_e32 v187, v187
	v_cvt_i32_f32_e32 v187, v187
	v_mul_f32_e32 v188, v94, v226
	v_rndne_f32_e32 v188, v188
	v_cvt_i32_f32_e32 v188, v188
	v_mul_f32_e32 v189, v98, v226
	v_rndne_f32_e32 v189, v189
	v_cvt_i32_f32_e32 v189, v189
	v_and_b32_e32 v186, 0xff, v186
	v_and_b32_e32 v187, 0xff, v187
	v_and_b32_e32 v188, 0xff, v188
	v_lshl_or_b32 v190, v187, 8, v186
	v_lshl_or_b32 v190, v188, 16, v190
	v_lshl_or_b32 v190, v189, 24, v190
	ds_write_b32 v139, v190 offset:320
	v_mul_f32_e32 v186, v87, v227
	v_rndne_f32_e32 v186, v186
	v_cvt_i32_f32_e32 v186, v186
	v_mul_f32_e32 v187, v91, v227
	v_rndne_f32_e32 v187, v187
	v_cvt_i32_f32_e32 v187, v187
	v_mul_f32_e32 v188, v95, v227
	v_rndne_f32_e32 v188, v188
	v_cvt_i32_f32_e32 v188, v188
	v_mul_f32_e32 v189, v99, v227
	v_rndne_f32_e32 v189, v189
	v_cvt_i32_f32_e32 v189, v189
	v_and_b32_e32 v186, 0xff, v186
	v_and_b32_e32 v187, 0xff, v187
	v_and_b32_e32 v188, 0xff, v188
	v_lshl_or_b32 v190, v187, 8, v186
	v_lshl_or_b32 v190, v188, 16, v190
	v_lshl_or_b32 v190, v189, 24, v190
	ds_write_b32 v139, v190 offset:832
	v_mul_f32_e32 v186, v88, v228
	v_rndne_f32_e32 v186, v186
	v_cvt_i32_f32_e32 v186, v186
	v_mul_f32_e32 v187, v92, v228
	v_rndne_f32_e32 v187, v187
	v_cvt_i32_f32_e32 v187, v187
	v_mul_f32_e32 v188, v96, v228
	v_rndne_f32_e32 v188, v188
	v_cvt_i32_f32_e32 v188, v188
	v_mul_f32_e32 v189, v100, v228
	v_rndne_f32_e32 v189, v189
	v_cvt_i32_f32_e32 v189, v189
	v_and_b32_e32 v186, 0xff, v186
	v_and_b32_e32 v187, 0xff, v187
	v_and_b32_e32 v188, 0xff, v188
	v_lshl_or_b32 v190, v187, 8, v186
	v_lshl_or_b32 v190, v188, 16, v190
	v_lshl_or_b32 v190, v189, 24, v190
	ds_write_b32 v139, v190 offset:1344
	v_mul_f32_e32 v186, v89, v229
	v_rndne_f32_e32 v186, v186
	v_cvt_i32_f32_e32 v186, v186
	v_mul_f32_e32 v187, v93, v229
	v_rndne_f32_e32 v187, v187
	v_cvt_i32_f32_e32 v187, v187
	v_mul_f32_e32 v188, v97, v229
	v_rndne_f32_e32 v188, v188
	v_cvt_i32_f32_e32 v188, v188
	v_mul_f32_e32 v189, v101, v229
	v_rndne_f32_e32 v189, v189
	v_cvt_i32_f32_e32 v189, v189
	v_and_b32_e32 v186, 0xff, v186
	v_and_b32_e32 v187, 0xff, v187
	v_and_b32_e32 v188, 0xff, v188
	v_lshl_or_b32 v190, v187, 8, v186
	v_lshl_or_b32 v190, v188, 16, v190
	v_lshl_or_b32 v190, v189, 24, v190
	ds_write_b32 v139, v190 offset:1856
	s_cmp_ge_u32 s4, 0x560
	s_cbranch_scc1 .Lc16p3_ffn2_nopf_5
	global_load_dwordx4 v[86:89], v138, s[54:55] nt
	s_add_u32 s54, s54, 0x15800
	s_addc_u32 s55, s55, 0
	global_load_dwordx4 v[90:93], v138, s[54:55] nt
	s_add_u32 s54, s54, 0x15800
	s_addc_u32 s55, s55, 0
	global_load_dwordx4 v[94:97], v138, s[54:55] nt
	s_add_u32 s54, s54, 0x15800
	s_addc_u32 s55, s55, 0
	global_load_dwordx4 v[98:101], v138, s[54:55] nt
	s_add_u32 s54, s54, 0x51f800
	s_addc_u32 s55, s55, 0
.Lc16p3_ffn2_nopf_5:
	v_mul_f32_e32 v186, v102, v226
	v_rndne_f32_e32 v186, v186
	v_cvt_i32_f32_e32 v186, v186
	v_mul_f32_e32 v187, v106, v226
	v_rndne_f32_e32 v187, v187
	v_cvt_i32_f32_e32 v187, v187
	v_mul_f32_e32 v188, v110, v226
	v_rndne_f32_e32 v188, v188
	v_cvt_i32_f32_e32 v188, v188
	v_mul_f32_e32 v189, v114, v226
	v_rndne_f32_e32 v189, v189
	v_cvt_i32_f32_e32 v189, v189
	v_and_b32_e32 v186, 0xff, v186
	v_and_b32_e32 v187, 0xff, v187
	v_and_b32_e32 v188, 0xff, v188
	v_lshl_or_b32 v190, v187, 8, v186
	v_lshl_or_b32 v190, v188, 16, v190
	v_lshl_or_b32 v190, v189, 24, v190
	ds_write_b32 v139, v190 offset:384
	v_mul_f32_e32 v186, v103, v227
	v_rndne_f32_e32 v186, v186
	v_cvt_i32_f32_e32 v186, v186
	v_mul_f32_e32 v187, v107, v227
	v_rndne_f32_e32 v187, v187
	v_cvt_i32_f32_e32 v187, v187
	v_mul_f32_e32 v188, v111, v227
	v_rndne_f32_e32 v188, v188
	v_cvt_i32_f32_e32 v188, v188
	v_mul_f32_e32 v189, v115, v227
	v_rndne_f32_e32 v189, v189
	v_cvt_i32_f32_e32 v189, v189
	v_and_b32_e32 v186, 0xff, v186
	v_and_b32_e32 v187, 0xff, v187
	v_and_b32_e32 v188, 0xff, v188
	v_lshl_or_b32 v190, v187, 8, v186
	v_lshl_or_b32 v190, v188, 16, v190
	v_lshl_or_b32 v190, v189, 24, v190
	ds_write_b32 v139, v190 offset:896
	v_mul_f32_e32 v186, v104, v228
	v_rndne_f32_e32 v186, v186
	v_cvt_i32_f32_e32 v186, v186
	v_mul_f32_e32 v187, v108, v228
	v_rndne_f32_e32 v187, v187
	v_cvt_i32_f32_e32 v187, v187
	v_mul_f32_e32 v188, v112, v228
	v_rndne_f32_e32 v188, v188
	v_cvt_i32_f32_e32 v188, v188
	v_mul_f32_e32 v189, v116, v228
	v_rndne_f32_e32 v189, v189
	v_cvt_i32_f32_e32 v189, v189
	v_and_b32_e32 v186, 0xff, v186
	v_and_b32_e32 v187, 0xff, v187
	v_and_b32_e32 v188, 0xff, v188
	v_lshl_or_b32 v190, v187, 8, v186
	v_lshl_or_b32 v190, v188, 16, v190
	v_lshl_or_b32 v190, v189, 24, v190
	ds_write_b32 v139, v190 offset:1408
	v_mul_f32_e32 v186, v105, v229
	v_rndne_f32_e32 v186, v186
	v_cvt_i32_f32_e32 v186, v186
	v_mul_f32_e32 v187, v109, v229
	v_rndne_f32_e32 v187, v187
	v_cvt_i32_f32_e32 v187, v187
	v_mul_f32_e32 v188, v113, v229
	v_rndne_f32_e32 v188, v188
	v_cvt_i32_f32_e32 v188, v188
	v_mul_f32_e32 v189, v117, v229
	v_rndne_f32_e32 v189, v189
	v_cvt_i32_f32_e32 v189, v189
	v_and_b32_e32 v186, 0xff, v186
	v_and_b32_e32 v187, 0xff, v187
	v_and_b32_e32 v188, 0xff, v188
	v_lshl_or_b32 v190, v187, 8, v186
	v_lshl_or_b32 v190, v188, 16, v190
	v_lshl_or_b32 v190, v189, 24, v190
	ds_write_b32 v139, v190 offset:1920
	s_cmp_ge_u32 s4, 0x560
	s_cbranch_scc1 .Lc16p3_ffn2_nopf_6
	global_load_dwordx4 v[102:105], v138, s[54:55] nt
	s_add_u32 s54, s54, 0x15800
	s_addc_u32 s55, s55, 0
	global_load_dwordx4 v[106:109], v138, s[54:55] nt
	s_add_u32 s54, s54, 0x15800
	s_addc_u32 s55, s55, 0
	global_load_dwordx4 v[110:113], v138, s[54:55] nt
	s_add_u32 s54, s54, 0x15800
	s_addc_u32 s55, s55, 0
	global_load_dwordx4 v[114:117], v138, s[54:55] nt
	s_add_u32 s54, s54, 0x51f800
	s_addc_u32 s55, s55, 0
.Lc16p3_ffn2_nopf_6:
	v_mul_f32_e32 v186, v118, v226
	v_rndne_f32_e32 v186, v186
	v_cvt_i32_f32_e32 v186, v186
	v_mul_f32_e32 v187, v122, v226
	v_rndne_f32_e32 v187, v187
	v_cvt_i32_f32_e32 v187, v187
	v_mul_f32_e32 v188, v126, v226
	v_rndne_f32_e32 v188, v188
	v_cvt_i32_f32_e32 v188, v188
	v_mul_f32_e32 v189, v130, v226
	v_rndne_f32_e32 v189, v189
	v_cvt_i32_f32_e32 v189, v189
	v_and_b32_e32 v186, 0xff, v186
	v_and_b32_e32 v187, 0xff, v187
	v_and_b32_e32 v188, 0xff, v188
	v_lshl_or_b32 v190, v187, 8, v186
	v_lshl_or_b32 v190, v188, 16, v190
	v_lshl_or_b32 v190, v189, 24, v190
	ds_write_b32 v139, v190 offset:448
	v_mul_f32_e32 v186, v119, v227
	v_rndne_f32_e32 v186, v186
	v_cvt_i32_f32_e32 v186, v186
	v_mul_f32_e32 v187, v123, v227
	v_rndne_f32_e32 v187, v187
	v_cvt_i32_f32_e32 v187, v187
	v_mul_f32_e32 v188, v127, v227
	v_rndne_f32_e32 v188, v188
	v_cvt_i32_f32_e32 v188, v188
	v_mul_f32_e32 v189, v131, v227
	v_rndne_f32_e32 v189, v189
	v_cvt_i32_f32_e32 v189, v189
	v_and_b32_e32 v186, 0xff, v186
	v_and_b32_e32 v187, 0xff, v187
	v_and_b32_e32 v188, 0xff, v188
	v_lshl_or_b32 v190, v187, 8, v186
	v_lshl_or_b32 v190, v188, 16, v190
	v_lshl_or_b32 v190, v189, 24, v190
	ds_write_b32 v139, v190 offset:960
	v_mul_f32_e32 v186, v120, v228
	v_rndne_f32_e32 v186, v186
	v_cvt_i32_f32_e32 v186, v186
	v_mul_f32_e32 v187, v124, v228
	v_rndne_f32_e32 v187, v187
	v_cvt_i32_f32_e32 v187, v187
	v_mul_f32_e32 v188, v128, v228
	v_rndne_f32_e32 v188, v188
	v_cvt_i32_f32_e32 v188, v188
	v_mul_f32_e32 v189, v132, v228
	v_rndne_f32_e32 v189, v189
	v_cvt_i32_f32_e32 v189, v189
	v_and_b32_e32 v186, 0xff, v186
	v_and_b32_e32 v187, 0xff, v187
	v_and_b32_e32 v188, 0xff, v188
	v_lshl_or_b32 v190, v187, 8, v186
	v_lshl_or_b32 v190, v188, 16, v190
	v_lshl_or_b32 v190, v189, 24, v190
	ds_write_b32 v139, v190 offset:1472
	v_mul_f32_e32 v186, v121, v229
	v_rndne_f32_e32 v186, v186
	v_cvt_i32_f32_e32 v186, v186
	v_mul_f32_e32 v187, v125, v229
	v_rndne_f32_e32 v187, v187
	v_cvt_i32_f32_e32 v187, v187
	v_mul_f32_e32 v188, v129, v229
	v_rndne_f32_e32 v188, v188
	v_cvt_i32_f32_e32 v188, v188
	v_mul_f32_e32 v189, v133, v229
	v_rndne_f32_e32 v189, v189
	v_cvt_i32_f32_e32 v189, v189
	v_and_b32_e32 v186, 0xff, v186
	v_and_b32_e32 v187, 0xff, v187
	v_and_b32_e32 v188, 0xff, v188
	v_lshl_or_b32 v190, v187, 8, v186
	v_lshl_or_b32 v190, v188, 16, v190
	v_lshl_or_b32 v190, v189, 24, v190
	ds_write_b32 v139, v190 offset:1984
	s_cmp_ge_u32 s4, 0x560
	s_cbranch_scc1 .Lc16p3_ffn2_nopf_7
	global_load_dwordx4 v[118:121], v138, s[54:55] nt
	s_add_u32 s54, s54, 0x15800
	s_addc_u32 s55, s55, 0
	global_load_dwordx4 v[122:125], v138, s[54:55] nt
	s_add_u32 s54, s54, 0x15800
	s_addc_u32 s55, s55, 0
	global_load_dwordx4 v[126:129], v138, s[54:55] nt
	s_add_u32 s54, s54, 0x15800
	s_addc_u32 s55, s55, 0
	global_load_dwordx4 v[130:133], v138, s[54:55] nt
.Lc16p3_ffn2_nopf_7:
	s_waitcnt lgkmcnt(0)
	s_lshl_b32 s3, s6, 12
	s_lshl_b32 s4, s1, 9
	s_add_u32 s3, s3, s4
	s_add_u32 s56, s34, s3
	s_addc_u32 s57, s35, 0
	s_add_u32 s56, s56, 0xe700000
	s_addc_u32 s57, s57, 0
	ds_read_b128 v[204:207], v212 offset:0
	s_waitcnt lgkmcnt(0)
	global_store_dwordx4 v213, v[204:207], s[56:57]
	s_add_u32 s56, s56, 0x2000
	s_addc_u32 s57, s57, 0
	ds_read_b128 v[208:211], v212 offset:1024
	s_waitcnt lgkmcnt(0)
	global_store_dwordx4 v213, v[208:211], s[56:57]
	s_add_u32 s56, s56, 0x2000
	s_addc_u32 s57, s57, 0
	ds_read_b128 v[204:207], v212 offset:2048
	s_waitcnt lgkmcnt(0)
	global_store_dwordx4 v213, v[204:207], s[56:57]
	s_add_u32 s56, s56, 0x2000
	s_addc_u32 s57, s57, 0
	ds_read_b128 v[208:211], v212 offset:3072
	s_waitcnt lgkmcnt(0)
	global_store_dwordx4 v213, v[208:211], s[56:57]
	s_add_u32 s56, s56, 0x2000
	s_addc_u32 s57, s57, 0
	ds_read_b128 v[204:207], v212 offset:4096
	s_waitcnt lgkmcnt(0)
	global_store_dwordx4 v213, v[204:207], s[56:57]
	s_add_u32 s56, s56, 0x2000
	s_addc_u32 s57, s57, 0
	ds_read_b128 v[208:211], v212 offset:5120
	s_waitcnt lgkmcnt(0)
	global_store_dwordx4 v213, v[208:211], s[56:57]
	s_add_u32 s56, s56, 0x2000
	s_addc_u32 s57, s57, 0
	ds_read_b128 v[204:207], v212 offset:6144
	s_waitcnt lgkmcnt(0)
	global_store_dwordx4 v213, v[204:207], s[56:57]
	s_add_u32 s56, s56, 0x2000
	s_addc_u32 s57, s57, 0
	ds_read_b128 v[208:211], v212 offset:7168
	s_waitcnt lgkmcnt(0)
	global_store_dwordx4 v213, v[208:211], s[56:57]
	s_xor_b32 s5, s5, 1
	s_add_u32 s0, s0, s33
	s_cmp_lt_u32 s0, 0x560
	s_cbranch_scc1 .Lc16p3_ffn2_loop
.Lc16p3_ffn2_done:
	s_branch .LBB0_487
	s_cmpk_gt_i32 s90, 0x2aff
	s_cbranch_scc1 .LBB0_487
	s_waitcnt vmcnt(31)
	v_lshlrev_b32_e32 v1, 2, v222
	v_ashrrev_i32_e32 v137, 3, v222
	s_waitcnt vmcnt(28)
	v_bitop3_b32 v12, v137, 28, v1 bitop3:0x48
	v_add_u32_e32 v139, 8, v137
	v_readlane_b32 s2, v254, 17
	v_lshlrev_b32_e32 v11, 7, v137
	v_lshlrev_b32_e32 v12, 2, v12
	v_bitop3_b32 v13, v139, 28, v1 bitop3:0x48
	v_add3_u32 v138, s2, v11, v12
	v_lshlrev_b32_e32 v11, 7, v139
	v_lshlrev_b32_e32 v13, 2, v13
	v_add_u32_e32 v141, 16, v137
	v_add3_u32 v140, s2, v11, v13
	v_bitop3_b32 v13, v141, 28, v1 bitop3:0x48
	v_ashrrev_i32_e32 v0, 4, v222
	v_lshlrev_b32_e32 v11, 7, v141
	v_lshlrev_b32_e32 v13, 2, v13
	v_add_u32_e32 v143, 24, v137
	v_lshlrev_b32_e32 v136, 2, v0
	v_and_b32_e32 v0, 60, v1
	v_readlane_b32 s0, v254, 27
	v_add3_u32 v142, s2, v11, v13
	v_bitop3_b32 v13, v143, 28, v1 bitop3:0x48
	v_mov_b32_e32 v129, 0
	v_lshlrev_b32_e32 v128, 2, v0
	v_readlane_b32 s1, v254, 28
	v_lshlrev_b32_e32 v3, 4, v222
	v_lshlrev_b32_e32 v11, 7, v143
	v_lshlrev_b32_e32 v13, 2, v13
	v_add_u32_e32 v145, 32, v137
	v_lshl_add_u64 v[130:131], s[0:1], 0, v[128:129]
	v_add_u32_e32 v2, s2, v136
	v_and_b32_e32 v128, 0x70, v3
	s_movk_i32 s1, 0x50
	v_add3_u32 v144, s2, v11, v13
	v_lshlrev_b32_e32 v11, 7, v145
	v_add_u32_e32 v147, 40, v137
	s_movk_i32 s0, 0x70
	v_xad_u32 v9, v128, s1, v2
	s_movk_i32 s1, 0x60
	v_add3_u32 v146, s2, v11, v12
	v_bitop3_b32 v12, v147, 28, v1 bitop3:0x48
	v_add_u32_e32 v3, v2, v128
	v_xad_u32 v5, v128, 16, v2
	v_xad_u32 v6, v128, 32, v2
	v_xad_u32 v7, v128, 48, v2
	v_xad_u32 v8, v128, 64, v2
	v_xad_u32 v10, v128, s1, v2
	v_xad_u32 v2, v128, s0, v2
	v_readlane_b32 s0, v254, 18
	v_lshlrev_b32_e32 v11, 7, v147
	v_lshlrev_b32_e32 v12, 2, v12
	v_add_u32_e32 v149, 48, v137
	v_readlane_b32 s1, v254, 19
	v_add3_u32 v148, s2, v11, v12
	v_bitop3_b32 v12, v149, 28, v1 bitop3:0x48
	v_add_u32_e32 v151, 56, v137
	v_lshl_add_u64 v[132:133], s[0:1], 0, v[128:129]
	v_lshlrev_b32_e32 v11, 7, v149
	v_lshlrev_b32_e32 v12, 2, v12
	v_bitop3_b32 v1, v151, 28, v1 bitop3:0x48
	v_readlane_b32 s0, v254, 15
	v_readlane_b32 s1, v254, 16
	v_readlane_b32 s52, v255, 55
	v_lshlrev_b32_e32 v4, 7, v0
	v_add3_u32 v150, s2, v11, v12
	v_lshlrev_b32_e32 v11, 7, v151
	v_lshlrev_b32_e32 v1, 2, v1
	s_lshl_b32 s0, s0, 9
	s_lshl_b32 s1, s1, 6
	v_readlane_b32 s58, v255, 61
	v_readlane_b32 s59, v255, 62
	v_add3_u32 v152, s2, v11, v1
	s_add_i32 s10, s0, s1
	v_mov_b64_e32 v[134:135], s[58:59]
	v_lshlrev_b32_e32 v128, 2, v0
	s_mov_b32 s11, 0x42fe0000
	s_mov_b32 s12, 0x40c0c00
	v_add_u32_e32 v153, v3, v4
	v_add_u32_e32 v154, v5, v4
	v_add_u32_e32 v155, v6, v4
	v_add_u32_e32 v156, v7, v4
	v_add_u32_e32 v157, v8, v4
	v_add_u32_e32 v158, v9, v4
	v_add_u32_e32 v159, v10, v4
	v_add_u32_e32 v160, v2, v4
	s_mov_b32 s13, s90
	v_readlane_b32 s53, v255, 56
	v_readlane_b32 s54, v255, 57
	v_readlane_b32 s55, v255, 58
	v_readlane_b32 s56, v255, 59
	v_readlane_b32 s57, v255, 60
	v_readlane_b32 s60, v255, 63
	v_readlane_b32 s61, v254, 0
	v_readlane_b32 s62, v254, 1
	v_readlane_b32 s63, v254, 2
	v_readlane_b32 s64, v254, 3
	v_readlane_b32 s65, v254, 4
	v_readlane_b32 s66, v254, 5
	v_readlane_b32 s67, v254, 6
